# cache-policy test: P6 stores the f32 residual again (old P11), x/y row loads non-temporal - checks whether absorbed writes beat the extra P11 reads
# baseline (speedup 1.0000x reference)
; __device__ __forceinline__ float bf_lo(unsigned w) { return __uint_as_float(w << 16); }
; __device__ __forceinline__ float bf_hi(unsigned w) { return __uint_as_float(w & 0xffff0000u); }
; __global__ void __launch_bounds__(NWAVES * 64, 2) mk_fwd(Args args) {
;     ...
;             for (int q = 0; q < 3; ++q) { const int row = row0 + q; const bool lat = row < ML; const int r = lat ? row / SEQ : 8;
;                 float sy = 0.f;
; #pragma unroll
;                 for (int j = 0; j < 8; ++j) { const float a = bf_lo(yw[q][j].x), b = bf_hi(yw[q][j].x), c2 = bf_lo(yw[q][j].y), d = bf_hi(yw[q][j].y); sy += (a * a + b * b) + (c2 * c2 + d * d); }
;                 const float rsy = __builtin_amdgcn_rsqf(wave_sum(sy) * (1.f / DM) + EPS);
;                 const float* m0 = mod + (size_t)r * 6144;
; #pragma unroll
;                 for (int j = 0; j < 8; ++j) { const int col = 4 * F.lane + 256 * j; const f32x4 gt = *(const f32x4*)(m0 + 2 * DM + col), pn = *(const f32x4*)(post_norm + col);
;                     const f32x4 y4 = (f32x4){bf_lo(yw[q][j].x), bf_hi(yw[q][j].x), bf_lo(yw[q][j].y), bf_hi(yw[q][j].y)};
;                     v[q][j] = v[q][j] + gt * (y4 * rsy * pn);
;                     if (lat) *(f32x4*)(args.out + (size_t)row * DM + col) = v[q][j]; }
.Lp6_np0:
	s_waitcnt vmcnt(16)
	v_lshlrev_b32_e32 v216, 16, v32
	v_and_b32_e32 v217, 0xffff0000, v32
	v_lshlrev_b32_e32 v218, 16, v33
	v_and_b32_e32 v219, 0xffff0000, v33
	v_mul_f32_e32 v222, v216, v216
	v_mul_f32_e32 v223, v217, v217
	v_fmac_f32_e32 v222, v218, v218
	v_fmac_f32_e32 v223, v219, v219
	v_lshlrev_b32_e32 v216, 16, v34
	v_and_b32_e32 v217, 0xffff0000, v34
	v_lshlrev_b32_e32 v218, 16, v35
	v_and_b32_e32 v219, 0xffff0000, v35
	v_fmac_f32_e32 v222, v216, v216
	v_fmac_f32_e32 v223, v217, v217
	v_fmac_f32_e32 v222, v218, v218
	v_fmac_f32_e32 v223, v219, v219
	v_lshlrev_b32_e32 v216, 16, v36
	v_and_b32_e32 v217, 0xffff0000, v36
	v_lshlrev_b32_e32 v218, 16, v37
	v_and_b32_e32 v219, 0xffff0000, v37
	v_fmac_f32_e32 v222, v216, v216
	v_fmac_f32_e32 v223, v217, v217
	v_fmac_f32_e32 v222, v218, v218
	v_fmac_f32_e32 v223, v219, v219
	v_lshlrev_b32_e32 v216, 16, v38
	v_and_b32_e32 v217, 0xffff0000, v38
	v_lshlrev_b32_e32 v218, 16, v39
	v_and_b32_e32 v219, 0xffff0000, v39
	v_fmac_f32_e32 v222, v216, v216
	v_fmac_f32_e32 v223, v217, v217
	v_fmac_f32_e32 v222, v218, v218
	v_fmac_f32_e32 v223, v219, v219
	v_lshlrev_b32_e32 v216, 16, v40
	v_and_b32_e32 v217, 0xffff0000, v40
	v_lshlrev_b32_e32 v218, 16, v41
	v_and_b32_e32 v219, 0xffff0000, v41
	v_fmac_f32_e32 v222, v216, v216
	v_fmac_f32_e32 v223, v217, v217
	v_fmac_f32_e32 v222, v218, v218
	v_fmac_f32_e32 v223, v219, v219
	v_lshlrev_b32_e32 v216, 16, v42
	v_and_b32_e32 v217, 0xffff0000, v42
	v_lshlrev_b32_e32 v218, 16, v43
	v_and_b32_e32 v219, 0xffff0000, v43
	v_fmac_f32_e32 v222, v216, v216
	v_fmac_f32_e32 v223, v217, v217
	v_fmac_f32_e32 v222, v218, v218
	v_fmac_f32_e32 v223, v219, v219
	v_lshlrev_b32_e32 v216, 16, v44
	v_and_b32_e32 v217, 0xffff0000, v44
	v_lshlrev_b32_e32 v218, 16, v45
	v_and_b32_e32 v219, 0xffff0000, v45
	v_fmac_f32_e32 v222, v216, v216
	v_fmac_f32_e32 v223, v217, v217
	v_fmac_f32_e32 v222, v218, v218
	v_fmac_f32_e32 v223, v219, v219
	v_lshlrev_b32_e32 v216, 16, v46
	v_and_b32_e32 v217, 0xffff0000, v46
	v_lshlrev_b32_e32 v218, 16, v47
	v_and_b32_e32 v219, 0xffff0000, v47
	v_fmac_f32_e32 v222, v216, v216
	v_fmac_f32_e32 v223, v217, v217
	v_fmac_f32_e32 v222, v218, v218
	v_fmac_f32_e32 v223, v219, v219
	v_add_f32_e32 v222, v222, v223
	s_nop 1
	v_add_f32_dpp v224, v222, v222 quad_perm:[1,0,3,2] row_mask:0xf bank_mask:0xf
	s_nop 1
	v_add_f32_dpp v224, v224, v224 quad_perm:[2,3,0,1] row_mask:0xf bank_mask:0xf
	s_nop 1
	v_add_f32_dpp v224, v224, v224 row_half_mirror row_mask:0xf bank_mask:0xf
	s_nop 1
	v_add_f32_dpp v224, v224, v224 row_mirror row_mask:0xf bank_mask:0xf
	s_nop 1
	v_readlane_b32 s40, v224, 0
	v_readlane_b32 s41, v224, 16
	v_readlane_b32 s42, v224, 32
	v_readlane_b32 s43, v224, 48
	s_nop 1
	v_mov_b32_e32 v225, s40
	v_add_f32_e32 v225, s41, v225
	v_add_f32_e32 v225, s42, v225
	v_add_f32_e32 v225, s43, v225
	v_fmamk_f32 v225, v225, 0x3a000000, v195
	v_rsq_f32_e32 v225, v225
	s_nop 0
	s_add_i32 s0, s6, 0
	s_cmp_lt_u32 s0, 0x4000
	s_cselect_b32 s24, s94, s84
	s_cselect_b32 s25, s95, s85
	s_cselect_b32 s44, 0, 0x16000000
	s_cselect_b32 s1, 0, 0x4000
	s_sub_i32 s1, s0, s1
	s_lshl_b32 s1, s1, 13
	s_add_u32 s24, s24, s1
	s_addc_u32 s25, s25, 0
	s_add_u32 s24, s24, s44
	s_addc_u32 s25, s25, 0
	v_lshlrev_b32_e32 v216, 16, v32
	v_and_b32_e32 v217, 0xffff0000, v32
	v_lshlrev_b32_e32 v218, 16, v33
	v_and_b32_e32 v219, 0xffff0000, v33
	v_mul_f32_e32 v216, v225, v216
	v_mul_f32_e32 v217, v225, v217
	v_mul_f32_e32 v218, v225, v218
	v_mul_f32_e32 v219, v225, v219
	v_fmac_f32_e32 v0, v96, v216
	v_fmac_f32_e32 v1, v97, v217
	v_fmac_f32_e32 v2, v98, v218
	v_fmac_f32_e32 v3, v99, v219
	global_store_dwordx4 v192, v[0:3], s[24:25] offset:0
	v_lshlrev_b32_e32 v216, 16, v34
	v_and_b32_e32 v217, 0xffff0000, v34
	v_lshlrev_b32_e32 v218, 16, v35
	v_and_b32_e32 v219, 0xffff0000, v35
	v_mul_f32_e32 v216, v225, v216
	v_mul_f32_e32 v217, v225, v217
	v_mul_f32_e32 v218, v225, v218
	v_mul_f32_e32 v219, v225, v219
	v_fmac_f32_e32 v4, v100, v216
	v_fmac_f32_e32 v5, v101, v217
	v_fmac_f32_e32 v6, v102, v218
	v_fmac_f32_e32 v7, v103, v219
	global_store_dwordx4 v192, v[4:7], s[24:25] offset:1024
	v_lshlrev_b32_e32 v216, 16, v36
	v_and_b32_e32 v217, 0xffff0000, v36
	v_lshlrev_b32_e32 v218, 16, v37
	v_and_b32_e32 v219, 0xffff0000, v37
	v_mul_f32_e32 v216, v225, v216
	v_mul_f32_e32 v217, v225, v217
	v_mul_f32_e32 v218, v225, v218
	v_mul_f32_e32 v219, v225, v219
	v_fmac_f32_e32 v8, v104, v216
	v_fmac_f32_e32 v9, v105, v217
	v_fmac_f32_e32 v10, v106, v218
	v_fmac_f32_e32 v11, v107, v219
	global_store_dwordx4 v192, v[8:11], s[24:25] offset:2048
	v_lshlrev_b32_e32 v216, 16, v38
	v_and_b32_e32 v217, 0xffff0000, v38
	v_lshlrev_b32_e32 v218, 16, v39
	v_and_b32_e32 v219, 0xffff0000, v39
	v_mul_f32_e32 v216, v225, v216
	v_mul_f32_e32 v217, v225, v217
	v_mul_f32_e32 v218, v225, v218
	v_mul_f32_e32 v219, v225, v219
	v_fmac_f32_e32 v12, v108, v216
	v_fmac_f32_e32 v13, v109, v217
	v_fmac_f32_e32 v14, v110, v218
	v_fmac_f32_e32 v15, v111, v219
	global_store_dwordx4 v192, v[12:15], s[24:25] offset:3072
	v_lshlrev_b32_e32 v216, 16, v40
	v_and_b32_e32 v217, 0xffff0000, v40
	v_lshlrev_b32_e32 v218, 16, v41
	v_and_b32_e32 v219, 0xffff0000, v41
	v_mul_f32_e32 v216, v225, v216
	v_mul_f32_e32 v217, v225, v217
	v_mul_f32_e32 v218, v225, v218
	v_mul_f32_e32 v219, v225, v219
	v_fmac_f32_e32 v16, v112, v216
	v_fmac_f32_e32 v17, v113, v217
	v_fmac_f32_e32 v18, v114, v218
	v_fmac_f32_e32 v19, v115, v219
	global_store_dwordx4 v193, v[16:19], s[24:25] offset:0
	v_lshlrev_b32_e32 v216, 16, v42
	v_and_b32_e32 v217, 0xffff0000, v42
	v_lshlrev_b32_e32 v218, 16, v43
	v_and_b32_e32 v219, 0xffff0000, v43
	v_mul_f32_e32 v216, v225, v216
; __device__ __forceinline__ unsigned cvt_pk_bf16(float lo, float hi) { unsigned r; asm volatile("v_cvt_pk_bf16_f32 %0, %1, %2" : "=v"(r) : "v"(lo), "v"(hi)); return r; }
; __device__ __forceinline__ float bf_lo(unsigned w) { return __uint_as_float(w << 16); }
; __device__ __forceinline__ float bf_hi(unsigned w) { return __uint_as_float(w & 0xffff0000u); }
; __device__ __forceinline__ float sumsq8(const f32x4 (&v)[8]) {
;     float s = 0.f;
; #pragma unroll
;     for (int j = 0; j < 8; ++j) s += (v[j][0] * v[j][0] + v[j][1] * v[j][1]) + (v[j][2] * v[j][2] + v[j][3] * v[j][3]);
;     return wave_sum(s);
; }
; __device__ __forceinline__ void modulate_store(const f32x4 (&v)[8], float rstd, const float* pn, const float* modr, bf16_t* orow, int lane) {
; #pragma unroll
;     for (int j = 0; j < 8; ++j) { const int col = 4 * lane + 256 * j;
;         const f32x4 g = *(const f32x4*)(pn + col), sh = *(const f32x4*)(modr + col), sc = *(const f32x4*)(modr + DM + col);
;         const f32x4 hh = v[j] * rstd * g * (sc + 1.f) + sh;
;         u32x2 w; w.x = cvt_pk_bf16(hh[0], hh[1]); w.y = cvt_pk_bf16(hh[2], hh[3]);
;         *(u32x2*)(orow + col) = w; }
; __global__ void __launch_bounds__(NWAVES * 64, 2) mk_fwd(Args args) {
;     ...
;                 for (int j = 0; j < 8; ++j) { const int col = 4 * F.lane + 256 * j; const f32x4 gt = *(const f32x4*)(m0 + 2 * DM + col), pn = *(const f32x4*)(post_norm + col);
;                     const f32x4 y4 = (f32x4){bf_lo(yw[q][j].x), bf_hi(yw[q][j].x), bf_lo(yw[q][j].y), bf_hi(yw[q][j].y)};
;                     v[q][j] = v[q][j] + gt * (y4 * rsy * pn);
;                     if (lat) *(f32x4*)(args.out + (size_t)row * DM + col) = v[q][j]; }
;                 const float rstd = __builtin_amdgcn_rsqf(sumsq8(v[q]) * (1.f / DM) + EPS);
;                 modulate_store(v[q], rstd, pre_norm + DM, mod + (size_t)(9 + r) * 6144, H + (size_t)row * DM, F.lane); }
	v_mul_f32_e32 v217, v225, v217
	v_mul_f32_e32 v218, v225, v218
	v_mul_f32_e32 v219, v225, v219
	v_fmac_f32_e32 v20, v116, v216
	v_fmac_f32_e32 v21, v117, v217
	v_fmac_f32_e32 v22, v118, v218
	v_fmac_f32_e32 v23, v119, v219
	global_store_dwordx4 v193, v[20:23], s[24:25] offset:1024
	v_lshlrev_b32_e32 v216, 16, v44
	v_and_b32_e32 v217, 0xffff0000, v44
	v_lshlrev_b32_e32 v218, 16, v45
	v_and_b32_e32 v219, 0xffff0000, v45
	v_mul_f32_e32 v216, v225, v216
	v_mul_f32_e32 v217, v225, v217
	v_mul_f32_e32 v218, v225, v218
	v_mul_f32_e32 v219, v225, v219
	v_fmac_f32_e32 v24, v120, v216
	v_fmac_f32_e32 v25, v121, v217
	v_fmac_f32_e32 v26, v122, v218
	v_fmac_f32_e32 v27, v123, v219
	global_store_dwordx4 v193, v[24:27], s[24:25] offset:2048
	v_lshlrev_b32_e32 v216, 16, v46
	v_and_b32_e32 v217, 0xffff0000, v46
	v_lshlrev_b32_e32 v218, 16, v47
	v_and_b32_e32 v219, 0xffff0000, v47
	v_mul_f32_e32 v216, v225, v216
	v_mul_f32_e32 v217, v225, v217
	v_mul_f32_e32 v218, v225, v218
	v_mul_f32_e32 v219, v225, v219
	v_fmac_f32_e32 v28, v124, v216
	v_fmac_f32_e32 v29, v125, v217
	v_fmac_f32_e32 v30, v126, v218
	v_fmac_f32_e32 v31, v127, v219
	global_store_dwordx4 v193, v[28:31], s[24:25] offset:3072
	v_mul_f32_e32 v222, v0, v0
	v_mul_f32_e32 v223, v1, v1
	v_fmac_f32_e32 v222, v2, v2
	v_fmac_f32_e32 v223, v3, v3
	v_fmac_f32_e32 v222, v4, v4
	v_fmac_f32_e32 v223, v5, v5
	v_fmac_f32_e32 v222, v6, v6
	v_fmac_f32_e32 v223, v7, v7
	v_fmac_f32_e32 v222, v8, v8
	v_fmac_f32_e32 v223, v9, v9
	v_fmac_f32_e32 v222, v10, v10
	v_fmac_f32_e32 v223, v11, v11
	v_fmac_f32_e32 v222, v12, v12
	v_fmac_f32_e32 v223, v13, v13
	v_fmac_f32_e32 v222, v14, v14
	v_fmac_f32_e32 v223, v15, v15
	v_fmac_f32_e32 v222, v16, v16
	v_fmac_f32_e32 v223, v17, v17
	v_fmac_f32_e32 v222, v18, v18
	v_fmac_f32_e32 v223, v19, v19
	v_fmac_f32_e32 v222, v20, v20
	v_fmac_f32_e32 v223, v21, v21
	v_fmac_f32_e32 v222, v22, v22
	v_fmac_f32_e32 v223, v23, v23
	v_fmac_f32_e32 v222, v24, v24
	v_fmac_f32_e32 v223, v25, v25
	v_fmac_f32_e32 v222, v26, v26
	v_fmac_f32_e32 v223, v27, v27
	v_fmac_f32_e32 v222, v28, v28
	v_fmac_f32_e32 v223, v29, v29
	v_fmac_f32_e32 v222, v30, v30
	v_fmac_f32_e32 v223, v31, v31
	v_add_f32_e32 v222, v222, v223
	s_nop 1
	v_add_f32_dpp v224, v222, v222 quad_perm:[1,0,3,2] row_mask:0xf bank_mask:0xf
	s_nop 1
	v_add_f32_dpp v224, v224, v224 quad_perm:[2,3,0,1] row_mask:0xf bank_mask:0xf
	s_nop 1
	v_add_f32_dpp v224, v224, v224 row_half_mirror row_mask:0xf bank_mask:0xf
	s_nop 1
	v_add_f32_dpp v224, v224, v224 row_mirror row_mask:0xf bank_mask:0xf
	s_nop 1
	v_readlane_b32 s40, v224, 0
	v_readlane_b32 s41, v224, 16
	v_readlane_b32 s42, v224, 32
	v_readlane_b32 s43, v224, 48
	s_nop 1
	v_mov_b32_e32 v225, s40
	v_add_f32_e32 v225, s41, v225
	v_add_f32_e32 v225, s42, v225
	v_add_f32_e32 v225, s43, v225
	v_fmamk_f32 v225, v225, 0x3a000000, v195
	v_rsq_f32_e32 v225, v225
	s_nop 0
	s_add_i32 s0, s6, 0
	s_lshl_b32 s1, s0, 12
	s_add_u32 s26, s84, s1
	s_addc_u32 s27, s85, 0
	s_add_u32 s26, s26, 0x4000000
	s_addc_u32 s27, s27, 0
	v_mul_f32_e32 v216, v225, v0
	v_mul_f32_e32 v217, v225, v1
	v_mul_f32_e32 v218, v225, v2
	v_mul_f32_e32 v219, v225, v3
	v_fma_f32 v216, v216, v128, v160
	v_fma_f32 v217, v217, v129, v161
	v_fma_f32 v218, v218, v130, v162
	v_fma_f32 v219, v219, v131, v163
	v_cvt_pk_bf16_f32 v196, v216, v217
	v_cvt_pk_bf16_f32 v197, v218, v219
	global_store_dwordx2 v194, v[196:197], s[26:27] offset:0
	v_mul_f32_e32 v216, v225, v4
	v_mul_f32_e32 v217, v225, v5
	v_mul_f32_e32 v218, v225, v6
	v_mul_f32_e32 v219, v225, v7
	v_fma_f32 v216, v216, v132, v164
	v_fma_f32 v217, v217, v133, v165
	v_fma_f32 v218, v218, v134, v166
	v_fma_f32 v219, v219, v135, v167
	v_cvt_pk_bf16_f32 v220, v216, v217
	v_cvt_pk_bf16_f32 v221, v218, v219
	global_store_dwordx2 v194, v[220:221], s[26:27] offset:512
	v_mul_f32_e32 v216, v225, v8
	v_mul_f32_e32 v217, v225, v9
	v_mul_f32_e32 v218, v225, v10
	v_mul_f32_e32 v219, v225, v11
	v_fma_f32 v216, v216, v136, v168
	v_fma_f32 v217, v217, v137, v169
	v_fma_f32 v218, v218, v138, v170
	v_fma_f32 v219, v219, v139, v171
	v_cvt_pk_bf16_f32 v196, v216, v217
	v_cvt_pk_bf16_f32 v197, v218, v219
	global_store_dwordx2 v194, v[196:197], s[26:27] offset:1024
	v_mul_f32_e32 v216, v225, v12
	v_mul_f32_e32 v217, v225, v13
	v_mul_f32_e32 v218, v225, v14
	v_mul_f32_e32 v219, v225, v15
	v_fma_f32 v216, v216, v140, v172
	v_fma_f32 v217, v217, v141, v173
	v_fma_f32 v218, v218, v142, v174
	v_fma_f32 v219, v219, v143, v175
	v_cvt_pk_bf16_f32 v220, v216, v217
	v_cvt_pk_bf16_f32 v221, v218, v219
	global_store_dwordx2 v194, v[220:221], s[26:27] offset:1536
	v_mul_f32_e32 v216, v225, v16
	v_mul_f32_e32 v217, v225, v17
	v_mul_f32_e32 v218, v225, v18
	v_mul_f32_e32 v219, v225, v19
	v_fma_f32 v216, v216, v144, v176
	v_fma_f32 v217, v217, v145, v177
	v_fma_f32 v218, v218, v146, v178
	v_fma_f32 v219, v219, v147, v179
	v_cvt_pk_bf16_f32 v196, v216, v217
	v_cvt_pk_bf16_f32 v197, v218, v219
	global_store_dwordx2 v194, v[196:197], s[26:27] offset:2048
	v_mul_f32_e32 v216, v225, v20
	v_mul_f32_e32 v217, v225, v21
	v_mul_f32_e32 v218, v225, v22
	v_mul_f32_e32 v219, v225, v23
	v_fma_f32 v216, v216, v148, v180
	v_fma_f32 v217, v217, v149, v181
	v_fma_f32 v218, v218, v150, v182
	v_fma_f32 v219, v219, v151, v183
	v_cvt_pk_bf16_f32 v220, v216, v217
	v_cvt_pk_bf16_f32 v221, v218, v219
	global_store_dwordx2 v194, v[220:221], s[26:27] offset:2560
	v_mul_f32_e32 v216, v225, v24
	v_mul_f32_e32 v217, v225, v25
	v_mul_f32_e32 v218, v225, v26
	v_mul_f32_e32 v219, v225, v27
	v_fma_f32 v216, v216, v152, v184
	v_fma_f32 v217, v217, v153, v185
	v_fma_f32 v218, v218, v154, v186
	v_fma_f32 v219, v219, v155, v187
	v_cvt_pk_bf16_f32 v196, v216, v217
; __device__ __forceinline__ unsigned cvt_pk_bf16(float lo, float hi) { unsigned r; asm volatile("v_cvt_pk_bf16_f32 %0, %1, %2" : "=v"(r) : "v"(lo), "v"(hi)); return r; }
; __device__ __forceinline__ void modulate_store(const f32x4 (&v)[8], float rstd, const float* pn, const float* modr, bf16_t* orow, int lane) {
; #pragma unroll
;     for (int j = 0; j < 8; ++j) { const int col = 4 * lane + 256 * j;
;         const f32x4 g = *(const f32x4*)(pn + col), sh = *(const f32x4*)(modr + col), sc = *(const f32x4*)(modr + DM + col);
;         const f32x4 hh = v[j] * rstd * g * (sc + 1.f) + sh;
;         u32x2 w; w.x = cvt_pk_bf16(hh[0], hh[1]); w.y = cvt_pk_bf16(hh[2], hh[3]);
;         *(u32x2*)(orow + col) = w; }
; __global__ void __launch_bounds__(NWAVES * 64, 2) mk_fwd(Args args) {
;     ...
;         for (int row0 = F.gw * 3; row0 < MT; row0 += F.NGW * 3) {
;             f32x4 v[3][8]; u32x2 yw[3][8];
; #pragma unroll
;             for (int q = 0; q < 3; ++q) { const int row = row0 + q; const float* src = row < ML ? x + (size_t)row * DM : ctx + (size_t)(row - ML) * DM; load_row_f32(src, F.lane, v[q]);
;                 const bf16_t* yr = Y + (size_t)row * DM;
; #pragma unroll
;                 for (int j = 0; j < 8; ++j) yw[q][j] = *(const u32x2*)(yr + 4 * F.lane + 256 * j); }
;     ...
;                 const float* m0 = mod + (size_t)r * 6144;
; #pragma unroll
;                 for (int j = 0; j < 8; ++j) { const int col = 4 * F.lane + 256 * j; const f32x4 gt = *(const f32x4*)(m0 + 2 * DM + col), pn = *(const f32x4*)(post_norm + col);
	v_cvt_pk_bf16_f32 v197, v218, v219
	global_store_dwordx2 v194, v[196:197], s[26:27] offset:3072
	v_mul_f32_e32 v216, v225, v28
	v_mul_f32_e32 v217, v225, v29
	v_mul_f32_e32 v218, v225, v30
	v_mul_f32_e32 v219, v225, v31
	v_fma_f32 v216, v216, v156, v188
	v_fma_f32 v217, v217, v157, v189
	v_fma_f32 v218, v218, v158, v190
	v_fma_f32 v219, v219, v159, v191
	v_cvt_pk_bf16_f32 v220, v216, v217
	v_cvt_pk_bf16_f32 v221, v218, v219
	global_store_dwordx2 v194, v[220:221], s[26:27] offset:3584
	s_add_i32 s0, s6, 2
	s_cmp_lt_u32 s0, 0x4000
	s_cselect_b32 s10, s68, s72
	s_cselect_b32 s11, s69, s73
	s_cselect_b32 s1, 0, 0x4000
	s_sub_i32 s1, s0, s1
	s_lshl_b32 s1, s1, 13
	s_add_u32 s10, s10, s1
	s_addc_u32 s11, s11, 0
	s_add_i32 s0, s6, 2
	s_lshl_b32 s1, s0, 12
	s_add_u32 s22, s84, s1
	s_addc_u32 s23, s85, 0
	s_add_u32 s22, s22, 0x11800000
	s_addc_u32 s23, s23, 0
	global_load_dwordx4 v[0:3], v192, s[10:11] offset:0 nt
	global_load_dwordx4 v[4:7], v192, s[10:11] offset:1024 nt
	global_load_dwordx4 v[8:11], v192, s[10:11] offset:2048 nt
	global_load_dwordx4 v[12:15], v192, s[10:11] offset:3072 nt
	global_load_dwordx4 v[16:19], v193, s[10:11] offset:0 nt
	global_load_dwordx4 v[20:23], v193, s[10:11] offset:1024 nt
	global_load_dwordx4 v[24:27], v193, s[10:11] offset:2048 nt
	global_load_dwordx4 v[28:31], v193, s[10:11] offset:3072 nt
	global_load_dwordx2 v[32:33], v194, s[22:23] offset:0 nt
	global_load_dwordx2 v[34:35], v194, s[22:23] offset:512 nt
	global_load_dwordx2 v[36:37], v194, s[22:23] offset:1024 nt
	global_load_dwordx2 v[38:39], v194, s[22:23] offset:1536 nt
	global_load_dwordx2 v[40:41], v194, s[22:23] offset:2048 nt
	global_load_dwordx2 v[42:43], v194, s[22:23] offset:2560 nt
	global_load_dwordx2 v[44:45], v194, s[22:23] offset:3072 nt
	global_load_dwordx2 v[46:47], v194, s[22:23] offset:3584 nt
	s_add_i32 s0, s6, 1
	s_add_i32 s0, s6, 1
	s_lshr_b32 s8, s0, 11
	s_cmp_lt_u32 s0, 0x4000
	s_cselect_b32 s8, s8, 8
	s_cmp_eq_u32 s8, s7
	s_cbranch_scc1 .Lp6_np1
	s_mov_b32 s7, s8
	s_add_i32 s1, s8, 9
	s_mul_i32 s1, s1, 0x6000
	s_add_u32 s44, s84, s1
	s_addc_u32 s45, s85, 0
	s_add_u32 s44, s44, 0x2000
	s_addc_u32 s45, s45, 0
	s_add_i32 s1, s8, 9
	s_mul_i32 s1, s1, 0x6000
	s_add_u32 s36, s84, s1
	s_addc_u32 s37, s85, 0
	s_add_u32 s38, s80, 0x2000
	s_addc_u32 s39, s81, 0
	s_mul_i32 s1, s8, 0x6000
	s_add_u32 s34, s84, s1
	s_addc_u32 s35, s85, 0
	s_add_u32 s34, s34, 0x4000
	s_addc_u32 s35, s35, 0
	global_load_dwordx4 v[96:99], v192, s[34:35] offset:0
	global_load_dwordx4 v[200:203], v192, s[82:83] offset:0
	global_load_dwordx4 v[100:103], v192, s[34:35] offset:1024
	global_load_dwordx4 v[204:207], v192, s[82:83] offset:1024
	global_load_dwordx4 v[104:107], v192, s[34:35] offset:2048
	global_load_dwordx4 v[208:211], v192, s[82:83] offset:2048
	global_load_dwordx4 v[108:111], v192, s[34:35] offset:3072
	global_load_dwordx4 v[212:215], v192, s[82:83] offset:3072
	s_waitcnt vmcnt(0)
	v_mul_f32_e32 v96, v96, v200
	v_mul_f32_e32 v97, v97, v201
	v_mul_f32_e32 v98, v98, v202
	v_mul_f32_e32 v99, v99, v203
	v_mul_f32_e32 v100, v100, v204
	v_mul_f32_e32 v101, v101, v205
	v_mul_f32_e32 v102, v102, v206
	v_mul_f32_e32 v103, v103, v207
	v_mul_f32_e32 v104, v104, v208
	v_mul_f32_e32 v105, v105, v209
	v_mul_f32_e32 v106, v106, v210
	v_mul_f32_e32 v107, v107, v211
	v_mul_f32_e32 v108, v108, v212
	v_mul_f32_e32 v109, v109, v213
	v_mul_f32_e32 v110, v110, v214
	v_mul_f32_e32 v111, v111, v215
	global_load_dwordx4 v[128:131], v192, s[38:39] offset:0
	global_load_dwordx4 v[200:203], v192, s[44:45] offset:0
	global_load_dwordx4 v[160:163], v192, s[36:37] offset:0
	global_load_dwordx4 v[132:135], v192, s[38:39] offset:1024
	global_load_dwordx4 v[204:207], v192, s[44:45] offset:1024
	global_load_dwordx4 v[164:167], v192, s[36:37] offset:1024
	global_load_dwordx4 v[136:139], v192, s[38:39] offset:2048
	global_load_dwordx4 v[208:211], v192, s[44:45] offset:2048
	global_load_dwordx4 v[168:171], v192, s[36:37] offset:2048
	global_load_dwordx4 v[140:143], v192, s[38:39] offset:3072
	global_load_dwordx4 v[212:215], v192, s[44:45] offset:3072
	global_load_dwordx4 v[172:175], v192, s[36:37] offset:3072
	s_waitcnt vmcnt(0)
	v_add_f32_e32 v200, 1.0, v200
	v_add_f32_e32 v201, 1.0, v201
	v_add_f32_e32 v202, 1.0, v202
	v_add_f32_e32 v203, 1.0, v203
	v_mul_f32_e32 v128, v128, v200
	v_mul_f32_e32 v129, v129, v201
	v_mul_f32_e32 v130, v130, v202
	v_mul_f32_e32 v131, v131, v203
	v_add_f32_e32 v204, 1.0, v204
	v_add_f32_e32 v205, 1.0, v205
	v_add_f32_e32 v206, 1.0, v206
	v_add_f32_e32 v207, 1.0, v207
	v_mul_f32_e32 v132, v132, v204
	v_mul_f32_e32 v133, v133, v205
	v_mul_f32_e32 v134, v134, v206
	v_mul_f32_e32 v135, v135, v207
	v_add_f32_e32 v208, 1.0, v208
	v_add_f32_e32 v209, 1.0, v209
	v_add_f32_e32 v210, 1.0, v210
	v_add_f32_e32 v211, 1.0, v211
	v_mul_f32_e32 v136, v136, v208
	v_mul_f32_e32 v137, v137, v209
	v_mul_f32_e32 v138, v138, v210
	v_mul_f32_e32 v139, v139, v211
	v_add_f32_e32 v212, 1.0, v212
	v_add_f32_e32 v213, 1.0, v213
	v_add_f32_e32 v214, 1.0, v214
	v_add_f32_e32 v215, 1.0, v215
	v_mul_f32_e32 v140, v140, v212
	v_mul_f32_e32 v141, v141, v213
	v_mul_f32_e32 v142, v142, v214
	v_mul_f32_e32 v143, v143, v215
	global_load_dwordx4 v[112:115], v193, s[34:35] offset:0
	global_load_dwordx4 v[200:203], v193, s[82:83] offset:0
	global_load_dwordx4 v[116:119], v193, s[34:35] offset:1024
	global_load_dwordx4 v[204:207], v193, s[82:83] offset:1024
	global_load_dwordx4 v[120:123], v193, s[34:35] offset:2048
	global_load_dwordx4 v[208:211], v193, s[82:83] offset:2048
	global_load_dwordx4 v[124:127], v193, s[34:35] offset:3072
	global_load_dwordx4 v[212:215], v193, s[82:83] offset:3072
	s_waitcnt vmcnt(0)
; __device__ __forceinline__ float bf_lo(unsigned w) { return __uint_as_float(w << 16); }
; __device__ __forceinline__ float bf_hi(unsigned w) { return __uint_as_float(w & 0xffff0000u); }
; __global__ void __launch_bounds__(NWAVES * 64, 2) mk_fwd(Args args) {
;     ...
;             for (int q = 0; q < 3; ++q) { const int row = row0 + q; const bool lat = row < ML; const int r = lat ? row / SEQ : 8;
;                 float sy = 0.f;
; #pragma unroll
;                 for (int j = 0; j < 8; ++j) { const float a = bf_lo(yw[q][j].x), b = bf_hi(yw[q][j].x), c2 = bf_lo(yw[q][j].y), d = bf_hi(yw[q][j].y); sy += (a * a + b * b) + (c2 * c2 + d * d); }
;                 const float rsy = __builtin_amdgcn_rsqf(wave_sum(sy) * (1.f / DM) + EPS);
;                 const float* m0 = mod + (size_t)r * 6144;
; #pragma unroll
;                 for (int j = 0; j < 8; ++j) { const int col = 4 * F.lane + 256 * j; const f32x4 gt = *(const f32x4*)(m0 + 2 * DM + col), pn = *(const f32x4*)(post_norm + col);
;                     const f32x4 y4 = (f32x4){bf_lo(yw[q][j].x), bf_hi(yw[q][j].x), bf_lo(yw[q][j].y), bf_hi(yw[q][j].y)};
;                     v[q][j] = v[q][j] + gt * (y4 * rsy * pn);
	v_mul_f32_e32 v112, v112, v200
	v_mul_f32_e32 v113, v113, v201
	v_mul_f32_e32 v114, v114, v202
	v_mul_f32_e32 v115, v115, v203
	v_mul_f32_e32 v116, v116, v204
	v_mul_f32_e32 v117, v117, v205
	v_mul_f32_e32 v118, v118, v206
	v_mul_f32_e32 v119, v119, v207
	v_mul_f32_e32 v120, v120, v208
	v_mul_f32_e32 v121, v121, v209
	v_mul_f32_e32 v122, v122, v210
	v_mul_f32_e32 v123, v123, v211
	v_mul_f32_e32 v124, v124, v212
	v_mul_f32_e32 v125, v125, v213
	v_mul_f32_e32 v126, v126, v214
	v_mul_f32_e32 v127, v127, v215
	global_load_dwordx4 v[144:147], v193, s[38:39] offset:0
	global_load_dwordx4 v[200:203], v193, s[44:45] offset:0
	global_load_dwordx4 v[176:179], v193, s[36:37] offset:0
	global_load_dwordx4 v[148:151], v193, s[38:39] offset:1024
	global_load_dwordx4 v[204:207], v193, s[44:45] offset:1024
	global_load_dwordx4 v[180:183], v193, s[36:37] offset:1024
	global_load_dwordx4 v[152:155], v193, s[38:39] offset:2048
	global_load_dwordx4 v[208:211], v193, s[44:45] offset:2048
	global_load_dwordx4 v[184:187], v193, s[36:37] offset:2048
	global_load_dwordx4 v[156:159], v193, s[38:39] offset:3072
	global_load_dwordx4 v[212:215], v193, s[44:45] offset:3072
	global_load_dwordx4 v[188:191], v193, s[36:37] offset:3072
	s_waitcnt vmcnt(0)
	v_add_f32_e32 v200, 1.0, v200
	v_add_f32_e32 v201, 1.0, v201
	v_add_f32_e32 v202, 1.0, v202
	v_add_f32_e32 v203, 1.0, v203
	v_mul_f32_e32 v144, v144, v200
	v_mul_f32_e32 v145, v145, v201
	v_mul_f32_e32 v146, v146, v202
	v_mul_f32_e32 v147, v147, v203
	v_add_f32_e32 v204, 1.0, v204
	v_add_f32_e32 v205, 1.0, v205
	v_add_f32_e32 v206, 1.0, v206
	v_add_f32_e32 v207, 1.0, v207
	v_mul_f32_e32 v148, v148, v204
	v_mul_f32_e32 v149, v149, v205
	v_mul_f32_e32 v150, v150, v206
	v_mul_f32_e32 v151, v151, v207
	v_add_f32_e32 v208, 1.0, v208
	v_add_f32_e32 v209, 1.0, v209
	v_add_f32_e32 v210, 1.0, v210
	v_add_f32_e32 v211, 1.0, v211
	v_mul_f32_e32 v152, v152, v208
	v_mul_f32_e32 v153, v153, v209
	v_mul_f32_e32 v154, v154, v210
	v_mul_f32_e32 v155, v155, v211
	v_add_f32_e32 v212, 1.0, v212
	v_add_f32_e32 v213, 1.0, v213
	v_add_f32_e32 v214, 1.0, v214
	v_add_f32_e32 v215, 1.0, v215
	v_mul_f32_e32 v156, v156, v212
	v_mul_f32_e32 v157, v157, v213
	v_mul_f32_e32 v158, v158, v214
	v_mul_f32_e32 v159, v159, v215
.Lp6_np1:
	s_waitcnt vmcnt(32)
	v_lshlrev_b32_e32 v216, 16, v80
	v_and_b32_e32 v217, 0xffff0000, v80
	v_lshlrev_b32_e32 v218, 16, v81
	v_and_b32_e32 v219, 0xffff0000, v81
	v_mul_f32_e32 v222, v216, v216
	v_mul_f32_e32 v223, v217, v217
	v_fmac_f32_e32 v222, v218, v218
	v_fmac_f32_e32 v223, v219, v219
	v_lshlrev_b32_e32 v216, 16, v82
	v_and_b32_e32 v217, 0xffff0000, v82
	v_lshlrev_b32_e32 v218, 16, v83
	v_and_b32_e32 v219, 0xffff0000, v83
	v_fmac_f32_e32 v222, v216, v216
	v_fmac_f32_e32 v223, v217, v217
	v_fmac_f32_e32 v222, v218, v218
	v_fmac_f32_e32 v223, v219, v219
	v_lshlrev_b32_e32 v216, 16, v84
	v_and_b32_e32 v217, 0xffff0000, v84
	v_lshlrev_b32_e32 v218, 16, v85
	v_and_b32_e32 v219, 0xffff0000, v85
	v_fmac_f32_e32 v222, v216, v216
	v_fmac_f32_e32 v223, v217, v217
	v_fmac_f32_e32 v222, v218, v218
	v_fmac_f32_e32 v223, v219, v219
	v_lshlrev_b32_e32 v216, 16, v86
	v_and_b32_e32 v217, 0xffff0000, v86
	v_lshlrev_b32_e32 v218, 16, v87
	v_and_b32_e32 v219, 0xffff0000, v87
	v_fmac_f32_e32 v222, v216, v216
	v_fmac_f32_e32 v223, v217, v217
	v_fmac_f32_e32 v222, v218, v218
	v_fmac_f32_e32 v223, v219, v219
	v_lshlrev_b32_e32 v216, 16, v88
	v_and_b32_e32 v217, 0xffff0000, v88
	v_lshlrev_b32_e32 v218, 16, v89
	v_and_b32_e32 v219, 0xffff0000, v89
	v_fmac_f32_e32 v222, v216, v216
	v_fmac_f32_e32 v223, v217, v217
	v_fmac_f32_e32 v222, v218, v218
	v_fmac_f32_e32 v223, v219, v219
	v_lshlrev_b32_e32 v216, 16, v90
	v_and_b32_e32 v217, 0xffff0000, v90
	v_lshlrev_b32_e32 v218, 16, v91
	v_and_b32_e32 v219, 0xffff0000, v91
	v_fmac_f32_e32 v222, v216, v216
	v_fmac_f32_e32 v223, v217, v217
	v_fmac_f32_e32 v222, v218, v218
	v_fmac_f32_e32 v223, v219, v219
	v_lshlrev_b32_e32 v216, 16, v92
	v_and_b32_e32 v217, 0xffff0000, v92
	v_lshlrev_b32_e32 v218, 16, v93
	v_and_b32_e32 v219, 0xffff0000, v93
	v_fmac_f32_e32 v222, v216, v216
	v_fmac_f32_e32 v223, v217, v217
	v_fmac_f32_e32 v222, v218, v218
	v_fmac_f32_e32 v223, v219, v219
	v_lshlrev_b32_e32 v216, 16, v94
	v_and_b32_e32 v217, 0xffff0000, v94
	v_lshlrev_b32_e32 v218, 16, v95
	v_and_b32_e32 v219, 0xffff0000, v95
	v_fmac_f32_e32 v222, v216, v216
	v_fmac_f32_e32 v223, v217, v217
	v_fmac_f32_e32 v222, v218, v218
	v_fmac_f32_e32 v223, v219, v219
	v_add_f32_e32 v222, v222, v223
	s_nop 1
	v_add_f32_dpp v224, v222, v222 quad_perm:[1,0,3,2] row_mask:0xf bank_mask:0xf
	s_nop 1
	v_add_f32_dpp v224, v224, v224 quad_perm:[2,3,0,1] row_mask:0xf bank_mask:0xf
	s_nop 1
	v_add_f32_dpp v224, v224, v224 row_half_mirror row_mask:0xf bank_mask:0xf
	s_nop 1
	v_add_f32_dpp v224, v224, v224 row_mirror row_mask:0xf bank_mask:0xf
	s_nop 1
	v_readlane_b32 s40, v224, 0
	v_readlane_b32 s41, v224, 16
	v_readlane_b32 s42, v224, 32
	v_readlane_b32 s43, v224, 48
	s_nop 1
	v_mov_b32_e32 v225, s40
	v_add_f32_e32 v225, s41, v225
	v_add_f32_e32 v225, s42, v225
	v_add_f32_e32 v225, s43, v225
	v_fmamk_f32 v225, v225, 0x3a000000, v195
	v_rsq_f32_e32 v225, v225
	s_nop 0
	s_add_i32 s0, s6, 1
	s_cmp_lt_u32 s0, 0x4000
	s_cselect_b32 s24, s94, s84
	s_cselect_b32 s25, s95, s85
	s_cselect_b32 s44, 0, 0x16000000
	s_cselect_b32 s1, 0, 0x4000
	s_sub_i32 s1, s0, s1
	s_lshl_b32 s1, s1, 13
	s_add_u32 s24, s24, s1
	s_addc_u32 s25, s25, 0
	s_add_u32 s24, s24, s44
	s_addc_u32 s25, s25, 0
	v_lshlrev_b32_e32 v216, 16, v80
	v_and_b32_e32 v217, 0xffff0000, v80
	v_lshlrev_b32_e32 v218, 16, v81
	v_and_b32_e32 v219, 0xffff0000, v81
	v_mul_f32_e32 v216, v225, v216
; __device__ __forceinline__ float bf_lo(unsigned w) { return __uint_as_float(w << 16); }
; __device__ __forceinline__ float bf_hi(unsigned w) { return __uint_as_float(w & 0xffff0000u); }
; __global__ void __launch_bounds__(NWAVES * 64, 2) mk_fwd(Args args) {
;     ...
;                 for (int j = 0; j < 8; ++j) { const int col = 4 * F.lane + 256 * j; const f32x4 gt = *(const f32x4*)(m0 + 2 * DM + col), pn = *(const f32x4*)(post_norm + col);
;                     const f32x4 y4 = (f32x4){bf_lo(yw[q][j].x), bf_hi(yw[q][j].x), bf_lo(yw[q][j].y), bf_hi(yw[q][j].y)};
;                     v[q][j] = v[q][j] + gt * (y4 * rsy * pn);
;                     if (lat) *(f32x4*)(args.out + (size_t)row * DM + col) = v[q][j]; }
;                 const float rstd = __builtin_amdgcn_rsqf(sumsq8(v[q]) * (1.f / DM) + EPS);
;                 modulate_store(v[q], rstd, pre_norm + DM, mod + (size_t)(9 + r) * 6144, H + (size_t)row * DM, F.lane); }
	v_mul_f32_e32 v217, v225, v217
	v_mul_f32_e32 v218, v225, v218
	v_mul_f32_e32 v219, v225, v219
	v_fmac_f32_e32 v48, v96, v216
	v_fmac_f32_e32 v49, v97, v217
	v_fmac_f32_e32 v50, v98, v218
	v_fmac_f32_e32 v51, v99, v219
	global_store_dwordx4 v192, v[48:51], s[24:25] offset:0
	v_lshlrev_b32_e32 v216, 16, v82
	v_and_b32_e32 v217, 0xffff0000, v82
	v_lshlrev_b32_e32 v218, 16, v83
	v_and_b32_e32 v219, 0xffff0000, v83
	v_mul_f32_e32 v216, v225, v216
	v_mul_f32_e32 v217, v225, v217
	v_mul_f32_e32 v218, v225, v218
	v_mul_f32_e32 v219, v225, v219
	v_fmac_f32_e32 v52, v100, v216
	v_fmac_f32_e32 v53, v101, v217
	v_fmac_f32_e32 v54, v102, v218
	v_fmac_f32_e32 v55, v103, v219
	global_store_dwordx4 v192, v[52:55], s[24:25] offset:1024
	v_lshlrev_b32_e32 v216, 16, v84
	v_and_b32_e32 v217, 0xffff0000, v84
	v_lshlrev_b32_e32 v218, 16, v85
	v_and_b32_e32 v219, 0xffff0000, v85
	v_mul_f32_e32 v216, v225, v216
	v_mul_f32_e32 v217, v225, v217
	v_mul_f32_e32 v218, v225, v218
	v_mul_f32_e32 v219, v225, v219
	v_fmac_f32_e32 v56, v104, v216
	v_fmac_f32_e32 v57, v105, v217
	v_fmac_f32_e32 v58, v106, v218
	v_fmac_f32_e32 v59, v107, v219
	global_store_dwordx4 v192, v[56:59], s[24:25] offset:2048
	v_lshlrev_b32_e32 v216, 16, v86
	v_and_b32_e32 v217, 0xffff0000, v86
	v_lshlrev_b32_e32 v218, 16, v87
	v_and_b32_e32 v219, 0xffff0000, v87
	v_mul_f32_e32 v216, v225, v216
	v_mul_f32_e32 v217, v225, v217
	v_mul_f32_e32 v218, v225, v218
	v_mul_f32_e32 v219, v225, v219
	v_fmac_f32_e32 v60, v108, v216
	v_fmac_f32_e32 v61, v109, v217
	v_fmac_f32_e32 v62, v110, v218
	v_fmac_f32_e32 v63, v111, v219
	global_store_dwordx4 v192, v[60:63], s[24:25] offset:3072
	v_lshlrev_b32_e32 v216, 16, v88
	v_and_b32_e32 v217, 0xffff0000, v88
	v_lshlrev_b32_e32 v218, 16, v89
	v_and_b32_e32 v219, 0xffff0000, v89
	v_mul_f32_e32 v216, v225, v216
	v_mul_f32_e32 v217, v225, v217
	v_mul_f32_e32 v218, v225, v218
	v_mul_f32_e32 v219, v225, v219
	v_fmac_f32_e32 v64, v112, v216
	v_fmac_f32_e32 v65, v113, v217
	v_fmac_f32_e32 v66, v114, v218
	v_fmac_f32_e32 v67, v115, v219
	global_store_dwordx4 v193, v[64:67], s[24:25] offset:0
	v_lshlrev_b32_e32 v216, 16, v90
	v_and_b32_e32 v217, 0xffff0000, v90
	v_lshlrev_b32_e32 v218, 16, v91
	v_and_b32_e32 v219, 0xffff0000, v91
	v_mul_f32_e32 v216, v225, v216
	v_mul_f32_e32 v217, v225, v217
	v_mul_f32_e32 v218, v225, v218
	v_mul_f32_e32 v219, v225, v219
	v_fmac_f32_e32 v68, v116, v216
	v_fmac_f32_e32 v69, v117, v217
	v_fmac_f32_e32 v70, v118, v218
	v_fmac_f32_e32 v71, v119, v219
	global_store_dwordx4 v193, v[68:71], s[24:25] offset:1024
	v_lshlrev_b32_e32 v216, 16, v92
	v_and_b32_e32 v217, 0xffff0000, v92
	v_lshlrev_b32_e32 v218, 16, v93
	v_and_b32_e32 v219, 0xffff0000, v93
	v_mul_f32_e32 v216, v225, v216
	v_mul_f32_e32 v217, v225, v217
	v_mul_f32_e32 v218, v225, v218
	v_mul_f32_e32 v219, v225, v219
	v_fmac_f32_e32 v72, v120, v216
	v_fmac_f32_e32 v73, v121, v217
	v_fmac_f32_e32 v74, v122, v218
	v_fmac_f32_e32 v75, v123, v219
	global_store_dwordx4 v193, v[72:75], s[24:25] offset:2048
	v_lshlrev_b32_e32 v216, 16, v94
	v_and_b32_e32 v217, 0xffff0000, v94
	v_lshlrev_b32_e32 v218, 16, v95
	v_and_b32_e32 v219, 0xffff0000, v95
	v_mul_f32_e32 v216, v225, v216
	v_mul_f32_e32 v217, v225, v217
	v_mul_f32_e32 v218, v225, v218
	v_mul_f32_e32 v219, v225, v219
	v_fmac_f32_e32 v76, v124, v216
	v_fmac_f32_e32 v77, v125, v217
	v_fmac_f32_e32 v78, v126, v218
	v_fmac_f32_e32 v79, v127, v219
	global_store_dwordx4 v193, v[76:79], s[24:25] offset:3072
	v_mul_f32_e32 v222, v48, v48
	v_mul_f32_e32 v223, v49, v49
	v_fmac_f32_e32 v222, v50, v50
	v_fmac_f32_e32 v223, v51, v51
	v_fmac_f32_e32 v222, v52, v52
	v_fmac_f32_e32 v223, v53, v53
	v_fmac_f32_e32 v222, v54, v54
	v_fmac_f32_e32 v223, v55, v55
	v_fmac_f32_e32 v222, v56, v56
	v_fmac_f32_e32 v223, v57, v57
	v_fmac_f32_e32 v222, v58, v58
	v_fmac_f32_e32 v223, v59, v59
	v_fmac_f32_e32 v222, v60, v60
	v_fmac_f32_e32 v223, v61, v61
	v_fmac_f32_e32 v222, v62, v62
	v_fmac_f32_e32 v223, v63, v63
	v_fmac_f32_e32 v222, v64, v64
	v_fmac_f32_e32 v223, v65, v65
	v_fmac_f32_e32 v222, v66, v66
	v_fmac_f32_e32 v223, v67, v67
	v_fmac_f32_e32 v222, v68, v68
	v_fmac_f32_e32 v223, v69, v69
	v_fmac_f32_e32 v222, v70, v70
	v_fmac_f32_e32 v223, v71, v71
	v_fmac_f32_e32 v222, v72, v72
	v_fmac_f32_e32 v223, v73, v73
	v_fmac_f32_e32 v222, v74, v74
	v_fmac_f32_e32 v223, v75, v75
	v_fmac_f32_e32 v222, v76, v76
	v_fmac_f32_e32 v223, v77, v77
	v_fmac_f32_e32 v222, v78, v78
	v_fmac_f32_e32 v223, v79, v79
	v_add_f32_e32 v222, v222, v223
	s_nop 1
	v_add_f32_dpp v224, v222, v222 quad_perm:[1,0,3,2] row_mask:0xf bank_mask:0xf
	s_nop 1
	v_add_f32_dpp v224, v224, v224 quad_perm:[2,3,0,1] row_mask:0xf bank_mask:0xf
	s_nop 1
	v_add_f32_dpp v224, v224, v224 row_half_mirror row_mask:0xf bank_mask:0xf
	s_nop 1
	v_add_f32_dpp v224, v224, v224 row_mirror row_mask:0xf bank_mask:0xf
	s_nop 1
	v_readlane_b32 s40, v224, 0
	v_readlane_b32 s41, v224, 16
	v_readlane_b32 s42, v224, 32
	v_readlane_b32 s43, v224, 48
	s_nop 1
	v_mov_b32_e32 v225, s40
	v_add_f32_e32 v225, s41, v225
	v_add_f32_e32 v225, s42, v225
	v_add_f32_e32 v225, s43, v225
	v_fmamk_f32 v225, v225, 0x3a000000, v195
	v_rsq_f32_e32 v225, v225
	s_nop 0
	s_add_i32 s0, s6, 1
	s_lshl_b32 s1, s0, 12
	s_add_u32 s26, s84, s1
	s_addc_u32 s27, s85, 0
	s_add_u32 s26, s26, 0x4000000
	s_addc_u32 s27, s27, 0
	v_mul_f32_e32 v216, v225, v48
	v_mul_f32_e32 v217, v225, v49
	v_mul_f32_e32 v218, v225, v50
	v_mul_f32_e32 v219, v225, v51
	v_fma_f32 v216, v216, v128, v160
	v_fma_f32 v217, v217, v129, v161
	v_fma_f32 v218, v218, v130, v162
	v_fma_f32 v219, v219, v131, v163
	v_cvt_pk_bf16_f32 v196, v216, v217
	v_cvt_pk_bf16_f32 v197, v218, v219
; __device__ __forceinline__ unsigned cvt_pk_bf16(float lo, float hi) { unsigned r; asm volatile("v_cvt_pk_bf16_f32 %0, %1, %2" : "=v"(r) : "v"(lo), "v"(hi)); return r; }
; __device__ __forceinline__ void modulate_store(const f32x4 (&v)[8], float rstd, const float* pn, const float* modr, bf16_t* orow, int lane) {
; #pragma unroll
;     for (int j = 0; j < 8; ++j) { const int col = 4 * lane + 256 * j;
;         const f32x4 g = *(const f32x4*)(pn + col), sh = *(const f32x4*)(modr + col), sc = *(const f32x4*)(modr + DM + col);
;         const f32x4 hh = v[j] * rstd * g * (sc + 1.f) + sh;
;         u32x2 w; w.x = cvt_pk_bf16(hh[0], hh[1]); w.y = cvt_pk_bf16(hh[2], hh[3]);
;         *(u32x2*)(orow + col) = w; }
; __global__ void __launch_bounds__(NWAVES * 64, 2) mk_fwd(Args args) {
;     ...
;         for (int row0 = F.gw * 3; row0 < MT; row0 += F.NGW * 3) {
;             f32x4 v[3][8]; u32x2 yw[3][8];
; #pragma unroll
;             for (int q = 0; q < 3; ++q) { const int row = row0 + q; const float* src = row < ML ? x + (size_t)row * DM : ctx + (size_t)(row - ML) * DM; load_row_f32(src, F.lane, v[q]);
;                 const bf16_t* yr = Y + (size_t)row * DM;
; #pragma unroll
;                 for (int j = 0; j < 8; ++j) yw[q][j] = *(const u32x2*)(yr + 4 * F.lane + 256 * j); }
	global_store_dwordx2 v194, v[196:197], s[26:27] offset:0
	v_mul_f32_e32 v216, v225, v52
	v_mul_f32_e32 v217, v225, v53
	v_mul_f32_e32 v218, v225, v54
	v_mul_f32_e32 v219, v225, v55
	v_fma_f32 v216, v216, v132, v164
	v_fma_f32 v217, v217, v133, v165
	v_fma_f32 v218, v218, v134, v166
	v_fma_f32 v219, v219, v135, v167
	v_cvt_pk_bf16_f32 v220, v216, v217
	v_cvt_pk_bf16_f32 v221, v218, v219
	global_store_dwordx2 v194, v[220:221], s[26:27] offset:512
	v_mul_f32_e32 v216, v225, v56
	v_mul_f32_e32 v217, v225, v57
	v_mul_f32_e32 v218, v225, v58
	v_mul_f32_e32 v219, v225, v59
	v_fma_f32 v216, v216, v136, v168
	v_fma_f32 v217, v217, v137, v169
	v_fma_f32 v218, v218, v138, v170
	v_fma_f32 v219, v219, v139, v171
	v_cvt_pk_bf16_f32 v196, v216, v217
	v_cvt_pk_bf16_f32 v197, v218, v219
	global_store_dwordx2 v194, v[196:197], s[26:27] offset:1024
	v_mul_f32_e32 v216, v225, v60
	v_mul_f32_e32 v217, v225, v61
	v_mul_f32_e32 v218, v225, v62
	v_mul_f32_e32 v219, v225, v63
	v_fma_f32 v216, v216, v140, v172
	v_fma_f32 v217, v217, v141, v173
	v_fma_f32 v218, v218, v142, v174
	v_fma_f32 v219, v219, v143, v175
	v_cvt_pk_bf16_f32 v220, v216, v217
	v_cvt_pk_bf16_f32 v221, v218, v219
	global_store_dwordx2 v194, v[220:221], s[26:27] offset:1536
	v_mul_f32_e32 v216, v225, v64
	v_mul_f32_e32 v217, v225, v65
	v_mul_f32_e32 v218, v225, v66
	v_mul_f32_e32 v219, v225, v67
	v_fma_f32 v216, v216, v144, v176
	v_fma_f32 v217, v217, v145, v177
	v_fma_f32 v218, v218, v146, v178
	v_fma_f32 v219, v219, v147, v179
	v_cvt_pk_bf16_f32 v196, v216, v217
	v_cvt_pk_bf16_f32 v197, v218, v219
	global_store_dwordx2 v194, v[196:197], s[26:27] offset:2048
	v_mul_f32_e32 v216, v225, v68
	v_mul_f32_e32 v217, v225, v69
	v_mul_f32_e32 v218, v225, v70
	v_mul_f32_e32 v219, v225, v71
	v_fma_f32 v216, v216, v148, v180
	v_fma_f32 v217, v217, v149, v181
	v_fma_f32 v218, v218, v150, v182
	v_fma_f32 v219, v219, v151, v183
	v_cvt_pk_bf16_f32 v220, v216, v217
	v_cvt_pk_bf16_f32 v221, v218, v219
	global_store_dwordx2 v194, v[220:221], s[26:27] offset:2560
	v_mul_f32_e32 v216, v225, v72
	v_mul_f32_e32 v217, v225, v73
	v_mul_f32_e32 v218, v225, v74
	v_mul_f32_e32 v219, v225, v75
	v_fma_f32 v216, v216, v152, v184
	v_fma_f32 v217, v217, v153, v185
	v_fma_f32 v218, v218, v154, v186
	v_fma_f32 v219, v219, v155, v187
	v_cvt_pk_bf16_f32 v196, v216, v217
	v_cvt_pk_bf16_f32 v197, v218, v219
	global_store_dwordx2 v194, v[196:197], s[26:27] offset:3072
	v_mul_f32_e32 v216, v225, v76
	v_mul_f32_e32 v217, v225, v77
	v_mul_f32_e32 v218, v225, v78
	v_mul_f32_e32 v219, v225, v79
	v_fma_f32 v216, v216, v156, v188
	v_fma_f32 v217, v217, v157, v189
	v_fma_f32 v218, v218, v158, v190
	v_fma_f32 v219, v219, v159, v191
	v_cvt_pk_bf16_f32 v220, v216, v217
	v_cvt_pk_bf16_f32 v221, v218, v219
	global_store_dwordx2 v194, v[220:221], s[26:27] offset:3584
	s_add_i32 s0, s6, 3
	s_cmp_lt_u32 s0, 0x4000
	s_cselect_b32 s10, s68, s72
	s_cselect_b32 s11, s69, s73
	s_cselect_b32 s1, 0, 0x4000
	s_sub_i32 s1, s0, s1
	s_lshl_b32 s1, s1, 13
	s_add_u32 s10, s10, s1
	s_addc_u32 s11, s11, 0
	s_add_i32 s0, s6, 3
	s_lshl_b32 s1, s0, 12
	s_add_u32 s22, s84, s1
	s_addc_u32 s23, s85, 0
	s_add_u32 s22, s22, 0x11800000
	s_addc_u32 s23, s23, 0
	global_load_dwordx4 v[48:51], v192, s[10:11] offset:0 nt
	global_load_dwordx4 v[52:55], v192, s[10:11] offset:1024 nt
	global_load_dwordx4 v[56:59], v192, s[10:11] offset:2048 nt
	global_load_dwordx4 v[60:63], v192, s[10:11] offset:3072 nt
	global_load_dwordx4 v[64:67], v193, s[10:11] offset:0 nt
	global_load_dwordx4 v[68:71], v193, s[10:11] offset:1024 nt
	global_load_dwordx4 v[72:75], v193, s[10:11] offset:2048 nt
	global_load_dwordx4 v[76:79], v193, s[10:11] offset:3072 nt
	global_load_dwordx2 v[80:81], v194, s[22:23] offset:0 nt
	global_load_dwordx2 v[82:83], v194, s[22:23] offset:512 nt
	global_load_dwordx2 v[84:85], v194, s[22:23] offset:1024 nt
	global_load_dwordx2 v[86:87], v194, s[22:23] offset:1536 nt
	global_load_dwordx2 v[88:89], v194, s[22:23] offset:2048 nt
	global_load_dwordx2 v[90:91], v194, s[22:23] offset:2560 nt
	global_load_dwordx2 v[92:93], v194, s[22:23] offset:3072 nt
	global_load_dwordx2 v[94:95], v194, s[22:23] offset:3584 nt
	s_add_i32 s0, s6, 2
	s_add_i32 s0, s6, 2
	s_lshr_b32 s8, s0, 11
	s_cmp_lt_u32 s0, 0x4000
	s_cselect_b32 s8, s8, 8
	s_cmp_eq_u32 s8, s7
	s_cbranch_scc1 .Lp6_np2
; __device__ __forceinline__ unsigned cvt_pk_bf16(float lo, float hi) { unsigned r; asm volatile("v_cvt_pk_bf16_f32 %0, %1, %2" : "=v"(r) : "v"(lo), "v"(hi)); return r; }
; __device__ __forceinline__ float bf_lo(unsigned w) { return __uint_as_float(w << 16); }
; __device__ __forceinline__ float bf_hi(unsigned w) { return __uint_as_float(w & 0xffff0000u); }
; __device__ __forceinline__ void modulate_store(const f32x4 (&v)[8], float rstd, const float* pn, const float* modr, bf16_t* orow, int lane) {
; #pragma unroll
;     for (int j = 0; j < 8; ++j) { const int col = 4 * lane + 256 * j;
;         const f32x4 g = *(const f32x4*)(pn + col), sh = *(const f32x4*)(modr + col), sc = *(const f32x4*)(modr + DM + col);
;         const f32x4 hh = v[j] * rstd * g * (sc + 1.f) + sh;
;         u32x2 w; w.x = cvt_pk_bf16(hh[0], hh[1]); w.y = cvt_pk_bf16(hh[2], hh[3]);
;         *(u32x2*)(orow + col) = w; }
; __global__ void __launch_bounds__(NWAVES * 64, 2) mk_fwd(Args args) {
;     ...
;                 const float* m0 = mod + (size_t)r * 6144;
; #pragma unroll
;                 for (int j = 0; j < 8; ++j) { const int col = 4 * F.lane + 256 * j; const f32x4 gt = *(const f32x4*)(m0 + 2 * DM + col), pn = *(const f32x4*)(post_norm + col);
;                     const f32x4 y4 = (f32x4){bf_lo(yw[q][j].x), bf_hi(yw[q][j].x), bf_lo(yw[q][j].y), bf_hi(yw[q][j].y)};
;                     v[q][j] = v[q][j] + gt * (y4 * rsy * pn);
	s_mov_b32 s7, s8
	s_add_i32 s1, s8, 9
	s_mul_i32 s1, s1, 0x6000
	s_add_u32 s44, s84, s1
	s_addc_u32 s45, s85, 0
	s_add_u32 s44, s44, 0x2000
	s_addc_u32 s45, s45, 0
	s_add_i32 s1, s8, 9
	s_mul_i32 s1, s1, 0x6000
	s_add_u32 s36, s84, s1
	s_addc_u32 s37, s85, 0
	s_add_u32 s38, s80, 0x2000
	s_addc_u32 s39, s81, 0
	s_mul_i32 s1, s8, 0x6000
	s_add_u32 s34, s84, s1
	s_addc_u32 s35, s85, 0
	s_add_u32 s34, s34, 0x4000
	s_addc_u32 s35, s35, 0
	global_load_dwordx4 v[96:99], v192, s[34:35] offset:0
	global_load_dwordx4 v[200:203], v192, s[82:83] offset:0
	global_load_dwordx4 v[100:103], v192, s[34:35] offset:1024
	global_load_dwordx4 v[204:207], v192, s[82:83] offset:1024
	global_load_dwordx4 v[104:107], v192, s[34:35] offset:2048
	global_load_dwordx4 v[208:211], v192, s[82:83] offset:2048
	global_load_dwordx4 v[108:111], v192, s[34:35] offset:3072
	global_load_dwordx4 v[212:215], v192, s[82:83] offset:3072
	s_waitcnt vmcnt(0)
	v_mul_f32_e32 v96, v96, v200
	v_mul_f32_e32 v97, v97, v201
	v_mul_f32_e32 v98, v98, v202
	v_mul_f32_e32 v99, v99, v203
	v_mul_f32_e32 v100, v100, v204
	v_mul_f32_e32 v101, v101, v205
	v_mul_f32_e32 v102, v102, v206
	v_mul_f32_e32 v103, v103, v207
	v_mul_f32_e32 v104, v104, v208
	v_mul_f32_e32 v105, v105, v209
	v_mul_f32_e32 v106, v106, v210
	v_mul_f32_e32 v107, v107, v211
	v_mul_f32_e32 v108, v108, v212
	v_mul_f32_e32 v109, v109, v213
	v_mul_f32_e32 v110, v110, v214
	v_mul_f32_e32 v111, v111, v215
	global_load_dwordx4 v[128:131], v192, s[38:39] offset:0
	global_load_dwordx4 v[200:203], v192, s[44:45] offset:0
	global_load_dwordx4 v[160:163], v192, s[36:37] offset:0
	global_load_dwordx4 v[132:135], v192, s[38:39] offset:1024
	global_load_dwordx4 v[204:207], v192, s[44:45] offset:1024
	global_load_dwordx4 v[164:167], v192, s[36:37] offset:1024
	global_load_dwordx4 v[136:139], v192, s[38:39] offset:2048
	global_load_dwordx4 v[208:211], v192, s[44:45] offset:2048
	global_load_dwordx4 v[168:171], v192, s[36:37] offset:2048
	global_load_dwordx4 v[140:143], v192, s[38:39] offset:3072
	global_load_dwordx4 v[212:215], v192, s[44:45] offset:3072
	global_load_dwordx4 v[172:175], v192, s[36:37] offset:3072
	s_waitcnt vmcnt(0)
	v_add_f32_e32 v200, 1.0, v200
	v_add_f32_e32 v201, 1.0, v201
	v_add_f32_e32 v202, 1.0, v202
	v_add_f32_e32 v203, 1.0, v203
	v_mul_f32_e32 v128, v128, v200
	v_mul_f32_e32 v129, v129, v201
	v_mul_f32_e32 v130, v130, v202
	v_mul_f32_e32 v131, v131, v203
	v_add_f32_e32 v204, 1.0, v204
	v_add_f32_e32 v205, 1.0, v205
	v_add_f32_e32 v206, 1.0, v206
	v_add_f32_e32 v207, 1.0, v207
	v_mul_f32_e32 v132, v132, v204
	v_mul_f32_e32 v133, v133, v205
	v_mul_f32_e32 v134, v134, v206
	v_mul_f32_e32 v135, v135, v207
	v_add_f32_e32 v208, 1.0, v208
	v_add_f32_e32 v209, 1.0, v209
	v_add_f32_e32 v210, 1.0, v210
	v_add_f32_e32 v211, 1.0, v211
	v_mul_f32_e32 v136, v136, v208
	v_mul_f32_e32 v137, v137, v209
	v_mul_f32_e32 v138, v138, v210
	v_mul_f32_e32 v139, v139, v211
	v_add_f32_e32 v212, 1.0, v212
	v_add_f32_e32 v213, 1.0, v213
	v_add_f32_e32 v214, 1.0, v214
	v_add_f32_e32 v215, 1.0, v215
	v_mul_f32_e32 v140, v140, v212
	v_mul_f32_e32 v141, v141, v213
	v_mul_f32_e32 v142, v142, v214
	v_mul_f32_e32 v143, v143, v215
	global_load_dwordx4 v[112:115], v193, s[34:35] offset:0
	global_load_dwordx4 v[200:203], v193, s[82:83] offset:0
	global_load_dwordx4 v[116:119], v193, s[34:35] offset:1024
	global_load_dwordx4 v[204:207], v193, s[82:83] offset:1024
	global_load_dwordx4 v[120:123], v193, s[34:35] offset:2048
	global_load_dwordx4 v[208:211], v193, s[82:83] offset:2048
	global_load_dwordx4 v[124:127], v193, s[34:35] offset:3072
	global_load_dwordx4 v[212:215], v193, s[82:83] offset:3072
	s_waitcnt vmcnt(0)
	v_mul_f32_e32 v112, v112, v200
	v_mul_f32_e32 v113, v113, v201
	v_mul_f32_e32 v114, v114, v202
	v_mul_f32_e32 v115, v115, v203
	v_mul_f32_e32 v116, v116, v204
	v_mul_f32_e32 v117, v117, v205
	v_mul_f32_e32 v118, v118, v206
	v_mul_f32_e32 v119, v119, v207
	v_mul_f32_e32 v120, v120, v208
	v_mul_f32_e32 v121, v121, v209
	v_mul_f32_e32 v122, v122, v210
	v_mul_f32_e32 v123, v123, v211
	v_mul_f32_e32 v124, v124, v212
	v_mul_f32_e32 v125, v125, v213
	v_mul_f32_e32 v126, v126, v214
	v_mul_f32_e32 v127, v127, v215
	global_load_dwordx4 v[144:147], v193, s[38:39] offset:0
	global_load_dwordx4 v[200:203], v193, s[44:45] offset:0
	global_load_dwordx4 v[176:179], v193, s[36:37] offset:0
	global_load_dwordx4 v[148:151], v193, s[38:39] offset:1024
	global_load_dwordx4 v[204:207], v193, s[44:45] offset:1024
	global_load_dwordx4 v[180:183], v193, s[36:37] offset:1024
	global_load_dwordx4 v[152:155], v193, s[38:39] offset:2048
	global_load_dwordx4 v[208:211], v193, s[44:45] offset:2048
	global_load_dwordx4 v[184:187], v193, s[36:37] offset:2048
	global_load_dwordx4 v[156:159], v193, s[38:39] offset:3072
	global_load_dwordx4 v[212:215], v193, s[44:45] offset:3072
	global_load_dwordx4 v[188:191], v193, s[36:37] offset:3072
	s_waitcnt vmcnt(0)
	v_add_f32_e32 v200, 1.0, v200
	v_add_f32_e32 v201, 1.0, v201
	v_add_f32_e32 v202, 1.0, v202
	v_add_f32_e32 v203, 1.0, v203
	v_mul_f32_e32 v144, v144, v200
	v_mul_f32_e32 v145, v145, v201
	v_mul_f32_e32 v146, v146, v202
	v_mul_f32_e32 v147, v147, v203
	v_add_f32_e32 v204, 1.0, v204
	v_add_f32_e32 v205, 1.0, v205
	v_add_f32_e32 v206, 1.0, v206
	v_add_f32_e32 v207, 1.0, v207
	v_mul_f32_e32 v148, v148, v204
	v_mul_f32_e32 v149, v149, v205
	v_mul_f32_e32 v150, v150, v206
	v_mul_f32_e32 v151, v151, v207
	v_add_f32_e32 v208, 1.0, v208
	v_add_f32_e32 v209, 1.0, v209
	v_add_f32_e32 v210, 1.0, v210
	v_add_f32_e32 v211, 1.0, v211
	v_mul_f32_e32 v152, v152, v208
	v_mul_f32_e32 v153, v153, v209
	v_mul_f32_e32 v154, v154, v210
	v_mul_f32_e32 v155, v155, v211
	v_add_f32_e32 v212, 1.0, v212
	v_add_f32_e32 v213, 1.0, v213
	v_add_f32_e32 v214, 1.0, v214
	v_add_f32_e32 v215, 1.0, v215
	v_mul_f32_e32 v156, v156, v212
	v_mul_f32_e32 v157, v157, v213
	v_mul_f32_e32 v158, v158, v214
	v_mul_f32_e32 v159, v159, v215
; __device__ __forceinline__ float bf_lo(unsigned w) { return __uint_as_float(w << 16); }
; __device__ __forceinline__ float bf_hi(unsigned w) { return __uint_as_float(w & 0xffff0000u); }
; __global__ void __launch_bounds__(NWAVES * 64, 2) mk_fwd(Args args) {
;     ...
;             for (int q = 0; q < 3; ++q) { const int row = row0 + q; const bool lat = row < ML; const int r = lat ? row / SEQ : 8;
;                 float sy = 0.f;
; #pragma unroll
;                 for (int j = 0; j < 8; ++j) { const float a = bf_lo(yw[q][j].x), b = bf_hi(yw[q][j].x), c2 = bf_lo(yw[q][j].y), d = bf_hi(yw[q][j].y); sy += (a * a + b * b) + (c2 * c2 + d * d); }
;                 const float rsy = __builtin_amdgcn_rsqf(wave_sum(sy) * (1.f / DM) + EPS);
;                 const float* m0 = mod + (size_t)r * 6144;
; #pragma unroll
;                 for (int j = 0; j < 8; ++j) { const int col = 4 * F.lane + 256 * j; const f32x4 gt = *(const f32x4*)(m0 + 2 * DM + col), pn = *(const f32x4*)(post_norm + col);
;                     const f32x4 y4 = (f32x4){bf_lo(yw[q][j].x), bf_hi(yw[q][j].x), bf_lo(yw[q][j].y), bf_hi(yw[q][j].y)};
;                     v[q][j] = v[q][j] + gt * (y4 * rsy * pn);
;                     if (lat) *(f32x4*)(args.out + (size_t)row * DM + col) = v[q][j]; }
.Lp6_np2:
	s_waitcnt vmcnt(32)
	v_lshlrev_b32_e32 v216, 16, v32
	v_and_b32_e32 v217, 0xffff0000, v32
	v_lshlrev_b32_e32 v218, 16, v33
	v_and_b32_e32 v219, 0xffff0000, v33
	v_mul_f32_e32 v222, v216, v216
	v_mul_f32_e32 v223, v217, v217
	v_fmac_f32_e32 v222, v218, v218
	v_fmac_f32_e32 v223, v219, v219
	v_lshlrev_b32_e32 v216, 16, v34
	v_and_b32_e32 v217, 0xffff0000, v34
	v_lshlrev_b32_e32 v218, 16, v35
	v_and_b32_e32 v219, 0xffff0000, v35
	v_fmac_f32_e32 v222, v216, v216
	v_fmac_f32_e32 v223, v217, v217
	v_fmac_f32_e32 v222, v218, v218
	v_fmac_f32_e32 v223, v219, v219
	v_lshlrev_b32_e32 v216, 16, v36
	v_and_b32_e32 v217, 0xffff0000, v36
	v_lshlrev_b32_e32 v218, 16, v37
	v_and_b32_e32 v219, 0xffff0000, v37
	v_fmac_f32_e32 v222, v216, v216
	v_fmac_f32_e32 v223, v217, v217
	v_fmac_f32_e32 v222, v218, v218
	v_fmac_f32_e32 v223, v219, v219
	v_lshlrev_b32_e32 v216, 16, v38
	v_and_b32_e32 v217, 0xffff0000, v38
	v_lshlrev_b32_e32 v218, 16, v39
	v_and_b32_e32 v219, 0xffff0000, v39
	v_fmac_f32_e32 v222, v216, v216
	v_fmac_f32_e32 v223, v217, v217
	v_fmac_f32_e32 v222, v218, v218
	v_fmac_f32_e32 v223, v219, v219
	v_lshlrev_b32_e32 v216, 16, v40
	v_and_b32_e32 v217, 0xffff0000, v40
	v_lshlrev_b32_e32 v218, 16, v41
	v_and_b32_e32 v219, 0xffff0000, v41
	v_fmac_f32_e32 v222, v216, v216
	v_fmac_f32_e32 v223, v217, v217
	v_fmac_f32_e32 v222, v218, v218
	v_fmac_f32_e32 v223, v219, v219
	v_lshlrev_b32_e32 v216, 16, v42
	v_and_b32_e32 v217, 0xffff0000, v42
	v_lshlrev_b32_e32 v218, 16, v43
	v_and_b32_e32 v219, 0xffff0000, v43
	v_fmac_f32_e32 v222, v216, v216
	v_fmac_f32_e32 v223, v217, v217
	v_fmac_f32_e32 v222, v218, v218
	v_fmac_f32_e32 v223, v219, v219
	v_lshlrev_b32_e32 v216, 16, v44
	v_and_b32_e32 v217, 0xffff0000, v44
	v_lshlrev_b32_e32 v218, 16, v45
	v_and_b32_e32 v219, 0xffff0000, v45
	v_fmac_f32_e32 v222, v216, v216
	v_fmac_f32_e32 v223, v217, v217
	v_fmac_f32_e32 v222, v218, v218
	v_fmac_f32_e32 v223, v219, v219
	v_lshlrev_b32_e32 v216, 16, v46
	v_and_b32_e32 v217, 0xffff0000, v46
	v_lshlrev_b32_e32 v218, 16, v47
	v_and_b32_e32 v219, 0xffff0000, v47
	v_fmac_f32_e32 v222, v216, v216
	v_fmac_f32_e32 v223, v217, v217
	v_fmac_f32_e32 v222, v218, v218
	v_fmac_f32_e32 v223, v219, v219
	v_add_f32_e32 v222, v222, v223
	s_nop 1
	v_add_f32_dpp v224, v222, v222 quad_perm:[1,0,3,2] row_mask:0xf bank_mask:0xf
	s_nop 1
	v_add_f32_dpp v224, v224, v224 quad_perm:[2,3,0,1] row_mask:0xf bank_mask:0xf
	s_nop 1
	v_add_f32_dpp v224, v224, v224 row_half_mirror row_mask:0xf bank_mask:0xf
	s_nop 1
	v_add_f32_dpp v224, v224, v224 row_mirror row_mask:0xf bank_mask:0xf
	s_nop 1
	v_readlane_b32 s40, v224, 0
	v_readlane_b32 s41, v224, 16
	v_readlane_b32 s42, v224, 32
	v_readlane_b32 s43, v224, 48
	s_nop 1
	v_mov_b32_e32 v225, s40
	v_add_f32_e32 v225, s41, v225
	v_add_f32_e32 v225, s42, v225
	v_add_f32_e32 v225, s43, v225
	v_fmamk_f32 v225, v225, 0x3a000000, v195
	v_rsq_f32_e32 v225, v225
	s_nop 0
	s_add_i32 s0, s6, 2
	s_cmp_lt_u32 s0, 0x4000
	s_cselect_b32 s24, s94, s84
	s_cselect_b32 s25, s95, s85
	s_cselect_b32 s44, 0, 0x16000000
	s_cselect_b32 s1, 0, 0x4000
	s_sub_i32 s1, s0, s1
	s_lshl_b32 s1, s1, 13
	s_add_u32 s24, s24, s1
	s_addc_u32 s25, s25, 0
	s_add_u32 s24, s24, s44
	s_addc_u32 s25, s25, 0
	v_lshlrev_b32_e32 v216, 16, v32
	v_and_b32_e32 v217, 0xffff0000, v32
	v_lshlrev_b32_e32 v218, 16, v33
	v_and_b32_e32 v219, 0xffff0000, v33
	v_mul_f32_e32 v216, v225, v216
	v_mul_f32_e32 v217, v225, v217
	v_mul_f32_e32 v218, v225, v218
	v_mul_f32_e32 v219, v225, v219
	v_fmac_f32_e32 v0, v96, v216
	v_fmac_f32_e32 v1, v97, v217
	v_fmac_f32_e32 v2, v98, v218
	v_fmac_f32_e32 v3, v99, v219
	global_store_dwordx4 v192, v[0:3], s[24:25] offset:0
	v_lshlrev_b32_e32 v216, 16, v34
	v_and_b32_e32 v217, 0xffff0000, v34
	v_lshlrev_b32_e32 v218, 16, v35
	v_and_b32_e32 v219, 0xffff0000, v35
	v_mul_f32_e32 v216, v225, v216
	v_mul_f32_e32 v217, v225, v217
	v_mul_f32_e32 v218, v225, v218
	v_mul_f32_e32 v219, v225, v219
	v_fmac_f32_e32 v4, v100, v216
	v_fmac_f32_e32 v5, v101, v217
	v_fmac_f32_e32 v6, v102, v218
	v_fmac_f32_e32 v7, v103, v219
	global_store_dwordx4 v192, v[4:7], s[24:25] offset:1024
	v_lshlrev_b32_e32 v216, 16, v36
	v_and_b32_e32 v217, 0xffff0000, v36
	v_lshlrev_b32_e32 v218, 16, v37
	v_and_b32_e32 v219, 0xffff0000, v37
	v_mul_f32_e32 v216, v225, v216
	v_mul_f32_e32 v217, v225, v217
	v_mul_f32_e32 v218, v225, v218
	v_mul_f32_e32 v219, v225, v219
	v_fmac_f32_e32 v8, v104, v216
	v_fmac_f32_e32 v9, v105, v217
	v_fmac_f32_e32 v10, v106, v218
	v_fmac_f32_e32 v11, v107, v219
	global_store_dwordx4 v192, v[8:11], s[24:25] offset:2048
	v_lshlrev_b32_e32 v216, 16, v38
	v_and_b32_e32 v217, 0xffff0000, v38
	v_lshlrev_b32_e32 v218, 16, v39
	v_and_b32_e32 v219, 0xffff0000, v39
	v_mul_f32_e32 v216, v225, v216
	v_mul_f32_e32 v217, v225, v217
	v_mul_f32_e32 v218, v225, v218
	v_mul_f32_e32 v219, v225, v219
	v_fmac_f32_e32 v12, v108, v216
	v_fmac_f32_e32 v13, v109, v217
	v_fmac_f32_e32 v14, v110, v218
	v_fmac_f32_e32 v15, v111, v219
	global_store_dwordx4 v192, v[12:15], s[24:25] offset:3072
	v_lshlrev_b32_e32 v216, 16, v40
	v_and_b32_e32 v217, 0xffff0000, v40
	v_lshlrev_b32_e32 v218, 16, v41
	v_and_b32_e32 v219, 0xffff0000, v41
	v_mul_f32_e32 v216, v225, v216
	v_mul_f32_e32 v217, v225, v217
	v_mul_f32_e32 v218, v225, v218
	v_mul_f32_e32 v219, v225, v219
	v_fmac_f32_e32 v16, v112, v216
	v_fmac_f32_e32 v17, v113, v217
	v_fmac_f32_e32 v18, v114, v218
	v_fmac_f32_e32 v19, v115, v219
	global_store_dwordx4 v193, v[16:19], s[24:25] offset:0
	v_lshlrev_b32_e32 v216, 16, v42
	v_and_b32_e32 v217, 0xffff0000, v42
	v_lshlrev_b32_e32 v218, 16, v43
	v_and_b32_e32 v219, 0xffff0000, v43
	v_mul_f32_e32 v216, v225, v216
; __device__ __forceinline__ unsigned cvt_pk_bf16(float lo, float hi) { unsigned r; asm volatile("v_cvt_pk_bf16_f32 %0, %1, %2" : "=v"(r) : "v"(lo), "v"(hi)); return r; }
; __device__ __forceinline__ float bf_lo(unsigned w) { return __uint_as_float(w << 16); }
; __device__ __forceinline__ float bf_hi(unsigned w) { return __uint_as_float(w & 0xffff0000u); }
; __device__ __forceinline__ float sumsq8(const f32x4 (&v)[8]) {
;     float s = 0.f;
; #pragma unroll
;     for (int j = 0; j < 8; ++j) s += (v[j][0] * v[j][0] + v[j][1] * v[j][1]) + (v[j][2] * v[j][2] + v[j][3] * v[j][3]);
;     return wave_sum(s);
; }
; __device__ __forceinline__ void modulate_store(const f32x4 (&v)[8], float rstd, const float* pn, const float* modr, bf16_t* orow, int lane) {
; #pragma unroll
;     for (int j = 0; j < 8; ++j) { const int col = 4 * lane + 256 * j;
;         const f32x4 g = *(const f32x4*)(pn + col), sh = *(const f32x4*)(modr + col), sc = *(const f32x4*)(modr + DM + col);
;         const f32x4 hh = v[j] * rstd * g * (sc + 1.f) + sh;
;         u32x2 w; w.x = cvt_pk_bf16(hh[0], hh[1]); w.y = cvt_pk_bf16(hh[2], hh[3]);
;         *(u32x2*)(orow + col) = w; }
; __global__ void __launch_bounds__(NWAVES * 64, 2) mk_fwd(Args args) {
;     ...
;                 for (int j = 0; j < 8; ++j) { const int col = 4 * F.lane + 256 * j; const f32x4 gt = *(const f32x4*)(m0 + 2 * DM + col), pn = *(const f32x4*)(post_norm + col);
;                     const f32x4 y4 = (f32x4){bf_lo(yw[q][j].x), bf_hi(yw[q][j].x), bf_lo(yw[q][j].y), bf_hi(yw[q][j].y)};
;                     v[q][j] = v[q][j] + gt * (y4 * rsy * pn);
;                     if (lat) *(f32x4*)(args.out + (size_t)row * DM + col) = v[q][j]; }
;                 const float rstd = __builtin_amdgcn_rsqf(sumsq8(v[q]) * (1.f / DM) + EPS);
;                 modulate_store(v[q], rstd, pre_norm + DM, mod + (size_t)(9 + r) * 6144, H + (size_t)row * DM, F.lane); }
	v_mul_f32_e32 v217, v225, v217
	v_mul_f32_e32 v218, v225, v218
	v_mul_f32_e32 v219, v225, v219
	v_fmac_f32_e32 v20, v116, v216
	v_fmac_f32_e32 v21, v117, v217
	v_fmac_f32_e32 v22, v118, v218
	v_fmac_f32_e32 v23, v119, v219
	global_store_dwordx4 v193, v[20:23], s[24:25] offset:1024
	v_lshlrev_b32_e32 v216, 16, v44
	v_and_b32_e32 v217, 0xffff0000, v44
	v_lshlrev_b32_e32 v218, 16, v45
	v_and_b32_e32 v219, 0xffff0000, v45
	v_mul_f32_e32 v216, v225, v216
	v_mul_f32_e32 v217, v225, v217
	v_mul_f32_e32 v218, v225, v218
	v_mul_f32_e32 v219, v225, v219
	v_fmac_f32_e32 v24, v120, v216
	v_fmac_f32_e32 v25, v121, v217
	v_fmac_f32_e32 v26, v122, v218
	v_fmac_f32_e32 v27, v123, v219
	global_store_dwordx4 v193, v[24:27], s[24:25] offset:2048
	v_lshlrev_b32_e32 v216, 16, v46
	v_and_b32_e32 v217, 0xffff0000, v46
	v_lshlrev_b32_e32 v218, 16, v47
	v_and_b32_e32 v219, 0xffff0000, v47
	v_mul_f32_e32 v216, v225, v216
	v_mul_f32_e32 v217, v225, v217
	v_mul_f32_e32 v218, v225, v218
	v_mul_f32_e32 v219, v225, v219
	v_fmac_f32_e32 v28, v124, v216
	v_fmac_f32_e32 v29, v125, v217
	v_fmac_f32_e32 v30, v126, v218
	v_fmac_f32_e32 v31, v127, v219
	global_store_dwordx4 v193, v[28:31], s[24:25] offset:3072
	v_mul_f32_e32 v222, v0, v0
	v_mul_f32_e32 v223, v1, v1
	v_fmac_f32_e32 v222, v2, v2
	v_fmac_f32_e32 v223, v3, v3
	v_fmac_f32_e32 v222, v4, v4
	v_fmac_f32_e32 v223, v5, v5
	v_fmac_f32_e32 v222, v6, v6
	v_fmac_f32_e32 v223, v7, v7
	v_fmac_f32_e32 v222, v8, v8
	v_fmac_f32_e32 v223, v9, v9
	v_fmac_f32_e32 v222, v10, v10
	v_fmac_f32_e32 v223, v11, v11
	v_fmac_f32_e32 v222, v12, v12
	v_fmac_f32_e32 v223, v13, v13
	v_fmac_f32_e32 v222, v14, v14
	v_fmac_f32_e32 v223, v15, v15
	v_fmac_f32_e32 v222, v16, v16
	v_fmac_f32_e32 v223, v17, v17
	v_fmac_f32_e32 v222, v18, v18
	v_fmac_f32_e32 v223, v19, v19
	v_fmac_f32_e32 v222, v20, v20
	v_fmac_f32_e32 v223, v21, v21
	v_fmac_f32_e32 v222, v22, v22
	v_fmac_f32_e32 v223, v23, v23
	v_fmac_f32_e32 v222, v24, v24
	v_fmac_f32_e32 v223, v25, v25
	v_fmac_f32_e32 v222, v26, v26
	v_fmac_f32_e32 v223, v27, v27
	v_fmac_f32_e32 v222, v28, v28
	v_fmac_f32_e32 v223, v29, v29
	v_fmac_f32_e32 v222, v30, v30
	v_fmac_f32_e32 v223, v31, v31
	v_add_f32_e32 v222, v222, v223
	s_nop 1
	v_add_f32_dpp v224, v222, v222 quad_perm:[1,0,3,2] row_mask:0xf bank_mask:0xf
	s_nop 1
	v_add_f32_dpp v224, v224, v224 quad_perm:[2,3,0,1] row_mask:0xf bank_mask:0xf
	s_nop 1
	v_add_f32_dpp v224, v224, v224 row_half_mirror row_mask:0xf bank_mask:0xf
	s_nop 1
	v_add_f32_dpp v224, v224, v224 row_mirror row_mask:0xf bank_mask:0xf
	s_nop 1
	v_readlane_b32 s40, v224, 0
	v_readlane_b32 s41, v224, 16
	v_readlane_b32 s42, v224, 32
	v_readlane_b32 s43, v224, 48
	s_nop 1
	v_mov_b32_e32 v225, s40
	v_add_f32_e32 v225, s41, v225
	v_add_f32_e32 v225, s42, v225
	v_add_f32_e32 v225, s43, v225
	v_fmamk_f32 v225, v225, 0x3a000000, v195
	v_rsq_f32_e32 v225, v225
	s_nop 0
	s_add_i32 s0, s6, 2
	s_lshl_b32 s1, s0, 12
	s_add_u32 s26, s84, s1
	s_addc_u32 s27, s85, 0
	s_add_u32 s26, s26, 0x4000000
	s_addc_u32 s27, s27, 0
	v_mul_f32_e32 v216, v225, v0
	v_mul_f32_e32 v217, v225, v1
	v_mul_f32_e32 v218, v225, v2
	v_mul_f32_e32 v219, v225, v3
	v_fma_f32 v216, v216, v128, v160
	v_fma_f32 v217, v217, v129, v161
	v_fma_f32 v218, v218, v130, v162
	v_fma_f32 v219, v219, v131, v163
	v_cvt_pk_bf16_f32 v196, v216, v217
	v_cvt_pk_bf16_f32 v197, v218, v219
	global_store_dwordx2 v194, v[196:197], s[26:27] offset:0
	v_mul_f32_e32 v216, v225, v4
	v_mul_f32_e32 v217, v225, v5
	v_mul_f32_e32 v218, v225, v6
	v_mul_f32_e32 v219, v225, v7
	v_fma_f32 v216, v216, v132, v164
	v_fma_f32 v217, v217, v133, v165
	v_fma_f32 v218, v218, v134, v166
	v_fma_f32 v219, v219, v135, v167
	v_cvt_pk_bf16_f32 v220, v216, v217
	v_cvt_pk_bf16_f32 v221, v218, v219
	global_store_dwordx2 v194, v[220:221], s[26:27] offset:512
	v_mul_f32_e32 v216, v225, v8
	v_mul_f32_e32 v217, v225, v9
	v_mul_f32_e32 v218, v225, v10
	v_mul_f32_e32 v219, v225, v11
	v_fma_f32 v216, v216, v136, v168
	v_fma_f32 v217, v217, v137, v169
	v_fma_f32 v218, v218, v138, v170
	v_fma_f32 v219, v219, v139, v171
	v_cvt_pk_bf16_f32 v196, v216, v217
	v_cvt_pk_bf16_f32 v197, v218, v219
	global_store_dwordx2 v194, v[196:197], s[26:27] offset:1024
	v_mul_f32_e32 v216, v225, v12
	v_mul_f32_e32 v217, v225, v13
	v_mul_f32_e32 v218, v225, v14
	v_mul_f32_e32 v219, v225, v15
	v_fma_f32 v216, v216, v140, v172
	v_fma_f32 v217, v217, v141, v173
	v_fma_f32 v218, v218, v142, v174
	v_fma_f32 v219, v219, v143, v175
	v_cvt_pk_bf16_f32 v220, v216, v217
	v_cvt_pk_bf16_f32 v221, v218, v219
	global_store_dwordx2 v194, v[220:221], s[26:27] offset:1536
	v_mul_f32_e32 v216, v225, v16
	v_mul_f32_e32 v217, v225, v17
	v_mul_f32_e32 v218, v225, v18
	v_mul_f32_e32 v219, v225, v19
	v_fma_f32 v216, v216, v144, v176
	v_fma_f32 v217, v217, v145, v177
	v_fma_f32 v218, v218, v146, v178
	v_fma_f32 v219, v219, v147, v179
	v_cvt_pk_bf16_f32 v196, v216, v217
	v_cvt_pk_bf16_f32 v197, v218, v219
	global_store_dwordx2 v194, v[196:197], s[26:27] offset:2048
	v_mul_f32_e32 v216, v225, v20
	v_mul_f32_e32 v217, v225, v21
	v_mul_f32_e32 v218, v225, v22
	v_mul_f32_e32 v219, v225, v23
	v_fma_f32 v216, v216, v148, v180
	v_fma_f32 v217, v217, v149, v181
	v_fma_f32 v218, v218, v150, v182
	v_fma_f32 v219, v219, v151, v183
	v_cvt_pk_bf16_f32 v220, v216, v217
	v_cvt_pk_bf16_f32 v221, v218, v219
	global_store_dwordx2 v194, v[220:221], s[26:27] offset:2560
	v_mul_f32_e32 v216, v225, v24
	v_mul_f32_e32 v217, v225, v25
	v_mul_f32_e32 v218, v225, v26
	v_mul_f32_e32 v219, v225, v27
	v_fma_f32 v216, v216, v152, v184
	v_fma_f32 v217, v217, v153, v185
	v_fma_f32 v218, v218, v154, v186
	v_fma_f32 v219, v219, v155, v187
	v_cvt_pk_bf16_f32 v196, v216, v217
; __device__ __forceinline__ unsigned cvt_pk_bf16(float lo, float hi) { unsigned r; asm volatile("v_cvt_pk_bf16_f32 %0, %1, %2" : "=v"(r) : "v"(lo), "v"(hi)); return r; }
; __device__ __forceinline__ void modulate_store(const f32x4 (&v)[8], float rstd, const float* pn, const float* modr, bf16_t* orow, int lane) {
; #pragma unroll
;     for (int j = 0; j < 8; ++j) { const int col = 4 * lane + 256 * j;
;         const f32x4 g = *(const f32x4*)(pn + col), sh = *(const f32x4*)(modr + col), sc = *(const f32x4*)(modr + DM + col);
;         const f32x4 hh = v[j] * rstd * g * (sc + 1.f) + sh;
;         u32x2 w; w.x = cvt_pk_bf16(hh[0], hh[1]); w.y = cvt_pk_bf16(hh[2], hh[3]);
;         *(u32x2*)(orow + col) = w; }
; __global__ void __launch_bounds__(NWAVES * 64, 2) mk_fwd(Args args) {
;     ...
;         for (int row0 = F.gw * 3; row0 < MT; row0 += F.NGW * 3) {
;             f32x4 v[3][8]; u32x2 yw[3][8];
; #pragma unroll
;             for (int q = 0; q < 3; ++q) { const int row = row0 + q; const float* src = row < ML ? x + (size_t)row * DM : ctx + (size_t)(row - ML) * DM; load_row_f32(src, F.lane, v[q]);
;                 const bf16_t* yr = Y + (size_t)row * DM;
; #pragma unroll
;                 for (int j = 0; j < 8; ++j) yw[q][j] = *(const u32x2*)(yr + 4 * F.lane + 256 * j); }
;     ...
;                 const float* m0 = mod + (size_t)r * 6144;
; #pragma unroll
;                 for (int j = 0; j < 8; ++j) { const int col = 4 * F.lane + 256 * j; const f32x4 gt = *(const f32x4*)(m0 + 2 * DM + col), pn = *(const f32x4*)(post_norm + col);
	v_cvt_pk_bf16_f32 v197, v218, v219
	global_store_dwordx2 v194, v[196:197], s[26:27] offset:3072
	v_mul_f32_e32 v216, v225, v28
	v_mul_f32_e32 v217, v225, v29
	v_mul_f32_e32 v218, v225, v30
	v_mul_f32_e32 v219, v225, v31
	v_fma_f32 v216, v216, v156, v188
	v_fma_f32 v217, v217, v157, v189
	v_fma_f32 v218, v218, v158, v190
	v_fma_f32 v219, v219, v159, v191
	v_cvt_pk_bf16_f32 v220, v216, v217
	v_cvt_pk_bf16_f32 v221, v218, v219
	global_store_dwordx2 v194, v[220:221], s[26:27] offset:3584
	s_add_i32 s0, s6, 4
	s_cmp_lt_u32 s0, 0x4000
	s_cselect_b32 s10, s68, s72
	s_cselect_b32 s11, s69, s73
	s_cselect_b32 s1, 0, 0x4000
	s_sub_i32 s1, s0, s1
	s_lshl_b32 s1, s1, 13
	s_add_u32 s10, s10, s1
	s_addc_u32 s11, s11, 0
	s_add_i32 s0, s6, 4
	s_lshl_b32 s1, s0, 12
	s_add_u32 s22, s84, s1
	s_addc_u32 s23, s85, 0
	s_add_u32 s22, s22, 0x11800000
	s_addc_u32 s23, s23, 0
	global_load_dwordx4 v[0:3], v192, s[10:11] offset:0 nt
	global_load_dwordx4 v[4:7], v192, s[10:11] offset:1024 nt
	global_load_dwordx4 v[8:11], v192, s[10:11] offset:2048 nt
	global_load_dwordx4 v[12:15], v192, s[10:11] offset:3072 nt
	global_load_dwordx4 v[16:19], v193, s[10:11] offset:0 nt
	global_load_dwordx4 v[20:23], v193, s[10:11] offset:1024 nt
	global_load_dwordx4 v[24:27], v193, s[10:11] offset:2048 nt
	global_load_dwordx4 v[28:31], v193, s[10:11] offset:3072 nt
	global_load_dwordx2 v[32:33], v194, s[22:23] offset:0 nt
	global_load_dwordx2 v[34:35], v194, s[22:23] offset:512 nt
	global_load_dwordx2 v[36:37], v194, s[22:23] offset:1024 nt
	global_load_dwordx2 v[38:39], v194, s[22:23] offset:1536 nt
	global_load_dwordx2 v[40:41], v194, s[22:23] offset:2048 nt
	global_load_dwordx2 v[42:43], v194, s[22:23] offset:2560 nt
	global_load_dwordx2 v[44:45], v194, s[22:23] offset:3072 nt
	global_load_dwordx2 v[46:47], v194, s[22:23] offset:3584 nt
	s_add_i32 s0, s6, 3
	s_add_i32 s0, s6, 3
	s_lshr_b32 s8, s0, 11
	s_cmp_lt_u32 s0, 0x4000
	s_cselect_b32 s8, s8, 8
	s_cmp_eq_u32 s8, s7
	s_cbranch_scc1 .Lp6_np3
	s_mov_b32 s7, s8
	s_add_i32 s1, s8, 9
	s_mul_i32 s1, s1, 0x6000
	s_add_u32 s44, s84, s1
	s_addc_u32 s45, s85, 0
	s_add_u32 s44, s44, 0x2000
	s_addc_u32 s45, s45, 0
	s_add_i32 s1, s8, 9
	s_mul_i32 s1, s1, 0x6000
	s_add_u32 s36, s84, s1
	s_addc_u32 s37, s85, 0
	s_add_u32 s38, s80, 0x2000
	s_addc_u32 s39, s81, 0
	s_mul_i32 s1, s8, 0x6000
	s_add_u32 s34, s84, s1
	s_addc_u32 s35, s85, 0
	s_add_u32 s34, s34, 0x4000
	s_addc_u32 s35, s35, 0
	global_load_dwordx4 v[96:99], v192, s[34:35] offset:0
	global_load_dwordx4 v[200:203], v192, s[82:83] offset:0
	global_load_dwordx4 v[100:103], v192, s[34:35] offset:1024
	global_load_dwordx4 v[204:207], v192, s[82:83] offset:1024
	global_load_dwordx4 v[104:107], v192, s[34:35] offset:2048
	global_load_dwordx4 v[208:211], v192, s[82:83] offset:2048
	global_load_dwordx4 v[108:111], v192, s[34:35] offset:3072
	global_load_dwordx4 v[212:215], v192, s[82:83] offset:3072
	s_waitcnt vmcnt(0)
	v_mul_f32_e32 v96, v96, v200
	v_mul_f32_e32 v97, v97, v201
	v_mul_f32_e32 v98, v98, v202
	v_mul_f32_e32 v99, v99, v203
	v_mul_f32_e32 v100, v100, v204
	v_mul_f32_e32 v101, v101, v205
	v_mul_f32_e32 v102, v102, v206
	v_mul_f32_e32 v103, v103, v207
	v_mul_f32_e32 v104, v104, v208
	v_mul_f32_e32 v105, v105, v209
	v_mul_f32_e32 v106, v106, v210
	v_mul_f32_e32 v107, v107, v211
	v_mul_f32_e32 v108, v108, v212
	v_mul_f32_e32 v109, v109, v213
	v_mul_f32_e32 v110, v110, v214
	v_mul_f32_e32 v111, v111, v215
	global_load_dwordx4 v[128:131], v192, s[38:39] offset:0
	global_load_dwordx4 v[200:203], v192, s[44:45] offset:0
	global_load_dwordx4 v[160:163], v192, s[36:37] offset:0
	global_load_dwordx4 v[132:135], v192, s[38:39] offset:1024
	global_load_dwordx4 v[204:207], v192, s[44:45] offset:1024
	global_load_dwordx4 v[164:167], v192, s[36:37] offset:1024
	global_load_dwordx4 v[136:139], v192, s[38:39] offset:2048
	global_load_dwordx4 v[208:211], v192, s[44:45] offset:2048
	global_load_dwordx4 v[168:171], v192, s[36:37] offset:2048
	global_load_dwordx4 v[140:143], v192, s[38:39] offset:3072
	global_load_dwordx4 v[212:215], v192, s[44:45] offset:3072
	global_load_dwordx4 v[172:175], v192, s[36:37] offset:3072
	s_waitcnt vmcnt(0)
	v_add_f32_e32 v200, 1.0, v200
	v_add_f32_e32 v201, 1.0, v201
	v_add_f32_e32 v202, 1.0, v202
	v_add_f32_e32 v203, 1.0, v203
	v_mul_f32_e32 v128, v128, v200
	v_mul_f32_e32 v129, v129, v201
	v_mul_f32_e32 v130, v130, v202
	v_mul_f32_e32 v131, v131, v203
	v_add_f32_e32 v204, 1.0, v204
	v_add_f32_e32 v205, 1.0, v205
	v_add_f32_e32 v206, 1.0, v206
	v_add_f32_e32 v207, 1.0, v207
	v_mul_f32_e32 v132, v132, v204
	v_mul_f32_e32 v133, v133, v205
	v_mul_f32_e32 v134, v134, v206
	v_mul_f32_e32 v135, v135, v207
	v_add_f32_e32 v208, 1.0, v208
	v_add_f32_e32 v209, 1.0, v209
	v_add_f32_e32 v210, 1.0, v210
	v_add_f32_e32 v211, 1.0, v211
	v_mul_f32_e32 v136, v136, v208
	v_mul_f32_e32 v137, v137, v209
	v_mul_f32_e32 v138, v138, v210
	v_mul_f32_e32 v139, v139, v211
	v_add_f32_e32 v212, 1.0, v212
	v_add_f32_e32 v213, 1.0, v213
	v_add_f32_e32 v214, 1.0, v214
	v_add_f32_e32 v215, 1.0, v215
	v_mul_f32_e32 v140, v140, v212
	v_mul_f32_e32 v141, v141, v213
	v_mul_f32_e32 v142, v142, v214
	v_mul_f32_e32 v143, v143, v215
	global_load_dwordx4 v[112:115], v193, s[34:35] offset:0
	global_load_dwordx4 v[200:203], v193, s[82:83] offset:0
	global_load_dwordx4 v[116:119], v193, s[34:35] offset:1024
	global_load_dwordx4 v[204:207], v193, s[82:83] offset:1024
	global_load_dwordx4 v[120:123], v193, s[34:35] offset:2048
	global_load_dwordx4 v[208:211], v193, s[82:83] offset:2048
	global_load_dwordx4 v[124:127], v193, s[34:35] offset:3072
	global_load_dwordx4 v[212:215], v193, s[82:83] offset:3072
	s_waitcnt vmcnt(0)
; __device__ __forceinline__ float bf_lo(unsigned w) { return __uint_as_float(w << 16); }
; __device__ __forceinline__ float bf_hi(unsigned w) { return __uint_as_float(w & 0xffff0000u); }
; __global__ void __launch_bounds__(NWAVES * 64, 2) mk_fwd(Args args) {
;     ...
;             for (int q = 0; q < 3; ++q) { const int row = row0 + q; const bool lat = row < ML; const int r = lat ? row / SEQ : 8;
;                 float sy = 0.f;
; #pragma unroll
;                 for (int j = 0; j < 8; ++j) { const float a = bf_lo(yw[q][j].x), b = bf_hi(yw[q][j].x), c2 = bf_lo(yw[q][j].y), d = bf_hi(yw[q][j].y); sy += (a * a + b * b) + (c2 * c2 + d * d); }
;                 const float rsy = __builtin_amdgcn_rsqf(wave_sum(sy) * (1.f / DM) + EPS);
;                 const float* m0 = mod + (size_t)r * 6144;
; #pragma unroll
;                 for (int j = 0; j < 8; ++j) { const int col = 4 * F.lane + 256 * j; const f32x4 gt = *(const f32x4*)(m0 + 2 * DM + col), pn = *(const f32x4*)(post_norm + col);
;                     const f32x4 y4 = (f32x4){bf_lo(yw[q][j].x), bf_hi(yw[q][j].x), bf_lo(yw[q][j].y), bf_hi(yw[q][j].y)};
;                     v[q][j] = v[q][j] + gt * (y4 * rsy * pn);
	v_mul_f32_e32 v112, v112, v200
	v_mul_f32_e32 v113, v113, v201
	v_mul_f32_e32 v114, v114, v202
	v_mul_f32_e32 v115, v115, v203
	v_mul_f32_e32 v116, v116, v204
	v_mul_f32_e32 v117, v117, v205
	v_mul_f32_e32 v118, v118, v206
	v_mul_f32_e32 v119, v119, v207
	v_mul_f32_e32 v120, v120, v208
	v_mul_f32_e32 v121, v121, v209
	v_mul_f32_e32 v122, v122, v210
	v_mul_f32_e32 v123, v123, v211
	v_mul_f32_e32 v124, v124, v212
	v_mul_f32_e32 v125, v125, v213
	v_mul_f32_e32 v126, v126, v214
	v_mul_f32_e32 v127, v127, v215
	global_load_dwordx4 v[144:147], v193, s[38:39] offset:0
	global_load_dwordx4 v[200:203], v193, s[44:45] offset:0
	global_load_dwordx4 v[176:179], v193, s[36:37] offset:0
	global_load_dwordx4 v[148:151], v193, s[38:39] offset:1024
	global_load_dwordx4 v[204:207], v193, s[44:45] offset:1024
	global_load_dwordx4 v[180:183], v193, s[36:37] offset:1024
	global_load_dwordx4 v[152:155], v193, s[38:39] offset:2048
	global_load_dwordx4 v[208:211], v193, s[44:45] offset:2048
	global_load_dwordx4 v[184:187], v193, s[36:37] offset:2048
	global_load_dwordx4 v[156:159], v193, s[38:39] offset:3072
	global_load_dwordx4 v[212:215], v193, s[44:45] offset:3072
	global_load_dwordx4 v[188:191], v193, s[36:37] offset:3072
	s_waitcnt vmcnt(0)
	v_add_f32_e32 v200, 1.0, v200
	v_add_f32_e32 v201, 1.0, v201
	v_add_f32_e32 v202, 1.0, v202
	v_add_f32_e32 v203, 1.0, v203
	v_mul_f32_e32 v144, v144, v200
	v_mul_f32_e32 v145, v145, v201
	v_mul_f32_e32 v146, v146, v202
	v_mul_f32_e32 v147, v147, v203
	v_add_f32_e32 v204, 1.0, v204
	v_add_f32_e32 v205, 1.0, v205
	v_add_f32_e32 v206, 1.0, v206
	v_add_f32_e32 v207, 1.0, v207
	v_mul_f32_e32 v148, v148, v204
	v_mul_f32_e32 v149, v149, v205
	v_mul_f32_e32 v150, v150, v206
	v_mul_f32_e32 v151, v151, v207
	v_add_f32_e32 v208, 1.0, v208
	v_add_f32_e32 v209, 1.0, v209
	v_add_f32_e32 v210, 1.0, v210
	v_add_f32_e32 v211, 1.0, v211
	v_mul_f32_e32 v152, v152, v208
	v_mul_f32_e32 v153, v153, v209
	v_mul_f32_e32 v154, v154, v210
	v_mul_f32_e32 v155, v155, v211
	v_add_f32_e32 v212, 1.0, v212
	v_add_f32_e32 v213, 1.0, v213
	v_add_f32_e32 v214, 1.0, v214
	v_add_f32_e32 v215, 1.0, v215
	v_mul_f32_e32 v156, v156, v212
	v_mul_f32_e32 v157, v157, v213
	v_mul_f32_e32 v158, v158, v214
	v_mul_f32_e32 v159, v159, v215
.Lp6_np3:
	s_waitcnt vmcnt(32)
	v_lshlrev_b32_e32 v216, 16, v80
	v_and_b32_e32 v217, 0xffff0000, v80
	v_lshlrev_b32_e32 v218, 16, v81
	v_and_b32_e32 v219, 0xffff0000, v81
	v_mul_f32_e32 v222, v216, v216
	v_mul_f32_e32 v223, v217, v217
	v_fmac_f32_e32 v222, v218, v218
	v_fmac_f32_e32 v223, v219, v219
	v_lshlrev_b32_e32 v216, 16, v82
	v_and_b32_e32 v217, 0xffff0000, v82
	v_lshlrev_b32_e32 v218, 16, v83
	v_and_b32_e32 v219, 0xffff0000, v83
	v_fmac_f32_e32 v222, v216, v216
	v_fmac_f32_e32 v223, v217, v217
	v_fmac_f32_e32 v222, v218, v218
	v_fmac_f32_e32 v223, v219, v219
	v_lshlrev_b32_e32 v216, 16, v84
	v_and_b32_e32 v217, 0xffff0000, v84
	v_lshlrev_b32_e32 v218, 16, v85
	v_and_b32_e32 v219, 0xffff0000, v85
	v_fmac_f32_e32 v222, v216, v216
	v_fmac_f32_e32 v223, v217, v217
	v_fmac_f32_e32 v222, v218, v218
	v_fmac_f32_e32 v223, v219, v219
	v_lshlrev_b32_e32 v216, 16, v86
	v_and_b32_e32 v217, 0xffff0000, v86
	v_lshlrev_b32_e32 v218, 16, v87
	v_and_b32_e32 v219, 0xffff0000, v87
	v_fmac_f32_e32 v222, v216, v216
	v_fmac_f32_e32 v223, v217, v217
	v_fmac_f32_e32 v222, v218, v218
	v_fmac_f32_e32 v223, v219, v219
	v_lshlrev_b32_e32 v216, 16, v88
	v_and_b32_e32 v217, 0xffff0000, v88
	v_lshlrev_b32_e32 v218, 16, v89
	v_and_b32_e32 v219, 0xffff0000, v89
	v_fmac_f32_e32 v222, v216, v216
	v_fmac_f32_e32 v223, v217, v217
	v_fmac_f32_e32 v222, v218, v218
	v_fmac_f32_e32 v223, v219, v219
	v_lshlrev_b32_e32 v216, 16, v90
	v_and_b32_e32 v217, 0xffff0000, v90
	v_lshlrev_b32_e32 v218, 16, v91
	v_and_b32_e32 v219, 0xffff0000, v91
	v_fmac_f32_e32 v222, v216, v216
	v_fmac_f32_e32 v223, v217, v217
	v_fmac_f32_e32 v222, v218, v218
	v_fmac_f32_e32 v223, v219, v219
	v_lshlrev_b32_e32 v216, 16, v92
	v_and_b32_e32 v217, 0xffff0000, v92
	v_lshlrev_b32_e32 v218, 16, v93
	v_and_b32_e32 v219, 0xffff0000, v93
	v_fmac_f32_e32 v222, v216, v216
	v_fmac_f32_e32 v223, v217, v217
	v_fmac_f32_e32 v222, v218, v218
	v_fmac_f32_e32 v223, v219, v219
	v_lshlrev_b32_e32 v216, 16, v94
	v_and_b32_e32 v217, 0xffff0000, v94
	v_lshlrev_b32_e32 v218, 16, v95
	v_and_b32_e32 v219, 0xffff0000, v95
	v_fmac_f32_e32 v222, v216, v216
	v_fmac_f32_e32 v223, v217, v217
	v_fmac_f32_e32 v222, v218, v218
	v_fmac_f32_e32 v223, v219, v219
	v_add_f32_e32 v222, v222, v223
	s_nop 1
	v_add_f32_dpp v224, v222, v222 quad_perm:[1,0,3,2] row_mask:0xf bank_mask:0xf
	s_nop 1
	v_add_f32_dpp v224, v224, v224 quad_perm:[2,3,0,1] row_mask:0xf bank_mask:0xf
	s_nop 1
	v_add_f32_dpp v224, v224, v224 row_half_mirror row_mask:0xf bank_mask:0xf
	s_nop 1
	v_add_f32_dpp v224, v224, v224 row_mirror row_mask:0xf bank_mask:0xf
	s_nop 1
	v_readlane_b32 s40, v224, 0
	v_readlane_b32 s41, v224, 16
	v_readlane_b32 s42, v224, 32
	v_readlane_b32 s43, v224, 48
	s_nop 1
	v_mov_b32_e32 v225, s40
	v_add_f32_e32 v225, s41, v225
	v_add_f32_e32 v225, s42, v225
	v_add_f32_e32 v225, s43, v225
	v_fmamk_f32 v225, v225, 0x3a000000, v195
	v_rsq_f32_e32 v225, v225
	s_nop 0
	s_add_i32 s0, s6, 3
	s_cmp_lt_u32 s0, 0x4000
	s_cselect_b32 s24, s94, s84
	s_cselect_b32 s25, s95, s85
	s_cselect_b32 s44, 0, 0x16000000
	s_cselect_b32 s1, 0, 0x4000
	s_sub_i32 s1, s0, s1
	s_lshl_b32 s1, s1, 13
	s_add_u32 s24, s24, s1
	s_addc_u32 s25, s25, 0
	s_add_u32 s24, s24, s44
	s_addc_u32 s25, s25, 0
	v_lshlrev_b32_e32 v216, 16, v80
	v_and_b32_e32 v217, 0xffff0000, v80
	v_lshlrev_b32_e32 v218, 16, v81
	v_and_b32_e32 v219, 0xffff0000, v81
	v_mul_f32_e32 v216, v225, v216
; __device__ __forceinline__ float bf_lo(unsigned w) { return __uint_as_float(w << 16); }
; __device__ __forceinline__ float bf_hi(unsigned w) { return __uint_as_float(w & 0xffff0000u); }
; __global__ void __launch_bounds__(NWAVES * 64, 2) mk_fwd(Args args) {
;     ...
;                 for (int j = 0; j < 8; ++j) { const int col = 4 * F.lane + 256 * j; const f32x4 gt = *(const f32x4*)(m0 + 2 * DM + col), pn = *(const f32x4*)(post_norm + col);
;                     const f32x4 y4 = (f32x4){bf_lo(yw[q][j].x), bf_hi(yw[q][j].x), bf_lo(yw[q][j].y), bf_hi(yw[q][j].y)};
;                     v[q][j] = v[q][j] + gt * (y4 * rsy * pn);
;                     if (lat) *(f32x4*)(args.out + (size_t)row * DM + col) = v[q][j]; }
;                 const float rstd = __builtin_amdgcn_rsqf(sumsq8(v[q]) * (1.f / DM) + EPS);
;                 modulate_store(v[q], rstd, pre_norm + DM, mod + (size_t)(9 + r) * 6144, H + (size_t)row * DM, F.lane); }
	v_mul_f32_e32 v217, v225, v217
	v_mul_f32_e32 v218, v225, v218
	v_mul_f32_e32 v219, v225, v219
	v_fmac_f32_e32 v48, v96, v216
	v_fmac_f32_e32 v49, v97, v217
	v_fmac_f32_e32 v50, v98, v218
	v_fmac_f32_e32 v51, v99, v219
	global_store_dwordx4 v192, v[48:51], s[24:25] offset:0
	v_lshlrev_b32_e32 v216, 16, v82
	v_and_b32_e32 v217, 0xffff0000, v82
	v_lshlrev_b32_e32 v218, 16, v83
	v_and_b32_e32 v219, 0xffff0000, v83
	v_mul_f32_e32 v216, v225, v216
	v_mul_f32_e32 v217, v225, v217
	v_mul_f32_e32 v218, v225, v218
	v_mul_f32_e32 v219, v225, v219
	v_fmac_f32_e32 v52, v100, v216
	v_fmac_f32_e32 v53, v101, v217
	v_fmac_f32_e32 v54, v102, v218
	v_fmac_f32_e32 v55, v103, v219
	global_store_dwordx4 v192, v[52:55], s[24:25] offset:1024
	v_lshlrev_b32_e32 v216, 16, v84
	v_and_b32_e32 v217, 0xffff0000, v84
	v_lshlrev_b32_e32 v218, 16, v85
	v_and_b32_e32 v219, 0xffff0000, v85
	v_mul_f32_e32 v216, v225, v216
	v_mul_f32_e32 v217, v225, v217
	v_mul_f32_e32 v218, v225, v218
	v_mul_f32_e32 v219, v225, v219
	v_fmac_f32_e32 v56, v104, v216
	v_fmac_f32_e32 v57, v105, v217
	v_fmac_f32_e32 v58, v106, v218
	v_fmac_f32_e32 v59, v107, v219
	global_store_dwordx4 v192, v[56:59], s[24:25] offset:2048
	v_lshlrev_b32_e32 v216, 16, v86
	v_and_b32_e32 v217, 0xffff0000, v86
	v_lshlrev_b32_e32 v218, 16, v87
	v_and_b32_e32 v219, 0xffff0000, v87
	v_mul_f32_e32 v216, v225, v216
	v_mul_f32_e32 v217, v225, v217
	v_mul_f32_e32 v218, v225, v218
	v_mul_f32_e32 v219, v225, v219
	v_fmac_f32_e32 v60, v108, v216
	v_fmac_f32_e32 v61, v109, v217
	v_fmac_f32_e32 v62, v110, v218
	v_fmac_f32_e32 v63, v111, v219
	global_store_dwordx4 v192, v[60:63], s[24:25] offset:3072
	v_lshlrev_b32_e32 v216, 16, v88
	v_and_b32_e32 v217, 0xffff0000, v88
	v_lshlrev_b32_e32 v218, 16, v89
	v_and_b32_e32 v219, 0xffff0000, v89
	v_mul_f32_e32 v216, v225, v216
	v_mul_f32_e32 v217, v225, v217
	v_mul_f32_e32 v218, v225, v218
	v_mul_f32_e32 v219, v225, v219
	v_fmac_f32_e32 v64, v112, v216
	v_fmac_f32_e32 v65, v113, v217
	v_fmac_f32_e32 v66, v114, v218
	v_fmac_f32_e32 v67, v115, v219
	global_store_dwordx4 v193, v[64:67], s[24:25] offset:0
	v_lshlrev_b32_e32 v216, 16, v90
	v_and_b32_e32 v217, 0xffff0000, v90
	v_lshlrev_b32_e32 v218, 16, v91
	v_and_b32_e32 v219, 0xffff0000, v91
	v_mul_f32_e32 v216, v225, v216
	v_mul_f32_e32 v217, v225, v217
	v_mul_f32_e32 v218, v225, v218
	v_mul_f32_e32 v219, v225, v219
	v_fmac_f32_e32 v68, v116, v216
	v_fmac_f32_e32 v69, v117, v217
	v_fmac_f32_e32 v70, v118, v218
	v_fmac_f32_e32 v71, v119, v219
	global_store_dwordx4 v193, v[68:71], s[24:25] offset:1024
	v_lshlrev_b32_e32 v216, 16, v92
	v_and_b32_e32 v217, 0xffff0000, v92
	v_lshlrev_b32_e32 v218, 16, v93
	v_and_b32_e32 v219, 0xffff0000, v93
	v_mul_f32_e32 v216, v225, v216
	v_mul_f32_e32 v217, v225, v217
	v_mul_f32_e32 v218, v225, v218
	v_mul_f32_e32 v219, v225, v219
	v_fmac_f32_e32 v72, v120, v216
	v_fmac_f32_e32 v73, v121, v217
	v_fmac_f32_e32 v74, v122, v218
	v_fmac_f32_e32 v75, v123, v219
	global_store_dwordx4 v193, v[72:75], s[24:25] offset:2048
	v_lshlrev_b32_e32 v216, 16, v94
	v_and_b32_e32 v217, 0xffff0000, v94
	v_lshlrev_b32_e32 v218, 16, v95
	v_and_b32_e32 v219, 0xffff0000, v95
	v_mul_f32_e32 v216, v225, v216
	v_mul_f32_e32 v217, v225, v217
	v_mul_f32_e32 v218, v225, v218
	v_mul_f32_e32 v219, v225, v219
	v_fmac_f32_e32 v76, v124, v216
	v_fmac_f32_e32 v77, v125, v217
	v_fmac_f32_e32 v78, v126, v218
	v_fmac_f32_e32 v79, v127, v219
	global_store_dwordx4 v193, v[76:79], s[24:25] offset:3072
	v_mul_f32_e32 v222, v48, v48
	v_mul_f32_e32 v223, v49, v49
	v_fmac_f32_e32 v222, v50, v50
	v_fmac_f32_e32 v223, v51, v51
	v_fmac_f32_e32 v222, v52, v52
	v_fmac_f32_e32 v223, v53, v53
	v_fmac_f32_e32 v222, v54, v54
	v_fmac_f32_e32 v223, v55, v55
	v_fmac_f32_e32 v222, v56, v56
	v_fmac_f32_e32 v223, v57, v57
	v_fmac_f32_e32 v222, v58, v58
	v_fmac_f32_e32 v223, v59, v59
	v_fmac_f32_e32 v222, v60, v60
	v_fmac_f32_e32 v223, v61, v61
	v_fmac_f32_e32 v222, v62, v62
	v_fmac_f32_e32 v223, v63, v63
	v_fmac_f32_e32 v222, v64, v64
	v_fmac_f32_e32 v223, v65, v65
	v_fmac_f32_e32 v222, v66, v66
	v_fmac_f32_e32 v223, v67, v67
	v_fmac_f32_e32 v222, v68, v68
	v_fmac_f32_e32 v223, v69, v69
	v_fmac_f32_e32 v222, v70, v70
	v_fmac_f32_e32 v223, v71, v71
	v_fmac_f32_e32 v222, v72, v72
	v_fmac_f32_e32 v223, v73, v73
	v_fmac_f32_e32 v222, v74, v74
	v_fmac_f32_e32 v223, v75, v75
	v_fmac_f32_e32 v222, v76, v76
	v_fmac_f32_e32 v223, v77, v77
	v_fmac_f32_e32 v222, v78, v78
	v_fmac_f32_e32 v223, v79, v79
	v_add_f32_e32 v222, v222, v223
	s_nop 1
	v_add_f32_dpp v224, v222, v222 quad_perm:[1,0,3,2] row_mask:0xf bank_mask:0xf
	s_nop 1
	v_add_f32_dpp v224, v224, v224 quad_perm:[2,3,0,1] row_mask:0xf bank_mask:0xf
	s_nop 1
	v_add_f32_dpp v224, v224, v224 row_half_mirror row_mask:0xf bank_mask:0xf
	s_nop 1
	v_add_f32_dpp v224, v224, v224 row_mirror row_mask:0xf bank_mask:0xf
	s_nop 1
	v_readlane_b32 s40, v224, 0
	v_readlane_b32 s41, v224, 16
	v_readlane_b32 s42, v224, 32
	v_readlane_b32 s43, v224, 48
	s_nop 1
	v_mov_b32_e32 v225, s40
	v_add_f32_e32 v225, s41, v225
	v_add_f32_e32 v225, s42, v225
	v_add_f32_e32 v225, s43, v225
	v_fmamk_f32 v225, v225, 0x3a000000, v195
	v_rsq_f32_e32 v225, v225
	s_nop 0
	s_add_i32 s0, s6, 3
	s_lshl_b32 s1, s0, 12
	s_add_u32 s26, s84, s1
	s_addc_u32 s27, s85, 0
	s_add_u32 s26, s26, 0x4000000
	s_addc_u32 s27, s27, 0
	v_mul_f32_e32 v216, v225, v48
	v_mul_f32_e32 v217, v225, v49
	v_mul_f32_e32 v218, v225, v50
	v_mul_f32_e32 v219, v225, v51
	v_fma_f32 v216, v216, v128, v160
	v_fma_f32 v217, v217, v129, v161
	v_fma_f32 v218, v218, v130, v162
	v_fma_f32 v219, v219, v131, v163
	v_cvt_pk_bf16_f32 v196, v216, v217
	v_cvt_pk_bf16_f32 v197, v218, v219
; __device__ __forceinline__ unsigned cvt_pk_bf16(float lo, float hi) { unsigned r; asm volatile("v_cvt_pk_bf16_f32 %0, %1, %2" : "=v"(r) : "v"(lo), "v"(hi)); return r; }
; __device__ __forceinline__ void modulate_store(const f32x4 (&v)[8], float rstd, const float* pn, const float* modr, bf16_t* orow, int lane) {
; #pragma unroll
;     for (int j = 0; j < 8; ++j) { const int col = 4 * lane + 256 * j;
;         const f32x4 g = *(const f32x4*)(pn + col), sh = *(const f32x4*)(modr + col), sc = *(const f32x4*)(modr + DM + col);
;         const f32x4 hh = v[j] * rstd * g * (sc + 1.f) + sh;
;         u32x2 w; w.x = cvt_pk_bf16(hh[0], hh[1]); w.y = cvt_pk_bf16(hh[2], hh[3]);
;         *(u32x2*)(orow + col) = w; }
; }
; __global__ void __launch_bounds__(NWAVES * 64, 2) mk_fwd(Args args) {
;     ...
;         for (int row0 = F.gw * 3; row0 < MT; row0 += F.NGW * 3) {
;             f32x4 v[3][8]; u32x2 yw[3][8];
; #pragma unroll
;             for (int q = 0; q < 3; ++q) { const int row = row0 + q; const float* src = row < ML ? x + (size_t)row * DM : ctx + (size_t)(row - ML) * DM; load_row_f32(src, F.lane, v[q]);
;                 const bf16_t* yr = Y + (size_t)row * DM;
; #pragma unroll
;                 for (int j = 0; j < 8; ++j) yw[q][j] = *(const u32x2*)(yr + 4 * F.lane + 256 * j); }
	global_store_dwordx2 v194, v[196:197], s[26:27] offset:0
	v_mul_f32_e32 v216, v225, v52
	v_mul_f32_e32 v217, v225, v53
	v_mul_f32_e32 v218, v225, v54
	v_mul_f32_e32 v219, v225, v55
	v_fma_f32 v216, v216, v132, v164
	v_fma_f32 v217, v217, v133, v165
	v_fma_f32 v218, v218, v134, v166
	v_fma_f32 v219, v219, v135, v167
	v_cvt_pk_bf16_f32 v220, v216, v217
	v_cvt_pk_bf16_f32 v221, v218, v219
	global_store_dwordx2 v194, v[220:221], s[26:27] offset:512
	v_mul_f32_e32 v216, v225, v56
	v_mul_f32_e32 v217, v225, v57
	v_mul_f32_e32 v218, v225, v58
	v_mul_f32_e32 v219, v225, v59
	v_fma_f32 v216, v216, v136, v168
	v_fma_f32 v217, v217, v137, v169
	v_fma_f32 v218, v218, v138, v170
	v_fma_f32 v219, v219, v139, v171
	v_cvt_pk_bf16_f32 v196, v216, v217
	v_cvt_pk_bf16_f32 v197, v218, v219
	global_store_dwordx2 v194, v[196:197], s[26:27] offset:1024
	v_mul_f32_e32 v216, v225, v60
	v_mul_f32_e32 v217, v225, v61
	v_mul_f32_e32 v218, v225, v62
	v_mul_f32_e32 v219, v225, v63
	v_fma_f32 v216, v216, v140, v172
	v_fma_f32 v217, v217, v141, v173
	v_fma_f32 v218, v218, v142, v174
	v_fma_f32 v219, v219, v143, v175
	v_cvt_pk_bf16_f32 v220, v216, v217
	v_cvt_pk_bf16_f32 v221, v218, v219
	global_store_dwordx2 v194, v[220:221], s[26:27] offset:1536
	v_mul_f32_e32 v216, v225, v64
	v_mul_f32_e32 v217, v225, v65
	v_mul_f32_e32 v218, v225, v66
	v_mul_f32_e32 v219, v225, v67
	v_fma_f32 v216, v216, v144, v176
	v_fma_f32 v217, v217, v145, v177
	v_fma_f32 v218, v218, v146, v178
	v_fma_f32 v219, v219, v147, v179
	v_cvt_pk_bf16_f32 v196, v216, v217
	v_cvt_pk_bf16_f32 v197, v218, v219
	global_store_dwordx2 v194, v[196:197], s[26:27] offset:2048
	v_mul_f32_e32 v216, v225, v68
	v_mul_f32_e32 v217, v225, v69
	v_mul_f32_e32 v218, v225, v70
	v_mul_f32_e32 v219, v225, v71
	v_fma_f32 v216, v216, v148, v180
	v_fma_f32 v217, v217, v149, v181
	v_fma_f32 v218, v218, v150, v182
	v_fma_f32 v219, v219, v151, v183
	v_cvt_pk_bf16_f32 v220, v216, v217
	v_cvt_pk_bf16_f32 v221, v218, v219
	global_store_dwordx2 v194, v[220:221], s[26:27] offset:2560
	v_mul_f32_e32 v216, v225, v72
	v_mul_f32_e32 v217, v225, v73
	v_mul_f32_e32 v218, v225, v74
	v_mul_f32_e32 v219, v225, v75
	v_fma_f32 v216, v216, v152, v184
	v_fma_f32 v217, v217, v153, v185
	v_fma_f32 v218, v218, v154, v186
	v_fma_f32 v219, v219, v155, v187
	v_cvt_pk_bf16_f32 v196, v216, v217
	v_cvt_pk_bf16_f32 v197, v218, v219
	global_store_dwordx2 v194, v[196:197], s[26:27] offset:3072
	v_mul_f32_e32 v216, v225, v76
	v_mul_f32_e32 v217, v225, v77
	v_mul_f32_e32 v218, v225, v78
	v_mul_f32_e32 v219, v225, v79
	v_fma_f32 v216, v216, v156, v188
	v_fma_f32 v217, v217, v157, v189
	v_fma_f32 v218, v218, v158, v190
	v_fma_f32 v219, v219, v159, v191
	v_cvt_pk_bf16_f32 v220, v216, v217
	v_cvt_pk_bf16_f32 v221, v218, v219
	global_store_dwordx2 v194, v[220:221], s[26:27] offset:3584
	s_add_i32 s0, s6, 5
	s_cmp_lt_u32 s0, 0x4000
	s_cselect_b32 s10, s68, s72
	s_cselect_b32 s11, s69, s73
	s_cselect_b32 s1, 0, 0x4000
	s_sub_i32 s1, s0, s1
	s_lshl_b32 s1, s1, 13
	s_add_u32 s10, s10, s1
	s_addc_u32 s11, s11, 0
	s_add_i32 s0, s6, 5
	s_lshl_b32 s1, s0, 12
	s_add_u32 s22, s84, s1
	s_addc_u32 s23, s85, 0
	s_add_u32 s22, s22, 0x11800000
	s_addc_u32 s23, s23, 0
	global_load_dwordx4 v[48:51], v192, s[10:11] offset:0 nt
	global_load_dwordx4 v[52:55], v192, s[10:11] offset:1024 nt
	global_load_dwordx4 v[56:59], v192, s[10:11] offset:2048 nt
	global_load_dwordx4 v[60:63], v192, s[10:11] offset:3072 nt
	global_load_dwordx4 v[64:67], v193, s[10:11] offset:0 nt
	global_load_dwordx4 v[68:71], v193, s[10:11] offset:1024 nt
	global_load_dwordx4 v[72:75], v193, s[10:11] offset:2048 nt
	global_load_dwordx4 v[76:79], v193, s[10:11] offset:3072 nt
	global_load_dwordx2 v[80:81], v194, s[22:23] offset:0 nt
	global_load_dwordx2 v[82:83], v194, s[22:23] offset:512 nt
	global_load_dwordx2 v[84:85], v194, s[22:23] offset:1024 nt
	global_load_dwordx2 v[86:87], v194, s[22:23] offset:1536 nt
	global_load_dwordx2 v[88:89], v194, s[22:23] offset:2048 nt
	global_load_dwordx2 v[90:91], v194, s[22:23] offset:2560 nt
	global_load_dwordx2 v[92:93], v194, s[22:23] offset:3072 nt
	global_load_dwordx2 v[94:95], v194, s[22:23] offset:3584 nt
	s_add_i32 s0, s6, 4
	s_add_i32 s0, s6, 4
	s_lshr_b32 s8, s0, 11
	s_cmp_lt_u32 s0, 0x4000
	s_cselect_b32 s8, s8, 8
	s_cmp_eq_u32 s8, s7
	s_cbranch_scc1 .Lp6_np4
; __device__ __forceinline__ float bf_lo(unsigned w) { return __uint_as_float(w << 16); }
; __device__ __forceinline__ float bf_hi(unsigned w) { return __uint_as_float(w & 0xffff0000u); }
; __device__ __forceinline__ void modulate_store(const f32x4 (&v)[8], float rstd, const float* pn, const float* modr, bf16_t* orow, int lane) {
; #pragma unroll
;     for (int j = 0; j < 8; ++j) { const int col = 4 * lane + 256 * j;
;         const f32x4 g = *(const f32x4*)(pn + col), sh = *(const f32x4*)(modr + col), sc = *(const f32x4*)(modr + DM + col);
;         const f32x4 hh = v[j] * rstd * g * (sc + 1.f) + sh;
; __global__ void __launch_bounds__(NWAVES * 64, 2) mk_fwd(Args args) {
;     ...
;                 const float* m0 = mod + (size_t)r * 6144;
; #pragma unroll
;                 for (int j = 0; j < 8; ++j) { const int col = 4 * F.lane + 256 * j; const f32x4 gt = *(const f32x4*)(m0 + 2 * DM + col), pn = *(const f32x4*)(post_norm + col);
;                     const f32x4 y4 = (f32x4){bf_lo(yw[q][j].x), bf_hi(yw[q][j].x), bf_lo(yw[q][j].y), bf_hi(yw[q][j].y)};
;                     v[q][j] = v[q][j] + gt * (y4 * rsy * pn);
	s_mov_b32 s7, s8
	s_add_i32 s1, s8, 9
	s_mul_i32 s1, s1, 0x6000
	s_add_u32 s44, s84, s1
	s_addc_u32 s45, s85, 0
	s_add_u32 s44, s44, 0x2000
	s_addc_u32 s45, s45, 0
	s_add_i32 s1, s8, 9
	s_mul_i32 s1, s1, 0x6000
	s_add_u32 s36, s84, s1
	s_addc_u32 s37, s85, 0
	s_add_u32 s38, s80, 0x2000
	s_addc_u32 s39, s81, 0
	s_mul_i32 s1, s8, 0x6000
	s_add_u32 s34, s84, s1
	s_addc_u32 s35, s85, 0
	s_add_u32 s34, s34, 0x4000
	s_addc_u32 s35, s35, 0
	global_load_dwordx4 v[96:99], v192, s[34:35] offset:0
	global_load_dwordx4 v[200:203], v192, s[82:83] offset:0
	global_load_dwordx4 v[100:103], v192, s[34:35] offset:1024
	global_load_dwordx4 v[204:207], v192, s[82:83] offset:1024
	global_load_dwordx4 v[104:107], v192, s[34:35] offset:2048
	global_load_dwordx4 v[208:211], v192, s[82:83] offset:2048
	global_load_dwordx4 v[108:111], v192, s[34:35] offset:3072
	global_load_dwordx4 v[212:215], v192, s[82:83] offset:3072
	s_waitcnt vmcnt(0)
	v_mul_f32_e32 v96, v96, v200
	v_mul_f32_e32 v97, v97, v201
	v_mul_f32_e32 v98, v98, v202
	v_mul_f32_e32 v99, v99, v203
	v_mul_f32_e32 v100, v100, v204
	v_mul_f32_e32 v101, v101, v205
	v_mul_f32_e32 v102, v102, v206
	v_mul_f32_e32 v103, v103, v207
	v_mul_f32_e32 v104, v104, v208
	v_mul_f32_e32 v105, v105, v209
	v_mul_f32_e32 v106, v106, v210
	v_mul_f32_e32 v107, v107, v211
	v_mul_f32_e32 v108, v108, v212
	v_mul_f32_e32 v109, v109, v213
	v_mul_f32_e32 v110, v110, v214
	v_mul_f32_e32 v111, v111, v215
	global_load_dwordx4 v[128:131], v192, s[38:39] offset:0
	global_load_dwordx4 v[200:203], v192, s[44:45] offset:0
	global_load_dwordx4 v[160:163], v192, s[36:37] offset:0
	global_load_dwordx4 v[132:135], v192, s[38:39] offset:1024
	global_load_dwordx4 v[204:207], v192, s[44:45] offset:1024
	global_load_dwordx4 v[164:167], v192, s[36:37] offset:1024
	global_load_dwordx4 v[136:139], v192, s[38:39] offset:2048
	global_load_dwordx4 v[208:211], v192, s[44:45] offset:2048
	global_load_dwordx4 v[168:171], v192, s[36:37] offset:2048
	global_load_dwordx4 v[140:143], v192, s[38:39] offset:3072
	global_load_dwordx4 v[212:215], v192, s[44:45] offset:3072
	global_load_dwordx4 v[172:175], v192, s[36:37] offset:3072
	s_waitcnt vmcnt(0)
	v_add_f32_e32 v200, 1.0, v200
	v_add_f32_e32 v201, 1.0, v201
	v_add_f32_e32 v202, 1.0, v202
	v_add_f32_e32 v203, 1.0, v203
	v_mul_f32_e32 v128, v128, v200
	v_mul_f32_e32 v129, v129, v201
	v_mul_f32_e32 v130, v130, v202
	v_mul_f32_e32 v131, v131, v203
	v_add_f32_e32 v204, 1.0, v204
	v_add_f32_e32 v205, 1.0, v205
	v_add_f32_e32 v206, 1.0, v206
	v_add_f32_e32 v207, 1.0, v207
	v_mul_f32_e32 v132, v132, v204
	v_mul_f32_e32 v133, v133, v205
	v_mul_f32_e32 v134, v134, v206
	v_mul_f32_e32 v135, v135, v207
	v_add_f32_e32 v208, 1.0, v208
	v_add_f32_e32 v209, 1.0, v209
	v_add_f32_e32 v210, 1.0, v210
	v_add_f32_e32 v211, 1.0, v211
	v_mul_f32_e32 v136, v136, v208
	v_mul_f32_e32 v137, v137, v209
	v_mul_f32_e32 v138, v138, v210
	v_mul_f32_e32 v139, v139, v211
	v_add_f32_e32 v212, 1.0, v212
	v_add_f32_e32 v213, 1.0, v213
	v_add_f32_e32 v214, 1.0, v214
	v_add_f32_e32 v215, 1.0, v215
	v_mul_f32_e32 v140, v140, v212
	v_mul_f32_e32 v141, v141, v213
	v_mul_f32_e32 v142, v142, v214
	v_mul_f32_e32 v143, v143, v215
	global_load_dwordx4 v[112:115], v193, s[34:35] offset:0
	global_load_dwordx4 v[200:203], v193, s[82:83] offset:0
	global_load_dwordx4 v[116:119], v193, s[34:35] offset:1024
	global_load_dwordx4 v[204:207], v193, s[82:83] offset:1024
	global_load_dwordx4 v[120:123], v193, s[34:35] offset:2048
	global_load_dwordx4 v[208:211], v193, s[82:83] offset:2048
	global_load_dwordx4 v[124:127], v193, s[34:35] offset:3072
	global_load_dwordx4 v[212:215], v193, s[82:83] offset:3072
	s_waitcnt vmcnt(0)
	v_mul_f32_e32 v112, v112, v200
	v_mul_f32_e32 v113, v113, v201
	v_mul_f32_e32 v114, v114, v202
	v_mul_f32_e32 v115, v115, v203
	v_mul_f32_e32 v116, v116, v204
	v_mul_f32_e32 v117, v117, v205
	v_mul_f32_e32 v118, v118, v206
	v_mul_f32_e32 v119, v119, v207
	v_mul_f32_e32 v120, v120, v208
	v_mul_f32_e32 v121, v121, v209
	v_mul_f32_e32 v122, v122, v210
	v_mul_f32_e32 v123, v123, v211
	v_mul_f32_e32 v124, v124, v212
	v_mul_f32_e32 v125, v125, v213
	v_mul_f32_e32 v126, v126, v214
	v_mul_f32_e32 v127, v127, v215
	global_load_dwordx4 v[144:147], v193, s[38:39] offset:0
	global_load_dwordx4 v[200:203], v193, s[44:45] offset:0
	global_load_dwordx4 v[176:179], v193, s[36:37] offset:0
	global_load_dwordx4 v[148:151], v193, s[38:39] offset:1024
	global_load_dwordx4 v[204:207], v193, s[44:45] offset:1024
	global_load_dwordx4 v[180:183], v193, s[36:37] offset:1024
	global_load_dwordx4 v[152:155], v193, s[38:39] offset:2048
	global_load_dwordx4 v[208:211], v193, s[44:45] offset:2048
	global_load_dwordx4 v[184:187], v193, s[36:37] offset:2048
	global_load_dwordx4 v[156:159], v193, s[38:39] offset:3072
	global_load_dwordx4 v[212:215], v193, s[44:45] offset:3072
	global_load_dwordx4 v[188:191], v193, s[36:37] offset:3072
	s_waitcnt vmcnt(0)
	v_add_f32_e32 v200, 1.0, v200
	v_add_f32_e32 v201, 1.0, v201
	v_add_f32_e32 v202, 1.0, v202
	v_add_f32_e32 v203, 1.0, v203
	v_mul_f32_e32 v144, v144, v200
	v_mul_f32_e32 v145, v145, v201
	v_mul_f32_e32 v146, v146, v202
	v_mul_f32_e32 v147, v147, v203
	v_add_f32_e32 v204, 1.0, v204
	v_add_f32_e32 v205, 1.0, v205
	v_add_f32_e32 v206, 1.0, v206
	v_add_f32_e32 v207, 1.0, v207
	v_mul_f32_e32 v148, v148, v204
	v_mul_f32_e32 v149, v149, v205
	v_mul_f32_e32 v150, v150, v206
	v_mul_f32_e32 v151, v151, v207
	v_add_f32_e32 v208, 1.0, v208
	v_add_f32_e32 v209, 1.0, v209
	v_add_f32_e32 v210, 1.0, v210
	v_add_f32_e32 v211, 1.0, v211
	v_mul_f32_e32 v152, v152, v208
	v_mul_f32_e32 v153, v153, v209
	v_mul_f32_e32 v154, v154, v210
	v_mul_f32_e32 v155, v155, v211
	v_add_f32_e32 v212, 1.0, v212
	v_add_f32_e32 v213, 1.0, v213
	v_add_f32_e32 v214, 1.0, v214
	v_add_f32_e32 v215, 1.0, v215
	v_mul_f32_e32 v156, v156, v212
	v_mul_f32_e32 v157, v157, v213
	v_mul_f32_e32 v158, v158, v214
	v_mul_f32_e32 v159, v159, v215
; __device__ __forceinline__ float bf_lo(unsigned w) { return __uint_as_float(w << 16); }
; __device__ __forceinline__ float bf_hi(unsigned w) { return __uint_as_float(w & 0xffff0000u); }
; __global__ void __launch_bounds__(NWAVES * 64, 2) mk_fwd(Args args) {
;     ...
;             for (int q = 0; q < 3; ++q) { const int row = row0 + q; const bool lat = row < ML; const int r = lat ? row / SEQ : 8;
;                 float sy = 0.f;
; #pragma unroll
;                 for (int j = 0; j < 8; ++j) { const float a = bf_lo(yw[q][j].x), b = bf_hi(yw[q][j].x), c2 = bf_lo(yw[q][j].y), d = bf_hi(yw[q][j].y); sy += (a * a + b * b) + (c2 * c2 + d * d); }
;                 const float rsy = __builtin_amdgcn_rsqf(wave_sum(sy) * (1.f / DM) + EPS);
;                 const float* m0 = mod + (size_t)r * 6144;
; #pragma unroll
;                 for (int j = 0; j < 8; ++j) { const int col = 4 * F.lane + 256 * j; const f32x4 gt = *(const f32x4*)(m0 + 2 * DM + col), pn = *(const f32x4*)(post_norm + col);
;                     const f32x4 y4 = (f32x4){bf_lo(yw[q][j].x), bf_hi(yw[q][j].x), bf_lo(yw[q][j].y), bf_hi(yw[q][j].y)};
;                     v[q][j] = v[q][j] + gt * (y4 * rsy * pn);
;                     if (lat) *(f32x4*)(args.out + (size_t)row * DM + col) = v[q][j]; }
.Lp6_np4:
	s_waitcnt vmcnt(32)
	v_lshlrev_b32_e32 v216, 16, v32
	v_and_b32_e32 v217, 0xffff0000, v32
	v_lshlrev_b32_e32 v218, 16, v33
	v_and_b32_e32 v219, 0xffff0000, v33
	v_mul_f32_e32 v222, v216, v216
	v_mul_f32_e32 v223, v217, v217
	v_fmac_f32_e32 v222, v218, v218
	v_fmac_f32_e32 v223, v219, v219
	v_lshlrev_b32_e32 v216, 16, v34
	v_and_b32_e32 v217, 0xffff0000, v34
	v_lshlrev_b32_e32 v218, 16, v35
	v_and_b32_e32 v219, 0xffff0000, v35
	v_fmac_f32_e32 v222, v216, v216
	v_fmac_f32_e32 v223, v217, v217
	v_fmac_f32_e32 v222, v218, v218
	v_fmac_f32_e32 v223, v219, v219
	v_lshlrev_b32_e32 v216, 16, v36
	v_and_b32_e32 v217, 0xffff0000, v36
	v_lshlrev_b32_e32 v218, 16, v37
	v_and_b32_e32 v219, 0xffff0000, v37
	v_fmac_f32_e32 v222, v216, v216
	v_fmac_f32_e32 v223, v217, v217
	v_fmac_f32_e32 v222, v218, v218
	v_fmac_f32_e32 v223, v219, v219
	v_lshlrev_b32_e32 v216, 16, v38
	v_and_b32_e32 v217, 0xffff0000, v38
	v_lshlrev_b32_e32 v218, 16, v39
	v_and_b32_e32 v219, 0xffff0000, v39
	v_fmac_f32_e32 v222, v216, v216
	v_fmac_f32_e32 v223, v217, v217
	v_fmac_f32_e32 v222, v218, v218
	v_fmac_f32_e32 v223, v219, v219
	v_lshlrev_b32_e32 v216, 16, v40
	v_and_b32_e32 v217, 0xffff0000, v40
	v_lshlrev_b32_e32 v218, 16, v41
	v_and_b32_e32 v219, 0xffff0000, v41
	v_fmac_f32_e32 v222, v216, v216
	v_fmac_f32_e32 v223, v217, v217
	v_fmac_f32_e32 v222, v218, v218
	v_fmac_f32_e32 v223, v219, v219
	v_lshlrev_b32_e32 v216, 16, v42
	v_and_b32_e32 v217, 0xffff0000, v42
	v_lshlrev_b32_e32 v218, 16, v43
	v_and_b32_e32 v219, 0xffff0000, v43
	v_fmac_f32_e32 v222, v216, v216
	v_fmac_f32_e32 v223, v217, v217
	v_fmac_f32_e32 v222, v218, v218
	v_fmac_f32_e32 v223, v219, v219
	v_lshlrev_b32_e32 v216, 16, v44
	v_and_b32_e32 v217, 0xffff0000, v44
	v_lshlrev_b32_e32 v218, 16, v45
	v_and_b32_e32 v219, 0xffff0000, v45
	v_fmac_f32_e32 v222, v216, v216
	v_fmac_f32_e32 v223, v217, v217
	v_fmac_f32_e32 v222, v218, v218
	v_fmac_f32_e32 v223, v219, v219
	v_lshlrev_b32_e32 v216, 16, v46
	v_and_b32_e32 v217, 0xffff0000, v46
	v_lshlrev_b32_e32 v218, 16, v47
	v_and_b32_e32 v219, 0xffff0000, v47
	v_fmac_f32_e32 v222, v216, v216
	v_fmac_f32_e32 v223, v217, v217
	v_fmac_f32_e32 v222, v218, v218
	v_fmac_f32_e32 v223, v219, v219
	v_add_f32_e32 v222, v222, v223
	s_nop 1
	v_add_f32_dpp v224, v222, v222 quad_perm:[1,0,3,2] row_mask:0xf bank_mask:0xf
	s_nop 1
	v_add_f32_dpp v224, v224, v224 quad_perm:[2,3,0,1] row_mask:0xf bank_mask:0xf
	s_nop 1
	v_add_f32_dpp v224, v224, v224 row_half_mirror row_mask:0xf bank_mask:0xf
	s_nop 1
	v_add_f32_dpp v224, v224, v224 row_mirror row_mask:0xf bank_mask:0xf
	s_nop 1
	v_readlane_b32 s40, v224, 0
	v_readlane_b32 s41, v224, 16
	v_readlane_b32 s42, v224, 32
	v_readlane_b32 s43, v224, 48
	s_nop 1
	v_mov_b32_e32 v225, s40
	v_add_f32_e32 v225, s41, v225
	v_add_f32_e32 v225, s42, v225
	v_add_f32_e32 v225, s43, v225
	v_fmamk_f32 v225, v225, 0x3a000000, v195
	v_rsq_f32_e32 v225, v225
	s_nop 0
	s_add_i32 s0, s6, 4
	s_cmp_lt_u32 s0, 0x4000
	s_cselect_b32 s24, s94, s84
	s_cselect_b32 s25, s95, s85
	s_cselect_b32 s44, 0, 0x16000000
	s_cselect_b32 s1, 0, 0x4000
	s_sub_i32 s1, s0, s1
	s_lshl_b32 s1, s1, 13
	s_add_u32 s24, s24, s1
	s_addc_u32 s25, s25, 0
	s_add_u32 s24, s24, s44
	s_addc_u32 s25, s25, 0
	v_lshlrev_b32_e32 v216, 16, v32
	v_and_b32_e32 v217, 0xffff0000, v32
	v_lshlrev_b32_e32 v218, 16, v33
	v_and_b32_e32 v219, 0xffff0000, v33
	v_mul_f32_e32 v216, v225, v216
	v_mul_f32_e32 v217, v225, v217
	v_mul_f32_e32 v218, v225, v218
	v_mul_f32_e32 v219, v225, v219
	v_fmac_f32_e32 v0, v96, v216
	v_fmac_f32_e32 v1, v97, v217
	v_fmac_f32_e32 v2, v98, v218
	v_fmac_f32_e32 v3, v99, v219
	global_store_dwordx4 v192, v[0:3], s[24:25] offset:0
	v_lshlrev_b32_e32 v216, 16, v34
	v_and_b32_e32 v217, 0xffff0000, v34
	v_lshlrev_b32_e32 v218, 16, v35
	v_and_b32_e32 v219, 0xffff0000, v35
	v_mul_f32_e32 v216, v225, v216
	v_mul_f32_e32 v217, v225, v217
	v_mul_f32_e32 v218, v225, v218
	v_mul_f32_e32 v219, v225, v219
	v_fmac_f32_e32 v4, v100, v216
	v_fmac_f32_e32 v5, v101, v217
	v_fmac_f32_e32 v6, v102, v218
	v_fmac_f32_e32 v7, v103, v219
	global_store_dwordx4 v192, v[4:7], s[24:25] offset:1024
	v_lshlrev_b32_e32 v216, 16, v36
	v_and_b32_e32 v217, 0xffff0000, v36
	v_lshlrev_b32_e32 v218, 16, v37
	v_and_b32_e32 v219, 0xffff0000, v37
	v_mul_f32_e32 v216, v225, v216
	v_mul_f32_e32 v217, v225, v217
	v_mul_f32_e32 v218, v225, v218
	v_mul_f32_e32 v219, v225, v219
	v_fmac_f32_e32 v8, v104, v216
	v_fmac_f32_e32 v9, v105, v217
	v_fmac_f32_e32 v10, v106, v218
	v_fmac_f32_e32 v11, v107, v219
	global_store_dwordx4 v192, v[8:11], s[24:25] offset:2048
	v_lshlrev_b32_e32 v216, 16, v38
	v_and_b32_e32 v217, 0xffff0000, v38
	v_lshlrev_b32_e32 v218, 16, v39
	v_and_b32_e32 v219, 0xffff0000, v39
	v_mul_f32_e32 v216, v225, v216
	v_mul_f32_e32 v217, v225, v217
	v_mul_f32_e32 v218, v225, v218
	v_mul_f32_e32 v219, v225, v219
	v_fmac_f32_e32 v12, v108, v216
	v_fmac_f32_e32 v13, v109, v217
	v_fmac_f32_e32 v14, v110, v218
	v_fmac_f32_e32 v15, v111, v219
	global_store_dwordx4 v192, v[12:15], s[24:25] offset:3072
	v_lshlrev_b32_e32 v216, 16, v40
	v_and_b32_e32 v217, 0xffff0000, v40
	v_lshlrev_b32_e32 v218, 16, v41
	v_and_b32_e32 v219, 0xffff0000, v41
	v_mul_f32_e32 v216, v225, v216
	v_mul_f32_e32 v217, v225, v217
	v_mul_f32_e32 v218, v225, v218
	v_mul_f32_e32 v219, v225, v219
	v_fmac_f32_e32 v16, v112, v216
	v_fmac_f32_e32 v17, v113, v217
	v_fmac_f32_e32 v18, v114, v218
	v_fmac_f32_e32 v19, v115, v219
	global_store_dwordx4 v193, v[16:19], s[24:25] offset:0
	v_lshlrev_b32_e32 v216, 16, v42
	v_and_b32_e32 v217, 0xffff0000, v42
	v_lshlrev_b32_e32 v218, 16, v43
	v_and_b32_e32 v219, 0xffff0000, v43
	v_mul_f32_e32 v216, v225, v216
; __device__ __forceinline__ float bf_lo(unsigned w) { return __uint_as_float(w << 16); }
; __device__ __forceinline__ float bf_hi(unsigned w) { return __uint_as_float(w & 0xffff0000u); }
; __global__ void __launch_bounds__(NWAVES * 64, 2) mk_fwd(Args args) {
;     ...
;             for (int q = 0; q < 3; ++q) { const int row = row0 + q; const bool lat = row < ML; const int r = lat ? row / SEQ : 8;
;                 float sy = 0.f;
; #pragma unroll
;                 for (int j = 0; j < 8; ++j) { const float a = bf_lo(yw[q][j].x), b = bf_hi(yw[q][j].x), c2 = bf_lo(yw[q][j].y), d = bf_hi(yw[q][j].y); sy += (a * a + b * b) + (c2 * c2 + d * d); }
;                 const float rsy = __builtin_amdgcn_rsqf(wave_sum(sy) * (1.f / DM) + EPS);
;                 const float* m0 = mod + (size_t)r * 6144;
; #pragma unroll
;                 for (int j = 0; j < 8; ++j) { const int col = 4 * F.lane + 256 * j; const f32x4 gt = *(const f32x4*)(m0 + 2 * DM + col), pn = *(const f32x4*)(post_norm + col);
;                     const f32x4 y4 = (f32x4){bf_lo(yw[q][j].x), bf_hi(yw[q][j].x), bf_lo(yw[q][j].y), bf_hi(yw[q][j].y)};
;                     v[q][j] = v[q][j] + gt * (y4 * rsy * pn);
;                     if (lat) *(f32x4*)(args.out + (size_t)row * DM + col) = v[q][j]; }
;                 const float rstd = __builtin_amdgcn_rsqf(sumsq8(v[q]) * (1.f / DM) + EPS);
;                 modulate_store(v[q], rstd, pre_norm + DM, mod + (size_t)(9 + r) * 6144, H + (size_t)row * DM, F.lane); }
	v_mul_f32_e32 v217, v225, v217
	v_mul_f32_e32 v218, v225, v218
	v_mul_f32_e32 v219, v225, v219
	v_fmac_f32_e32 v20, v116, v216
	v_fmac_f32_e32 v21, v117, v217
	v_fmac_f32_e32 v22, v118, v218
	v_fmac_f32_e32 v23, v119, v219
	global_store_dwordx4 v193, v[20:23], s[24:25] offset:1024
	v_lshlrev_b32_e32 v216, 16, v44
	v_and_b32_e32 v217, 0xffff0000, v44
	v_lshlrev_b32_e32 v218, 16, v45
	v_and_b32_e32 v219, 0xffff0000, v45
	v_mul_f32_e32 v216, v225, v216
	v_mul_f32_e32 v217, v225, v217
	v_mul_f32_e32 v218, v225, v218
	v_mul_f32_e32 v219, v225, v219
	v_fmac_f32_e32 v24, v120, v216
	v_fmac_f32_e32 v25, v121, v217
	v_fmac_f32_e32 v26, v122, v218
	v_fmac_f32_e32 v27, v123, v219
	global_store_dwordx4 v193, v[24:27], s[24:25] offset:2048
	v_lshlrev_b32_e32 v216, 16, v46
	v_and_b32_e32 v217, 0xffff0000, v46
	v_lshlrev_b32_e32 v218, 16, v47
	v_and_b32_e32 v219, 0xffff0000, v47
	v_mul_f32_e32 v216, v225, v216
	v_mul_f32_e32 v217, v225, v217
	v_mul_f32_e32 v218, v225, v218
	v_mul_f32_e32 v219, v225, v219
	v_fmac_f32_e32 v28, v124, v216
	v_fmac_f32_e32 v29, v125, v217
	v_fmac_f32_e32 v30, v126, v218
	v_fmac_f32_e32 v31, v127, v219
	global_store_dwordx4 v193, v[28:31], s[24:25] offset:3072
	v_mul_f32_e32 v222, v0, v0
	v_mul_f32_e32 v223, v1, v1
	v_fmac_f32_e32 v222, v2, v2
	v_fmac_f32_e32 v223, v3, v3
	v_fmac_f32_e32 v222, v4, v4
	v_fmac_f32_e32 v223, v5, v5
	v_fmac_f32_e32 v222, v6, v6
	v_fmac_f32_e32 v223, v7, v7
	v_fmac_f32_e32 v222, v8, v8
	v_fmac_f32_e32 v223, v9, v9
	v_fmac_f32_e32 v222, v10, v10
	v_fmac_f32_e32 v223, v11, v11
	v_fmac_f32_e32 v222, v12, v12
	v_fmac_f32_e32 v223, v13, v13
	v_fmac_f32_e32 v222, v14, v14
	v_fmac_f32_e32 v223, v15, v15
	v_fmac_f32_e32 v222, v16, v16
	v_fmac_f32_e32 v223, v17, v17
	v_fmac_f32_e32 v222, v18, v18
	v_fmac_f32_e32 v223, v19, v19
	v_fmac_f32_e32 v222, v20, v20
	v_fmac_f32_e32 v223, v21, v21
	v_fmac_f32_e32 v222, v22, v22
	v_fmac_f32_e32 v223, v23, v23
	v_fmac_f32_e32 v222, v24, v24
	v_fmac_f32_e32 v223, v25, v25
	v_fmac_f32_e32 v222, v26, v26
	v_fmac_f32_e32 v223, v27, v27
	v_fmac_f32_e32 v222, v28, v28
	v_fmac_f32_e32 v223, v29, v29
	v_fmac_f32_e32 v222, v30, v30
	v_fmac_f32_e32 v223, v31, v31
	v_add_f32_e32 v222, v222, v223
	s_nop 1
	v_add_f32_dpp v224, v222, v222 quad_perm:[1,0,3,2] row_mask:0xf bank_mask:0xf
	s_nop 1
	v_add_f32_dpp v224, v224, v224 quad_perm:[2,3,0,1] row_mask:0xf bank_mask:0xf
	s_nop 1
	v_add_f32_dpp v224, v224, v224 row_half_mirror row_mask:0xf bank_mask:0xf
	s_nop 1
	v_add_f32_dpp v224, v224, v224 row_mirror row_mask:0xf bank_mask:0xf
	s_nop 1
	v_readlane_b32 s40, v224, 0
	v_readlane_b32 s41, v224, 16
	v_readlane_b32 s42, v224, 32
	v_readlane_b32 s43, v224, 48
	s_nop 1
	v_mov_b32_e32 v225, s40
	v_add_f32_e32 v225, s41, v225
	v_add_f32_e32 v225, s42, v225
	v_add_f32_e32 v225, s43, v225
	v_fmamk_f32 v225, v225, 0x3a000000, v195
	v_rsq_f32_e32 v225, v225
	s_nop 0
	s_add_i32 s0, s6, 4
	s_lshl_b32 s1, s0, 12
	s_add_u32 s26, s84, s1
	s_addc_u32 s27, s85, 0
	s_add_u32 s26, s26, 0x4000000
	s_addc_u32 s27, s27, 0
	v_mul_f32_e32 v216, v225, v0
	v_mul_f32_e32 v217, v225, v1
	v_mul_f32_e32 v218, v225, v2
	v_mul_f32_e32 v219, v225, v3
	v_fma_f32 v216, v216, v128, v160
	v_fma_f32 v217, v217, v129, v161
	v_fma_f32 v218, v218, v130, v162
	v_fma_f32 v219, v219, v131, v163
	v_cvt_pk_bf16_f32 v196, v216, v217
	v_cvt_pk_bf16_f32 v197, v218, v219
	global_store_dwordx2 v194, v[196:197], s[26:27] offset:0
	v_mul_f32_e32 v216, v225, v4
	v_mul_f32_e32 v217, v225, v5
	v_mul_f32_e32 v218, v225, v6
	v_mul_f32_e32 v219, v225, v7
	v_fma_f32 v216, v216, v132, v164
	v_fma_f32 v217, v217, v133, v165
	v_fma_f32 v218, v218, v134, v166
	v_fma_f32 v219, v219, v135, v167
	v_cvt_pk_bf16_f32 v220, v216, v217
	v_cvt_pk_bf16_f32 v221, v218, v219
	global_store_dwordx2 v194, v[220:221], s[26:27] offset:512
	v_mul_f32_e32 v216, v225, v8
	v_mul_f32_e32 v217, v225, v9
	v_mul_f32_e32 v218, v225, v10
	v_mul_f32_e32 v219, v225, v11
	v_fma_f32 v216, v216, v136, v168
	v_fma_f32 v217, v217, v137, v169
	v_fma_f32 v218, v218, v138, v170
	v_fma_f32 v219, v219, v139, v171
	v_cvt_pk_bf16_f32 v196, v216, v217
	v_cvt_pk_bf16_f32 v197, v218, v219
	global_store_dwordx2 v194, v[196:197], s[26:27] offset:1024
	v_mul_f32_e32 v216, v225, v12
	v_mul_f32_e32 v217, v225, v13
	v_mul_f32_e32 v218, v225, v14
	v_mul_f32_e32 v219, v225, v15
	v_fma_f32 v216, v216, v140, v172
	v_fma_f32 v217, v217, v141, v173
	v_fma_f32 v218, v218, v142, v174
	v_fma_f32 v219, v219, v143, v175
	v_cvt_pk_bf16_f32 v220, v216, v217
	v_cvt_pk_bf16_f32 v221, v218, v219
	global_store_dwordx2 v194, v[220:221], s[26:27] offset:1536
	v_mul_f32_e32 v216, v225, v16
	v_mul_f32_e32 v217, v225, v17
	v_mul_f32_e32 v218, v225, v18
	v_mul_f32_e32 v219, v225, v19
	v_fma_f32 v216, v216, v144, v176
	v_fma_f32 v217, v217, v145, v177
	v_fma_f32 v218, v218, v146, v178
	v_fma_f32 v219, v219, v147, v179
	v_cvt_pk_bf16_f32 v196, v216, v217
	v_cvt_pk_bf16_f32 v197, v218, v219
	global_store_dwordx2 v194, v[196:197], s[26:27] offset:2048
	v_mul_f32_e32 v216, v225, v20
	v_mul_f32_e32 v217, v225, v21
	v_mul_f32_e32 v218, v225, v22
	v_mul_f32_e32 v219, v225, v23
	v_fma_f32 v216, v216, v148, v180
	v_fma_f32 v217, v217, v149, v181
	v_fma_f32 v218, v218, v150, v182
	v_fma_f32 v219, v219, v151, v183
	v_cvt_pk_bf16_f32 v220, v216, v217
	v_cvt_pk_bf16_f32 v221, v218, v219
	global_store_dwordx2 v194, v[220:221], s[26:27] offset:2560
	v_mul_f32_e32 v216, v225, v24
	v_mul_f32_e32 v217, v225, v25
	v_mul_f32_e32 v218, v225, v26
	v_mul_f32_e32 v219, v225, v27
	v_fma_f32 v216, v216, v152, v184
	v_fma_f32 v217, v217, v153, v185
	v_fma_f32 v218, v218, v154, v186
	v_fma_f32 v219, v219, v155, v187
	v_cvt_pk_bf16_f32 v196, v216, v217
; __device__ __forceinline__ unsigned cvt_pk_bf16(float lo, float hi) { unsigned r; asm volatile("v_cvt_pk_bf16_f32 %0, %1, %2" : "=v"(r) : "v"(lo), "v"(hi)); return r; }
; __device__ __forceinline__ float bf_lo(unsigned w) { return __uint_as_float(w << 16); }
; __device__ __forceinline__ float bf_hi(unsigned w) { return __uint_as_float(w & 0xffff0000u); }
; __device__ __forceinline__ void modulate_store(const f32x4 (&v)[8], float rstd, const float* pn, const float* modr, bf16_t* orow, int lane) {
; #pragma unroll
;     for (int j = 0; j < 8; ++j) { const int col = 4 * lane + 256 * j;
;         const f32x4 g = *(const f32x4*)(pn + col), sh = *(const f32x4*)(modr + col), sc = *(const f32x4*)(modr + DM + col);
;         const f32x4 hh = v[j] * rstd * g * (sc + 1.f) + sh;
;         u32x2 w; w.x = cvt_pk_bf16(hh[0], hh[1]); w.y = cvt_pk_bf16(hh[2], hh[3]);
;         *(u32x2*)(orow + col) = w; }
; }
; __global__ void __launch_bounds__(NWAVES * 64, 2) mk_fwd(Args args) {
;     ...
;         for (int row0 = F.gw * 3; row0 < MT; row0 += F.NGW * 3) {
;             f32x4 v[3][8]; u32x2 yw[3][8];
; #pragma unroll
;             for (int q = 0; q < 3; ++q) { const int row = row0 + q; const float* src = row < ML ? x + (size_t)row * DM : ctx + (size_t)(row - ML) * DM; load_row_f32(src, F.lane, v[q]);
;                 const bf16_t* yr = Y + (size_t)row * DM;
; #pragma unroll
;                 for (int j = 0; j < 8; ++j) yw[q][j] = *(const u32x2*)(yr + 4 * F.lane + 256 * j); }
;     ...
;                 const float* m0 = mod + (size_t)r * 6144;
; #pragma unroll
;                 for (int j = 0; j < 8; ++j) { const int col = 4 * F.lane + 256 * j; const f32x4 gt = *(const f32x4*)(m0 + 2 * DM + col), pn = *(const f32x4*)(post_norm + col);
;                     const f32x4 y4 = (f32x4){bf_lo(yw[q][j].x), bf_hi(yw[q][j].x), bf_lo(yw[q][j].y), bf_hi(yw[q][j].y)};
;                     v[q][j] = v[q][j] + gt * (y4 * rsy * pn);
	v_cvt_pk_bf16_f32 v197, v218, v219
	global_store_dwordx2 v194, v[196:197], s[26:27] offset:3072
	v_mul_f32_e32 v216, v225, v28
	v_mul_f32_e32 v217, v225, v29
	v_mul_f32_e32 v218, v225, v30
	v_mul_f32_e32 v219, v225, v31
	v_fma_f32 v216, v216, v156, v188
	v_fma_f32 v217, v217, v157, v189
	v_fma_f32 v218, v218, v158, v190
	v_fma_f32 v219, v219, v159, v191
	v_cvt_pk_bf16_f32 v220, v216, v217
	v_cvt_pk_bf16_f32 v221, v218, v219
	global_store_dwordx2 v194, v[220:221], s[26:27] offset:3584
	s_add_i32 s0, s6, 6
	s_cmp_lt_u32 s0, 0x4000
	s_cselect_b32 s10, s68, s72
	s_cselect_b32 s11, s69, s73
	s_cselect_b32 s1, 0, 0x4000
	s_sub_i32 s1, s0, s1
	s_lshl_b32 s1, s1, 13
	s_add_u32 s10, s10, s1
	s_addc_u32 s11, s11, 0
	s_add_i32 s0, s6, 6
	s_lshl_b32 s1, s0, 12
	s_add_u32 s22, s84, s1
	s_addc_u32 s23, s85, 0
	s_add_u32 s22, s22, 0x11800000
	s_addc_u32 s23, s23, 0
	global_load_dwordx4 v[0:3], v192, s[10:11] offset:0 nt
	global_load_dwordx4 v[4:7], v192, s[10:11] offset:1024 nt
	global_load_dwordx4 v[8:11], v192, s[10:11] offset:2048 nt
	global_load_dwordx4 v[12:15], v192, s[10:11] offset:3072 nt
	global_load_dwordx4 v[16:19], v193, s[10:11] offset:0 nt
	global_load_dwordx4 v[20:23], v193, s[10:11] offset:1024 nt
	global_load_dwordx4 v[24:27], v193, s[10:11] offset:2048 nt
	global_load_dwordx4 v[28:31], v193, s[10:11] offset:3072 nt
	global_load_dwordx2 v[32:33], v194, s[22:23] offset:0 nt
	global_load_dwordx2 v[34:35], v194, s[22:23] offset:512 nt
	global_load_dwordx2 v[36:37], v194, s[22:23] offset:1024 nt
	global_load_dwordx2 v[38:39], v194, s[22:23] offset:1536 nt
	global_load_dwordx2 v[40:41], v194, s[22:23] offset:2048 nt
	global_load_dwordx2 v[42:43], v194, s[22:23] offset:2560 nt
	global_load_dwordx2 v[44:45], v194, s[22:23] offset:3072 nt
	global_load_dwordx2 v[46:47], v194, s[22:23] offset:3584 nt
	s_add_i32 s0, s6, 5
	s_add_i32 s0, s6, 5
	s_lshr_b32 s8, s0, 11
	s_cmp_lt_u32 s0, 0x4000
	s_cselect_b32 s8, s8, 8
	s_cmp_eq_u32 s8, s7
	s_cbranch_scc1 .Lp6_np5
	s_mov_b32 s7, s8
	s_add_i32 s1, s8, 9
	s_mul_i32 s1, s1, 0x6000
	s_add_u32 s44, s84, s1
	s_addc_u32 s45, s85, 0
	s_add_u32 s44, s44, 0x2000
	s_addc_u32 s45, s45, 0
	s_add_i32 s1, s8, 9
	s_mul_i32 s1, s1, 0x6000
	s_add_u32 s36, s84, s1
	s_addc_u32 s37, s85, 0
	s_add_u32 s38, s80, 0x2000
	s_addc_u32 s39, s81, 0
	s_mul_i32 s1, s8, 0x6000
	s_add_u32 s34, s84, s1
	s_addc_u32 s35, s85, 0
	s_add_u32 s34, s34, 0x4000
	s_addc_u32 s35, s35, 0
	global_load_dwordx4 v[96:99], v192, s[34:35] offset:0
	global_load_dwordx4 v[200:203], v192, s[82:83] offset:0
	global_load_dwordx4 v[100:103], v192, s[34:35] offset:1024
	global_load_dwordx4 v[204:207], v192, s[82:83] offset:1024
	global_load_dwordx4 v[104:107], v192, s[34:35] offset:2048
	global_load_dwordx4 v[208:211], v192, s[82:83] offset:2048
	global_load_dwordx4 v[108:111], v192, s[34:35] offset:3072
	global_load_dwordx4 v[212:215], v192, s[82:83] offset:3072
	s_waitcnt vmcnt(0)
	v_mul_f32_e32 v96, v96, v200
	v_mul_f32_e32 v97, v97, v201
	v_mul_f32_e32 v98, v98, v202
	v_mul_f32_e32 v99, v99, v203
	v_mul_f32_e32 v100, v100, v204
	v_mul_f32_e32 v101, v101, v205
	v_mul_f32_e32 v102, v102, v206
	v_mul_f32_e32 v103, v103, v207
	v_mul_f32_e32 v104, v104, v208
	v_mul_f32_e32 v105, v105, v209
	v_mul_f32_e32 v106, v106, v210
	v_mul_f32_e32 v107, v107, v211
	v_mul_f32_e32 v108, v108, v212
	v_mul_f32_e32 v109, v109, v213
	v_mul_f32_e32 v110, v110, v214
	v_mul_f32_e32 v111, v111, v215
	global_load_dwordx4 v[128:131], v192, s[38:39] offset:0
	global_load_dwordx4 v[200:203], v192, s[44:45] offset:0
	global_load_dwordx4 v[160:163], v192, s[36:37] offset:0
	global_load_dwordx4 v[132:135], v192, s[38:39] offset:1024
	global_load_dwordx4 v[204:207], v192, s[44:45] offset:1024
	global_load_dwordx4 v[164:167], v192, s[36:37] offset:1024
	global_load_dwordx4 v[136:139], v192, s[38:39] offset:2048
	global_load_dwordx4 v[208:211], v192, s[44:45] offset:2048
	global_load_dwordx4 v[168:171], v192, s[36:37] offset:2048
	global_load_dwordx4 v[140:143], v192, s[38:39] offset:3072
	global_load_dwordx4 v[212:215], v192, s[44:45] offset:3072
	global_load_dwordx4 v[172:175], v192, s[36:37] offset:3072
	s_waitcnt vmcnt(0)
	v_add_f32_e32 v200, 1.0, v200
	v_add_f32_e32 v201, 1.0, v201
	v_add_f32_e32 v202, 1.0, v202
	v_add_f32_e32 v203, 1.0, v203
	v_mul_f32_e32 v128, v128, v200
	v_mul_f32_e32 v129, v129, v201
	v_mul_f32_e32 v130, v130, v202
	v_mul_f32_e32 v131, v131, v203
	v_add_f32_e32 v204, 1.0, v204
	v_add_f32_e32 v205, 1.0, v205
	v_add_f32_e32 v206, 1.0, v206
	v_add_f32_e32 v207, 1.0, v207
	v_mul_f32_e32 v132, v132, v204
	v_mul_f32_e32 v133, v133, v205
	v_mul_f32_e32 v134, v134, v206
	v_mul_f32_e32 v135, v135, v207
	v_add_f32_e32 v208, 1.0, v208
	v_add_f32_e32 v209, 1.0, v209
	v_add_f32_e32 v210, 1.0, v210
	v_add_f32_e32 v211, 1.0, v211
	v_mul_f32_e32 v136, v136, v208
	v_mul_f32_e32 v137, v137, v209
	v_mul_f32_e32 v138, v138, v210
	v_mul_f32_e32 v139, v139, v211
	v_add_f32_e32 v212, 1.0, v212
	v_add_f32_e32 v213, 1.0, v213
	v_add_f32_e32 v214, 1.0, v214
	v_add_f32_e32 v215, 1.0, v215
	v_mul_f32_e32 v140, v140, v212
	v_mul_f32_e32 v141, v141, v213
	v_mul_f32_e32 v142, v142, v214
	v_mul_f32_e32 v143, v143, v215
	global_load_dwordx4 v[112:115], v193, s[34:35] offset:0
	global_load_dwordx4 v[200:203], v193, s[82:83] offset:0
	global_load_dwordx4 v[116:119], v193, s[34:35] offset:1024
	global_load_dwordx4 v[204:207], v193, s[82:83] offset:1024
	global_load_dwordx4 v[120:123], v193, s[34:35] offset:2048
	global_load_dwordx4 v[208:211], v193, s[82:83] offset:2048
	global_load_dwordx4 v[124:127], v193, s[34:35] offset:3072
	global_load_dwordx4 v[212:215], v193, s[82:83] offset:3072
	s_waitcnt vmcnt(0)
; __device__ __forceinline__ float bf_lo(unsigned w) { return __uint_as_float(w << 16); }
; __device__ __forceinline__ float bf_hi(unsigned w) { return __uint_as_float(w & 0xffff0000u); }
; __global__ void __launch_bounds__(NWAVES * 64, 2) mk_fwd(Args args) {
;     ...
;             for (int q = 0; q < 3; ++q) { const int row = row0 + q; const bool lat = row < ML; const int r = lat ? row / SEQ : 8;
;                 float sy = 0.f;
; #pragma unroll
;                 for (int j = 0; j < 8; ++j) { const float a = bf_lo(yw[q][j].x), b = bf_hi(yw[q][j].x), c2 = bf_lo(yw[q][j].y), d = bf_hi(yw[q][j].y); sy += (a * a + b * b) + (c2 * c2 + d * d); }
;                 const float rsy = __builtin_amdgcn_rsqf(wave_sum(sy) * (1.f / DM) + EPS);
;                 const float* m0 = mod + (size_t)r * 6144;
; #pragma unroll
;                 for (int j = 0; j < 8; ++j) { const int col = 4 * F.lane + 256 * j; const f32x4 gt = *(const f32x4*)(m0 + 2 * DM + col), pn = *(const f32x4*)(post_norm + col);
	v_mul_f32_e32 v112, v112, v200
	v_mul_f32_e32 v113, v113, v201
	v_mul_f32_e32 v114, v114, v202
	v_mul_f32_e32 v115, v115, v203
	v_mul_f32_e32 v116, v116, v204
	v_mul_f32_e32 v117, v117, v205
	v_mul_f32_e32 v118, v118, v206
	v_mul_f32_e32 v119, v119, v207
	v_mul_f32_e32 v120, v120, v208
	v_mul_f32_e32 v121, v121, v209
	v_mul_f32_e32 v122, v122, v210
	v_mul_f32_e32 v123, v123, v211
	v_mul_f32_e32 v124, v124, v212
	v_mul_f32_e32 v125, v125, v213
	v_mul_f32_e32 v126, v126, v214
	v_mul_f32_e32 v127, v127, v215
	global_load_dwordx4 v[144:147], v193, s[38:39] offset:0
	global_load_dwordx4 v[200:203], v193, s[44:45] offset:0
	global_load_dwordx4 v[176:179], v193, s[36:37] offset:0
	global_load_dwordx4 v[148:151], v193, s[38:39] offset:1024
	global_load_dwordx4 v[204:207], v193, s[44:45] offset:1024
	global_load_dwordx4 v[180:183], v193, s[36:37] offset:1024
	global_load_dwordx4 v[152:155], v193, s[38:39] offset:2048
	global_load_dwordx4 v[208:211], v193, s[44:45] offset:2048
	global_load_dwordx4 v[184:187], v193, s[36:37] offset:2048
	global_load_dwordx4 v[156:159], v193, s[38:39] offset:3072
	global_load_dwordx4 v[212:215], v193, s[44:45] offset:3072
	global_load_dwordx4 v[188:191], v193, s[36:37] offset:3072
	s_waitcnt vmcnt(0)
	v_add_f32_e32 v200, 1.0, v200
	v_add_f32_e32 v201, 1.0, v201
	v_add_f32_e32 v202, 1.0, v202
	v_add_f32_e32 v203, 1.0, v203
	v_mul_f32_e32 v144, v144, v200
	v_mul_f32_e32 v145, v145, v201
	v_mul_f32_e32 v146, v146, v202
	v_mul_f32_e32 v147, v147, v203
	v_add_f32_e32 v204, 1.0, v204
	v_add_f32_e32 v205, 1.0, v205
	v_add_f32_e32 v206, 1.0, v206
	v_add_f32_e32 v207, 1.0, v207
	v_mul_f32_e32 v148, v148, v204
	v_mul_f32_e32 v149, v149, v205
	v_mul_f32_e32 v150, v150, v206
	v_mul_f32_e32 v151, v151, v207
	v_add_f32_e32 v208, 1.0, v208
	v_add_f32_e32 v209, 1.0, v209
	v_add_f32_e32 v210, 1.0, v210
	v_add_f32_e32 v211, 1.0, v211
	v_mul_f32_e32 v152, v152, v208
	v_mul_f32_e32 v153, v153, v209
	v_mul_f32_e32 v154, v154, v210
	v_mul_f32_e32 v155, v155, v211
	v_add_f32_e32 v212, 1.0, v212
	v_add_f32_e32 v213, 1.0, v213
	v_add_f32_e32 v214, 1.0, v214
	v_add_f32_e32 v215, 1.0, v215
	v_mul_f32_e32 v156, v156, v212
	v_mul_f32_e32 v157, v157, v213
	v_mul_f32_e32 v158, v158, v214
	v_mul_f32_e32 v159, v159, v215
.Lp6_np5:
	s_waitcnt vmcnt(32)
	v_lshlrev_b32_e32 v216, 16, v80
	v_and_b32_e32 v217, 0xffff0000, v80
	v_lshlrev_b32_e32 v218, 16, v81
	v_and_b32_e32 v219, 0xffff0000, v81
	v_mul_f32_e32 v222, v216, v216
	v_mul_f32_e32 v223, v217, v217
	v_fmac_f32_e32 v222, v218, v218
	v_fmac_f32_e32 v223, v219, v219
	v_lshlrev_b32_e32 v216, 16, v82
	v_and_b32_e32 v217, 0xffff0000, v82
	v_lshlrev_b32_e32 v218, 16, v83
	v_and_b32_e32 v219, 0xffff0000, v83
	v_fmac_f32_e32 v222, v216, v216
	v_fmac_f32_e32 v223, v217, v217
	v_fmac_f32_e32 v222, v218, v218
	v_fmac_f32_e32 v223, v219, v219
	v_lshlrev_b32_e32 v216, 16, v84
	v_and_b32_e32 v217, 0xffff0000, v84
	v_lshlrev_b32_e32 v218, 16, v85
	v_and_b32_e32 v219, 0xffff0000, v85
	v_fmac_f32_e32 v222, v216, v216
	v_fmac_f32_e32 v223, v217, v217
	v_fmac_f32_e32 v222, v218, v218
	v_fmac_f32_e32 v223, v219, v219
	v_lshlrev_b32_e32 v216, 16, v86
	v_and_b32_e32 v217, 0xffff0000, v86
	v_lshlrev_b32_e32 v218, 16, v87
	v_and_b32_e32 v219, 0xffff0000, v87
	v_fmac_f32_e32 v222, v216, v216
	v_fmac_f32_e32 v223, v217, v217
	v_fmac_f32_e32 v222, v218, v218
	v_fmac_f32_e32 v223, v219, v219
	v_lshlrev_b32_e32 v216, 16, v88
	v_and_b32_e32 v217, 0xffff0000, v88
	v_lshlrev_b32_e32 v218, 16, v89
	v_and_b32_e32 v219, 0xffff0000, v89
	v_fmac_f32_e32 v222, v216, v216
	v_fmac_f32_e32 v223, v217, v217
	v_fmac_f32_e32 v222, v218, v218
	v_fmac_f32_e32 v223, v219, v219
	v_lshlrev_b32_e32 v216, 16, v90
	v_and_b32_e32 v217, 0xffff0000, v90
	v_lshlrev_b32_e32 v218, 16, v91
	v_and_b32_e32 v219, 0xffff0000, v91
	v_fmac_f32_e32 v222, v216, v216
	v_fmac_f32_e32 v223, v217, v217
	v_fmac_f32_e32 v222, v218, v218
	v_fmac_f32_e32 v223, v219, v219
	v_lshlrev_b32_e32 v216, 16, v92
	v_and_b32_e32 v217, 0xffff0000, v92
	v_lshlrev_b32_e32 v218, 16, v93
	v_and_b32_e32 v219, 0xffff0000, v93
	v_fmac_f32_e32 v222, v216, v216
	v_fmac_f32_e32 v223, v217, v217
	v_fmac_f32_e32 v222, v218, v218
	v_fmac_f32_e32 v223, v219, v219
	v_lshlrev_b32_e32 v216, 16, v94
	v_and_b32_e32 v217, 0xffff0000, v94
	v_lshlrev_b32_e32 v218, 16, v95
	v_and_b32_e32 v219, 0xffff0000, v95
	v_fmac_f32_e32 v222, v216, v216
	v_fmac_f32_e32 v223, v217, v217
	v_fmac_f32_e32 v222, v218, v218
	v_fmac_f32_e32 v223, v219, v219
	v_add_f32_e32 v222, v222, v223
	s_nop 1
	v_add_f32_dpp v224, v222, v222 quad_perm:[1,0,3,2] row_mask:0xf bank_mask:0xf
	s_nop 1
	v_add_f32_dpp v224, v224, v224 quad_perm:[2,3,0,1] row_mask:0xf bank_mask:0xf
	s_nop 1
	v_add_f32_dpp v224, v224, v224 row_half_mirror row_mask:0xf bank_mask:0xf
	s_nop 1
	v_add_f32_dpp v224, v224, v224 row_mirror row_mask:0xf bank_mask:0xf
	s_nop 1
	v_readlane_b32 s40, v224, 0
	v_readlane_b32 s41, v224, 16
	v_readlane_b32 s42, v224, 32
	v_readlane_b32 s43, v224, 48
	s_nop 1
	v_mov_b32_e32 v225, s40
	v_add_f32_e32 v225, s41, v225
	v_add_f32_e32 v225, s42, v225
	v_add_f32_e32 v225, s43, v225
	v_fmamk_f32 v225, v225, 0x3a000000, v195
	v_rsq_f32_e32 v225, v225
	s_nop 0
	s_add_i32 s0, s6, 5
	s_cmp_lt_u32 s0, 0x4000
	s_cselect_b32 s24, s94, s84
	s_cselect_b32 s25, s95, s85
	s_cselect_b32 s44, 0, 0x16000000
	s_cselect_b32 s1, 0, 0x4000
	s_sub_i32 s1, s0, s1
	s_lshl_b32 s1, s1, 13
	s_add_u32 s24, s24, s1
	s_addc_u32 s25, s25, 0
	s_add_u32 s24, s24, s44
	s_addc_u32 s25, s25, 0
	v_lshlrev_b32_e32 v216, 16, v80
	v_and_b32_e32 v217, 0xffff0000, v80
	v_lshlrev_b32_e32 v218, 16, v81
	v_and_b32_e32 v219, 0xffff0000, v81
	v_mul_f32_e32 v216, v225, v216
; __device__ __forceinline__ float bf_lo(unsigned w) { return __uint_as_float(w << 16); }
; __device__ __forceinline__ float bf_hi(unsigned w) { return __uint_as_float(w & 0xffff0000u); }
; __global__ void __launch_bounds__(NWAVES * 64, 2) mk_fwd(Args args) {
;     ...
;                 for (int j = 0; j < 8; ++j) { const int col = 4 * F.lane + 256 * j; const f32x4 gt = *(const f32x4*)(m0 + 2 * DM + col), pn = *(const f32x4*)(post_norm + col);
;                     const f32x4 y4 = (f32x4){bf_lo(yw[q][j].x), bf_hi(yw[q][j].x), bf_lo(yw[q][j].y), bf_hi(yw[q][j].y)};
;                     v[q][j] = v[q][j] + gt * (y4 * rsy * pn);
;                     if (lat) *(f32x4*)(args.out + (size_t)row * DM + col) = v[q][j]; }
;                 const float rstd = __builtin_amdgcn_rsqf(sumsq8(v[q]) * (1.f / DM) + EPS);
;                 modulate_store(v[q], rstd, pre_norm + DM, mod + (size_t)(9 + r) * 6144, H + (size_t)row * DM, F.lane); }
	v_mul_f32_e32 v217, v225, v217
	v_mul_f32_e32 v218, v225, v218
	v_mul_f32_e32 v219, v225, v219
	v_fmac_f32_e32 v48, v96, v216
	v_fmac_f32_e32 v49, v97, v217
	v_fmac_f32_e32 v50, v98, v218
	v_fmac_f32_e32 v51, v99, v219
	global_store_dwordx4 v192, v[48:51], s[24:25] offset:0
	v_lshlrev_b32_e32 v216, 16, v82
	v_and_b32_e32 v217, 0xffff0000, v82
	v_lshlrev_b32_e32 v218, 16, v83
	v_and_b32_e32 v219, 0xffff0000, v83
	v_mul_f32_e32 v216, v225, v216
	v_mul_f32_e32 v217, v225, v217
	v_mul_f32_e32 v218, v225, v218
	v_mul_f32_e32 v219, v225, v219
	v_fmac_f32_e32 v52, v100, v216
	v_fmac_f32_e32 v53, v101, v217
	v_fmac_f32_e32 v54, v102, v218
	v_fmac_f32_e32 v55, v103, v219
	global_store_dwordx4 v192, v[52:55], s[24:25] offset:1024
	v_lshlrev_b32_e32 v216, 16, v84
	v_and_b32_e32 v217, 0xffff0000, v84
	v_lshlrev_b32_e32 v218, 16, v85
	v_and_b32_e32 v219, 0xffff0000, v85
	v_mul_f32_e32 v216, v225, v216
	v_mul_f32_e32 v217, v225, v217
	v_mul_f32_e32 v218, v225, v218
	v_mul_f32_e32 v219, v225, v219
	v_fmac_f32_e32 v56, v104, v216
	v_fmac_f32_e32 v57, v105, v217
	v_fmac_f32_e32 v58, v106, v218
	v_fmac_f32_e32 v59, v107, v219
	global_store_dwordx4 v192, v[56:59], s[24:25] offset:2048
	v_lshlrev_b32_e32 v216, 16, v86
	v_and_b32_e32 v217, 0xffff0000, v86
	v_lshlrev_b32_e32 v218, 16, v87
	v_and_b32_e32 v219, 0xffff0000, v87
	v_mul_f32_e32 v216, v225, v216
	v_mul_f32_e32 v217, v225, v217
	v_mul_f32_e32 v218, v225, v218
	v_mul_f32_e32 v219, v225, v219
	v_fmac_f32_e32 v60, v108, v216
	v_fmac_f32_e32 v61, v109, v217
	v_fmac_f32_e32 v62, v110, v218
	v_fmac_f32_e32 v63, v111, v219
	global_store_dwordx4 v192, v[60:63], s[24:25] offset:3072
	v_lshlrev_b32_e32 v216, 16, v88
	v_and_b32_e32 v217, 0xffff0000, v88
	v_lshlrev_b32_e32 v218, 16, v89
	v_and_b32_e32 v219, 0xffff0000, v89
	v_mul_f32_e32 v216, v225, v216
	v_mul_f32_e32 v217, v225, v217
	v_mul_f32_e32 v218, v225, v218
	v_mul_f32_e32 v219, v225, v219
	v_fmac_f32_e32 v64, v112, v216
	v_fmac_f32_e32 v65, v113, v217
	v_fmac_f32_e32 v66, v114, v218
	v_fmac_f32_e32 v67, v115, v219
	global_store_dwordx4 v193, v[64:67], s[24:25] offset:0
	v_lshlrev_b32_e32 v216, 16, v90
	v_and_b32_e32 v217, 0xffff0000, v90
	v_lshlrev_b32_e32 v218, 16, v91
	v_and_b32_e32 v219, 0xffff0000, v91
	v_mul_f32_e32 v216, v225, v216
	v_mul_f32_e32 v217, v225, v217
	v_mul_f32_e32 v218, v225, v218
	v_mul_f32_e32 v219, v225, v219
	v_fmac_f32_e32 v68, v116, v216
	v_fmac_f32_e32 v69, v117, v217
	v_fmac_f32_e32 v70, v118, v218
	v_fmac_f32_e32 v71, v119, v219
	global_store_dwordx4 v193, v[68:71], s[24:25] offset:1024
	v_lshlrev_b32_e32 v216, 16, v92
	v_and_b32_e32 v217, 0xffff0000, v92
	v_lshlrev_b32_e32 v218, 16, v93
	v_and_b32_e32 v219, 0xffff0000, v93
	v_mul_f32_e32 v216, v225, v216
	v_mul_f32_e32 v217, v225, v217
	v_mul_f32_e32 v218, v225, v218
	v_mul_f32_e32 v219, v225, v219
	v_fmac_f32_e32 v72, v120, v216
	v_fmac_f32_e32 v73, v121, v217
	v_fmac_f32_e32 v74, v122, v218
	v_fmac_f32_e32 v75, v123, v219
	global_store_dwordx4 v193, v[72:75], s[24:25] offset:2048
	v_lshlrev_b32_e32 v216, 16, v94
	v_and_b32_e32 v217, 0xffff0000, v94
	v_lshlrev_b32_e32 v218, 16, v95
	v_and_b32_e32 v219, 0xffff0000, v95
	v_mul_f32_e32 v216, v225, v216
	v_mul_f32_e32 v217, v225, v217
	v_mul_f32_e32 v218, v225, v218
	v_mul_f32_e32 v219, v225, v219
	v_fmac_f32_e32 v76, v124, v216
	v_fmac_f32_e32 v77, v125, v217
	v_fmac_f32_e32 v78, v126, v218
	v_fmac_f32_e32 v79, v127, v219
	global_store_dwordx4 v193, v[76:79], s[24:25] offset:3072
	v_mul_f32_e32 v222, v48, v48
	v_mul_f32_e32 v223, v49, v49
	v_fmac_f32_e32 v222, v50, v50
	v_fmac_f32_e32 v223, v51, v51
	v_fmac_f32_e32 v222, v52, v52
	v_fmac_f32_e32 v223, v53, v53
	v_fmac_f32_e32 v222, v54, v54
	v_fmac_f32_e32 v223, v55, v55
	v_fmac_f32_e32 v222, v56, v56
	v_fmac_f32_e32 v223, v57, v57
	v_fmac_f32_e32 v222, v58, v58
	v_fmac_f32_e32 v223, v59, v59
	v_fmac_f32_e32 v222, v60, v60
	v_fmac_f32_e32 v223, v61, v61
	v_fmac_f32_e32 v222, v62, v62
	v_fmac_f32_e32 v223, v63, v63
	v_fmac_f32_e32 v222, v64, v64
	v_fmac_f32_e32 v223, v65, v65
	v_fmac_f32_e32 v222, v66, v66
	v_fmac_f32_e32 v223, v67, v67
	v_fmac_f32_e32 v222, v68, v68
	v_fmac_f32_e32 v223, v69, v69
	v_fmac_f32_e32 v222, v70, v70
	v_fmac_f32_e32 v223, v71, v71
	v_fmac_f32_e32 v222, v72, v72
	v_fmac_f32_e32 v223, v73, v73
	v_fmac_f32_e32 v222, v74, v74
	v_fmac_f32_e32 v223, v75, v75
	v_fmac_f32_e32 v222, v76, v76
	v_fmac_f32_e32 v223, v77, v77
	v_fmac_f32_e32 v222, v78, v78
	v_fmac_f32_e32 v223, v79, v79
	v_add_f32_e32 v222, v222, v223
	s_nop 1
	v_add_f32_dpp v224, v222, v222 quad_perm:[1,0,3,2] row_mask:0xf bank_mask:0xf
	s_nop 1
	v_add_f32_dpp v224, v224, v224 quad_perm:[2,3,0,1] row_mask:0xf bank_mask:0xf
	s_nop 1
	v_add_f32_dpp v224, v224, v224 row_half_mirror row_mask:0xf bank_mask:0xf
	s_nop 1
	v_add_f32_dpp v224, v224, v224 row_mirror row_mask:0xf bank_mask:0xf
	s_nop 1
	v_readlane_b32 s40, v224, 0
	v_readlane_b32 s41, v224, 16
	v_readlane_b32 s42, v224, 32
	v_readlane_b32 s43, v224, 48
	s_nop 1
	v_mov_b32_e32 v225, s40
	v_add_f32_e32 v225, s41, v225
	v_add_f32_e32 v225, s42, v225
	v_add_f32_e32 v225, s43, v225
	v_fmamk_f32 v225, v225, 0x3a000000, v195
	v_rsq_f32_e32 v225, v225
	s_nop 0
	s_add_i32 s0, s6, 5
	s_lshl_b32 s1, s0, 12
	s_add_u32 s26, s84, s1
	s_addc_u32 s27, s85, 0
	s_add_u32 s26, s26, 0x4000000
	s_addc_u32 s27, s27, 0
	v_mul_f32_e32 v216, v225, v48
	v_mul_f32_e32 v217, v225, v49
	v_mul_f32_e32 v218, v225, v50
	v_mul_f32_e32 v219, v225, v51
	v_fma_f32 v216, v216, v128, v160
	v_fma_f32 v217, v217, v129, v161
	v_fma_f32 v218, v218, v130, v162
	v_fma_f32 v219, v219, v131, v163
	v_cvt_pk_bf16_f32 v196, v216, v217
	v_cvt_pk_bf16_f32 v197, v218, v219
; __device__ __forceinline__ unsigned cvt_pk_bf16(float lo, float hi) { unsigned r; asm volatile("v_cvt_pk_bf16_f32 %0, %1, %2" : "=v"(r) : "v"(lo), "v"(hi)); return r; }
; __device__ __forceinline__ void modulate_store(const f32x4 (&v)[8], float rstd, const float* pn, const float* modr, bf16_t* orow, int lane) {
; #pragma unroll
;     for (int j = 0; j < 8; ++j) { const int col = 4 * lane + 256 * j;
;         const f32x4 g = *(const f32x4*)(pn + col), sh = *(const f32x4*)(modr + col), sc = *(const f32x4*)(modr + DM + col);
;         const f32x4 hh = v[j] * rstd * g * (sc + 1.f) + sh;
;         u32x2 w; w.x = cvt_pk_bf16(hh[0], hh[1]); w.y = cvt_pk_bf16(hh[2], hh[3]);
;         *(u32x2*)(orow + col) = w; }
; }
; __global__ void __launch_bounds__(NWAVES * 64, 2) mk_fwd(Args args) {
;     ...
;         for (int row0 = F.gw * 3; row0 < MT; row0 += F.NGW * 3) {
;             f32x4 v[3][8]; u32x2 yw[3][8];
; #pragma unroll
;             for (int q = 0; q < 3; ++q) { const int row = row0 + q; const float* src = row < ML ? x + (size_t)row * DM : ctx + (size_t)(row - ML) * DM; load_row_f32(src, F.lane, v[q]);
;                 const bf16_t* yr = Y + (size_t)row * DM;
; #pragma unroll
;                 for (int j = 0; j < 8; ++j) yw[q][j] = *(const u32x2*)(yr + 4 * F.lane + 256 * j); }
	global_store_dwordx2 v194, v[196:197], s[26:27] offset:0
	v_mul_f32_e32 v216, v225, v52
	v_mul_f32_e32 v217, v225, v53
	v_mul_f32_e32 v218, v225, v54
	v_mul_f32_e32 v219, v225, v55
	v_fma_f32 v216, v216, v132, v164
	v_fma_f32 v217, v217, v133, v165
	v_fma_f32 v218, v218, v134, v166
	v_fma_f32 v219, v219, v135, v167
	v_cvt_pk_bf16_f32 v220, v216, v217
	v_cvt_pk_bf16_f32 v221, v218, v219
	global_store_dwordx2 v194, v[220:221], s[26:27] offset:512
	v_mul_f32_e32 v216, v225, v56
	v_mul_f32_e32 v217, v225, v57
	v_mul_f32_e32 v218, v225, v58
	v_mul_f32_e32 v219, v225, v59
	v_fma_f32 v216, v216, v136, v168
	v_fma_f32 v217, v217, v137, v169
	v_fma_f32 v218, v218, v138, v170
	v_fma_f32 v219, v219, v139, v171
	v_cvt_pk_bf16_f32 v196, v216, v217
	v_cvt_pk_bf16_f32 v197, v218, v219
	global_store_dwordx2 v194, v[196:197], s[26:27] offset:1024
	v_mul_f32_e32 v216, v225, v60
	v_mul_f32_e32 v217, v225, v61
	v_mul_f32_e32 v218, v225, v62
	v_mul_f32_e32 v219, v225, v63
	v_fma_f32 v216, v216, v140, v172
	v_fma_f32 v217, v217, v141, v173
	v_fma_f32 v218, v218, v142, v174
	v_fma_f32 v219, v219, v143, v175
	v_cvt_pk_bf16_f32 v220, v216, v217
	v_cvt_pk_bf16_f32 v221, v218, v219
	global_store_dwordx2 v194, v[220:221], s[26:27] offset:1536
	v_mul_f32_e32 v216, v225, v64
	v_mul_f32_e32 v217, v225, v65
	v_mul_f32_e32 v218, v225, v66
	v_mul_f32_e32 v219, v225, v67
	v_fma_f32 v216, v216, v144, v176
	v_fma_f32 v217, v217, v145, v177
	v_fma_f32 v218, v218, v146, v178
	v_fma_f32 v219, v219, v147, v179
	v_cvt_pk_bf16_f32 v196, v216, v217
	v_cvt_pk_bf16_f32 v197, v218, v219
	global_store_dwordx2 v194, v[196:197], s[26:27] offset:2048
	v_mul_f32_e32 v216, v225, v68
	v_mul_f32_e32 v217, v225, v69
	v_mul_f32_e32 v218, v225, v70
	v_mul_f32_e32 v219, v225, v71
	v_fma_f32 v216, v216, v148, v180
	v_fma_f32 v217, v217, v149, v181
	v_fma_f32 v218, v218, v150, v182
	v_fma_f32 v219, v219, v151, v183
	v_cvt_pk_bf16_f32 v220, v216, v217
	v_cvt_pk_bf16_f32 v221, v218, v219
	global_store_dwordx2 v194, v[220:221], s[26:27] offset:2560
	v_mul_f32_e32 v216, v225, v72
	v_mul_f32_e32 v217, v225, v73
	v_mul_f32_e32 v218, v225, v74
	v_mul_f32_e32 v219, v225, v75
	v_fma_f32 v216, v216, v152, v184
	v_fma_f32 v217, v217, v153, v185
	v_fma_f32 v218, v218, v154, v186
	v_fma_f32 v219, v219, v155, v187
	v_cvt_pk_bf16_f32 v196, v216, v217
	v_cvt_pk_bf16_f32 v197, v218, v219
	global_store_dwordx2 v194, v[196:197], s[26:27] offset:3072
	v_mul_f32_e32 v216, v225, v76
	v_mul_f32_e32 v217, v225, v77
	v_mul_f32_e32 v218, v225, v78
	v_mul_f32_e32 v219, v225, v79
	v_fma_f32 v216, v216, v156, v188
	v_fma_f32 v217, v217, v157, v189
	v_fma_f32 v218, v218, v158, v190
	v_fma_f32 v219, v219, v159, v191
	v_cvt_pk_bf16_f32 v220, v216, v217
	v_cvt_pk_bf16_f32 v221, v218, v219
	global_store_dwordx2 v194, v[220:221], s[26:27] offset:3584
	s_add_i32 s0, s6, 7
	s_cmp_lt_u32 s0, 0x4000
	s_cselect_b32 s10, s68, s72
	s_cselect_b32 s11, s69, s73
	s_cselect_b32 s1, 0, 0x4000
	s_sub_i32 s1, s0, s1
	s_lshl_b32 s1, s1, 13
	s_add_u32 s10, s10, s1
	s_addc_u32 s11, s11, 0
	s_add_i32 s0, s6, 7
	s_lshl_b32 s1, s0, 12
	s_add_u32 s22, s84, s1
	s_addc_u32 s23, s85, 0
	s_add_u32 s22, s22, 0x11800000
	s_addc_u32 s23, s23, 0
	global_load_dwordx4 v[48:51], v192, s[10:11] offset:0 nt
	global_load_dwordx4 v[52:55], v192, s[10:11] offset:1024 nt
	global_load_dwordx4 v[56:59], v192, s[10:11] offset:2048 nt
	global_load_dwordx4 v[60:63], v192, s[10:11] offset:3072 nt
	global_load_dwordx4 v[64:67], v193, s[10:11] offset:0 nt
	global_load_dwordx4 v[68:71], v193, s[10:11] offset:1024 nt
	global_load_dwordx4 v[72:75], v193, s[10:11] offset:2048 nt
	global_load_dwordx4 v[76:79], v193, s[10:11] offset:3072 nt
	global_load_dwordx2 v[80:81], v194, s[22:23] offset:0 nt
	global_load_dwordx2 v[82:83], v194, s[22:23] offset:512 nt
	global_load_dwordx2 v[84:85], v194, s[22:23] offset:1024 nt
	global_load_dwordx2 v[86:87], v194, s[22:23] offset:1536 nt
	global_load_dwordx2 v[88:89], v194, s[22:23] offset:2048 nt
	global_load_dwordx2 v[90:91], v194, s[22:23] offset:2560 nt
	global_load_dwordx2 v[92:93], v194, s[22:23] offset:3072 nt
	global_load_dwordx2 v[94:95], v194, s[22:23] offset:3584 nt
	s_add_i32 s0, s6, 6
	s_add_i32 s0, s6, 6
	s_lshr_b32 s8, s0, 11
	s_cmp_lt_u32 s0, 0x4000
	s_cselect_b32 s8, s8, 8
	s_cmp_eq_u32 s8, s7
	s_cbranch_scc1 .Lp6_np6
; __device__ __forceinline__ float bf_lo(unsigned w) { return __uint_as_float(w << 16); }
; __device__ __forceinline__ float bf_hi(unsigned w) { return __uint_as_float(w & 0xffff0000u); }
; __device__ __forceinline__ void modulate_store(const f32x4 (&v)[8], float rstd, const float* pn, const float* modr, bf16_t* orow, int lane) {
; #pragma unroll
;     for (int j = 0; j < 8; ++j) { const int col = 4 * lane + 256 * j;
;         const f32x4 g = *(const f32x4*)(pn + col), sh = *(const f32x4*)(modr + col), sc = *(const f32x4*)(modr + DM + col);
;         const f32x4 hh = v[j] * rstd * g * (sc + 1.f) + sh;
; __global__ void __launch_bounds__(NWAVES * 64, 2) mk_fwd(Args args) {
;     ...
;                 const float* m0 = mod + (size_t)r * 6144;
; #pragma unroll
;                 for (int j = 0; j < 8; ++j) { const int col = 4 * F.lane + 256 * j; const f32x4 gt = *(const f32x4*)(m0 + 2 * DM + col), pn = *(const f32x4*)(post_norm + col);
;                     const f32x4 y4 = (f32x4){bf_lo(yw[q][j].x), bf_hi(yw[q][j].x), bf_lo(yw[q][j].y), bf_hi(yw[q][j].y)};
;                     v[q][j] = v[q][j] + gt * (y4 * rsy * pn);
	s_mov_b32 s7, s8
	s_add_i32 s1, s8, 9
	s_mul_i32 s1, s1, 0x6000
	s_add_u32 s44, s84, s1
	s_addc_u32 s45, s85, 0
	s_add_u32 s44, s44, 0x2000
	s_addc_u32 s45, s45, 0
	s_add_i32 s1, s8, 9
	s_mul_i32 s1, s1, 0x6000
	s_add_u32 s36, s84, s1
	s_addc_u32 s37, s85, 0
	s_add_u32 s38, s80, 0x2000
	s_addc_u32 s39, s81, 0
	s_mul_i32 s1, s8, 0x6000
	s_add_u32 s34, s84, s1
	s_addc_u32 s35, s85, 0
	s_add_u32 s34, s34, 0x4000
	s_addc_u32 s35, s35, 0
	global_load_dwordx4 v[96:99], v192, s[34:35] offset:0
	global_load_dwordx4 v[200:203], v192, s[82:83] offset:0
	global_load_dwordx4 v[100:103], v192, s[34:35] offset:1024
	global_load_dwordx4 v[204:207], v192, s[82:83] offset:1024
	global_load_dwordx4 v[104:107], v192, s[34:35] offset:2048
	global_load_dwordx4 v[208:211], v192, s[82:83] offset:2048
	global_load_dwordx4 v[108:111], v192, s[34:35] offset:3072
	global_load_dwordx4 v[212:215], v192, s[82:83] offset:3072
	s_waitcnt vmcnt(0)
	v_mul_f32_e32 v96, v96, v200
	v_mul_f32_e32 v97, v97, v201
	v_mul_f32_e32 v98, v98, v202
	v_mul_f32_e32 v99, v99, v203
	v_mul_f32_e32 v100, v100, v204
	v_mul_f32_e32 v101, v101, v205
	v_mul_f32_e32 v102, v102, v206
	v_mul_f32_e32 v103, v103, v207
	v_mul_f32_e32 v104, v104, v208
	v_mul_f32_e32 v105, v105, v209
	v_mul_f32_e32 v106, v106, v210
	v_mul_f32_e32 v107, v107, v211
	v_mul_f32_e32 v108, v108, v212
	v_mul_f32_e32 v109, v109, v213
	v_mul_f32_e32 v110, v110, v214
	v_mul_f32_e32 v111, v111, v215
	global_load_dwordx4 v[128:131], v192, s[38:39] offset:0
	global_load_dwordx4 v[200:203], v192, s[44:45] offset:0
	global_load_dwordx4 v[160:163], v192, s[36:37] offset:0
	global_load_dwordx4 v[132:135], v192, s[38:39] offset:1024
	global_load_dwordx4 v[204:207], v192, s[44:45] offset:1024
	global_load_dwordx4 v[164:167], v192, s[36:37] offset:1024
	global_load_dwordx4 v[136:139], v192, s[38:39] offset:2048
	global_load_dwordx4 v[208:211], v192, s[44:45] offset:2048
	global_load_dwordx4 v[168:171], v192, s[36:37] offset:2048
	global_load_dwordx4 v[140:143], v192, s[38:39] offset:3072
	global_load_dwordx4 v[212:215], v192, s[44:45] offset:3072
	global_load_dwordx4 v[172:175], v192, s[36:37] offset:3072
	s_waitcnt vmcnt(0)
	v_add_f32_e32 v200, 1.0, v200
	v_add_f32_e32 v201, 1.0, v201
	v_add_f32_e32 v202, 1.0, v202
	v_add_f32_e32 v203, 1.0, v203
	v_mul_f32_e32 v128, v128, v200
	v_mul_f32_e32 v129, v129, v201
	v_mul_f32_e32 v130, v130, v202
	v_mul_f32_e32 v131, v131, v203
	v_add_f32_e32 v204, 1.0, v204
	v_add_f32_e32 v205, 1.0, v205
	v_add_f32_e32 v206, 1.0, v206
	v_add_f32_e32 v207, 1.0, v207
	v_mul_f32_e32 v132, v132, v204
	v_mul_f32_e32 v133, v133, v205
	v_mul_f32_e32 v134, v134, v206
	v_mul_f32_e32 v135, v135, v207
	v_add_f32_e32 v208, 1.0, v208
	v_add_f32_e32 v209, 1.0, v209
	v_add_f32_e32 v210, 1.0, v210
	v_add_f32_e32 v211, 1.0, v211
	v_mul_f32_e32 v136, v136, v208
	v_mul_f32_e32 v137, v137, v209
	v_mul_f32_e32 v138, v138, v210
	v_mul_f32_e32 v139, v139, v211
	v_add_f32_e32 v212, 1.0, v212
	v_add_f32_e32 v213, 1.0, v213
	v_add_f32_e32 v214, 1.0, v214
	v_add_f32_e32 v215, 1.0, v215
	v_mul_f32_e32 v140, v140, v212
	v_mul_f32_e32 v141, v141, v213
	v_mul_f32_e32 v142, v142, v214
	v_mul_f32_e32 v143, v143, v215
	global_load_dwordx4 v[112:115], v193, s[34:35] offset:0
	global_load_dwordx4 v[200:203], v193, s[82:83] offset:0
	global_load_dwordx4 v[116:119], v193, s[34:35] offset:1024
	global_load_dwordx4 v[204:207], v193, s[82:83] offset:1024
	global_load_dwordx4 v[120:123], v193, s[34:35] offset:2048
	global_load_dwordx4 v[208:211], v193, s[82:83] offset:2048
	global_load_dwordx4 v[124:127], v193, s[34:35] offset:3072
	global_load_dwordx4 v[212:215], v193, s[82:83] offset:3072
	s_waitcnt vmcnt(0)
	v_mul_f32_e32 v112, v112, v200
	v_mul_f32_e32 v113, v113, v201
	v_mul_f32_e32 v114, v114, v202
	v_mul_f32_e32 v115, v115, v203
	v_mul_f32_e32 v116, v116, v204
	v_mul_f32_e32 v117, v117, v205
	v_mul_f32_e32 v118, v118, v206
	v_mul_f32_e32 v119, v119, v207
	v_mul_f32_e32 v120, v120, v208
	v_mul_f32_e32 v121, v121, v209
	v_mul_f32_e32 v122, v122, v210
	v_mul_f32_e32 v123, v123, v211
	v_mul_f32_e32 v124, v124, v212
	v_mul_f32_e32 v125, v125, v213
	v_mul_f32_e32 v126, v126, v214
	v_mul_f32_e32 v127, v127, v215
	global_load_dwordx4 v[144:147], v193, s[38:39] offset:0
	global_load_dwordx4 v[200:203], v193, s[44:45] offset:0
	global_load_dwordx4 v[176:179], v193, s[36:37] offset:0
	global_load_dwordx4 v[148:151], v193, s[38:39] offset:1024
	global_load_dwordx4 v[204:207], v193, s[44:45] offset:1024
	global_load_dwordx4 v[180:183], v193, s[36:37] offset:1024
	global_load_dwordx4 v[152:155], v193, s[38:39] offset:2048
	global_load_dwordx4 v[208:211], v193, s[44:45] offset:2048
	global_load_dwordx4 v[184:187], v193, s[36:37] offset:2048
	global_load_dwordx4 v[156:159], v193, s[38:39] offset:3072
	global_load_dwordx4 v[212:215], v193, s[44:45] offset:3072
	global_load_dwordx4 v[188:191], v193, s[36:37] offset:3072
	s_waitcnt vmcnt(0)
	v_add_f32_e32 v200, 1.0, v200
	v_add_f32_e32 v201, 1.0, v201
	v_add_f32_e32 v202, 1.0, v202
	v_add_f32_e32 v203, 1.0, v203
	v_mul_f32_e32 v144, v144, v200
	v_mul_f32_e32 v145, v145, v201
	v_mul_f32_e32 v146, v146, v202
	v_mul_f32_e32 v147, v147, v203
	v_add_f32_e32 v204, 1.0, v204
	v_add_f32_e32 v205, 1.0, v205
	v_add_f32_e32 v206, 1.0, v206
	v_add_f32_e32 v207, 1.0, v207
	v_mul_f32_e32 v148, v148, v204
	v_mul_f32_e32 v149, v149, v205
	v_mul_f32_e32 v150, v150, v206
	v_mul_f32_e32 v151, v151, v207
	v_add_f32_e32 v208, 1.0, v208
	v_add_f32_e32 v209, 1.0, v209
	v_add_f32_e32 v210, 1.0, v210
	v_add_f32_e32 v211, 1.0, v211
	v_mul_f32_e32 v152, v152, v208
	v_mul_f32_e32 v153, v153, v209
	v_mul_f32_e32 v154, v154, v210
	v_mul_f32_e32 v155, v155, v211
	v_add_f32_e32 v212, 1.0, v212
	v_add_f32_e32 v213, 1.0, v213
	v_add_f32_e32 v214, 1.0, v214
	v_add_f32_e32 v215, 1.0, v215
	v_mul_f32_e32 v156, v156, v212
	v_mul_f32_e32 v157, v157, v213
	v_mul_f32_e32 v158, v158, v214
	v_mul_f32_e32 v159, v159, v215
; __device__ __forceinline__ float bf_lo(unsigned w) { return __uint_as_float(w << 16); }
; __device__ __forceinline__ float bf_hi(unsigned w) { return __uint_as_float(w & 0xffff0000u); }
; __global__ void __launch_bounds__(NWAVES * 64, 2) mk_fwd(Args args) {
;     ...
;             for (int q = 0; q < 3; ++q) { const int row = row0 + q; const bool lat = row < ML; const int r = lat ? row / SEQ : 8;
;                 float sy = 0.f;
; #pragma unroll
;                 for (int j = 0; j < 8; ++j) { const float a = bf_lo(yw[q][j].x), b = bf_hi(yw[q][j].x), c2 = bf_lo(yw[q][j].y), d = bf_hi(yw[q][j].y); sy += (a * a + b * b) + (c2 * c2 + d * d); }
;                 const float rsy = __builtin_amdgcn_rsqf(wave_sum(sy) * (1.f / DM) + EPS);
;                 const float* m0 = mod + (size_t)r * 6144;
; #pragma unroll
;                 for (int j = 0; j < 8; ++j) { const int col = 4 * F.lane + 256 * j; const f32x4 gt = *(const f32x4*)(m0 + 2 * DM + col), pn = *(const f32x4*)(post_norm + col);
;                     const f32x4 y4 = (f32x4){bf_lo(yw[q][j].x), bf_hi(yw[q][j].x), bf_lo(yw[q][j].y), bf_hi(yw[q][j].y)};
;                     v[q][j] = v[q][j] + gt * (y4 * rsy * pn);
;                     if (lat) *(f32x4*)(args.out + (size_t)row * DM + col) = v[q][j]; }
.Lp6_np6:
	s_waitcnt vmcnt(32)
	v_lshlrev_b32_e32 v216, 16, v32
	v_and_b32_e32 v217, 0xffff0000, v32
	v_lshlrev_b32_e32 v218, 16, v33
	v_and_b32_e32 v219, 0xffff0000, v33
	v_mul_f32_e32 v222, v216, v216
	v_mul_f32_e32 v223, v217, v217
	v_fmac_f32_e32 v222, v218, v218
	v_fmac_f32_e32 v223, v219, v219
	v_lshlrev_b32_e32 v216, 16, v34
	v_and_b32_e32 v217, 0xffff0000, v34
	v_lshlrev_b32_e32 v218, 16, v35
	v_and_b32_e32 v219, 0xffff0000, v35
	v_fmac_f32_e32 v222, v216, v216
	v_fmac_f32_e32 v223, v217, v217
	v_fmac_f32_e32 v222, v218, v218
	v_fmac_f32_e32 v223, v219, v219
	v_lshlrev_b32_e32 v216, 16, v36
	v_and_b32_e32 v217, 0xffff0000, v36
	v_lshlrev_b32_e32 v218, 16, v37
	v_and_b32_e32 v219, 0xffff0000, v37
	v_fmac_f32_e32 v222, v216, v216
	v_fmac_f32_e32 v223, v217, v217
	v_fmac_f32_e32 v222, v218, v218
	v_fmac_f32_e32 v223, v219, v219
	v_lshlrev_b32_e32 v216, 16, v38
	v_and_b32_e32 v217, 0xffff0000, v38
	v_lshlrev_b32_e32 v218, 16, v39
	v_and_b32_e32 v219, 0xffff0000, v39
	v_fmac_f32_e32 v222, v216, v216
	v_fmac_f32_e32 v223, v217, v217
	v_fmac_f32_e32 v222, v218, v218
	v_fmac_f32_e32 v223, v219, v219
	v_lshlrev_b32_e32 v216, 16, v40
	v_and_b32_e32 v217, 0xffff0000, v40
	v_lshlrev_b32_e32 v218, 16, v41
	v_and_b32_e32 v219, 0xffff0000, v41
	v_fmac_f32_e32 v222, v216, v216
	v_fmac_f32_e32 v223, v217, v217
	v_fmac_f32_e32 v222, v218, v218
	v_fmac_f32_e32 v223, v219, v219
	v_lshlrev_b32_e32 v216, 16, v42
	v_and_b32_e32 v217, 0xffff0000, v42
	v_lshlrev_b32_e32 v218, 16, v43
	v_and_b32_e32 v219, 0xffff0000, v43
	v_fmac_f32_e32 v222, v216, v216
	v_fmac_f32_e32 v223, v217, v217
	v_fmac_f32_e32 v222, v218, v218
	v_fmac_f32_e32 v223, v219, v219
	v_lshlrev_b32_e32 v216, 16, v44
	v_and_b32_e32 v217, 0xffff0000, v44
	v_lshlrev_b32_e32 v218, 16, v45
	v_and_b32_e32 v219, 0xffff0000, v45
	v_fmac_f32_e32 v222, v216, v216
	v_fmac_f32_e32 v223, v217, v217
	v_fmac_f32_e32 v222, v218, v218
	v_fmac_f32_e32 v223, v219, v219
	v_lshlrev_b32_e32 v216, 16, v46
	v_and_b32_e32 v217, 0xffff0000, v46
	v_lshlrev_b32_e32 v218, 16, v47
	v_and_b32_e32 v219, 0xffff0000, v47
	v_fmac_f32_e32 v222, v216, v216
	v_fmac_f32_e32 v223, v217, v217
	v_fmac_f32_e32 v222, v218, v218
	v_fmac_f32_e32 v223, v219, v219
	v_add_f32_e32 v222, v222, v223
	s_nop 1
	v_add_f32_dpp v224, v222, v222 quad_perm:[1,0,3,2] row_mask:0xf bank_mask:0xf
	s_nop 1
	v_add_f32_dpp v224, v224, v224 quad_perm:[2,3,0,1] row_mask:0xf bank_mask:0xf
	s_nop 1
	v_add_f32_dpp v224, v224, v224 row_half_mirror row_mask:0xf bank_mask:0xf
	s_nop 1
	v_add_f32_dpp v224, v224, v224 row_mirror row_mask:0xf bank_mask:0xf
	s_nop 1
	v_readlane_b32 s40, v224, 0
	v_readlane_b32 s41, v224, 16
	v_readlane_b32 s42, v224, 32
	v_readlane_b32 s43, v224, 48
	s_nop 1
	v_mov_b32_e32 v225, s40
	v_add_f32_e32 v225, s41, v225
	v_add_f32_e32 v225, s42, v225
	v_add_f32_e32 v225, s43, v225
	v_fmamk_f32 v225, v225, 0x3a000000, v195
	v_rsq_f32_e32 v225, v225
	s_nop 0
	s_add_i32 s0, s6, 6
	s_cmp_lt_u32 s0, 0x4000
	s_cselect_b32 s24, s94, s84
	s_cselect_b32 s25, s95, s85
	s_cselect_b32 s44, 0, 0x16000000
	s_cselect_b32 s1, 0, 0x4000
	s_sub_i32 s1, s0, s1
	s_lshl_b32 s1, s1, 13
	s_add_u32 s24, s24, s1
	s_addc_u32 s25, s25, 0
	s_add_u32 s24, s24, s44
	s_addc_u32 s25, s25, 0
	v_lshlrev_b32_e32 v216, 16, v32
	v_and_b32_e32 v217, 0xffff0000, v32
	v_lshlrev_b32_e32 v218, 16, v33
	v_and_b32_e32 v219, 0xffff0000, v33
	v_mul_f32_e32 v216, v225, v216
	v_mul_f32_e32 v217, v225, v217
	v_mul_f32_e32 v218, v225, v218
	v_mul_f32_e32 v219, v225, v219
	v_fmac_f32_e32 v0, v96, v216
	v_fmac_f32_e32 v1, v97, v217
	v_fmac_f32_e32 v2, v98, v218
	v_fmac_f32_e32 v3, v99, v219
	global_store_dwordx4 v192, v[0:3], s[24:25] offset:0
	v_lshlrev_b32_e32 v216, 16, v34
	v_and_b32_e32 v217, 0xffff0000, v34
	v_lshlrev_b32_e32 v218, 16, v35
	v_and_b32_e32 v219, 0xffff0000, v35
	v_mul_f32_e32 v216, v225, v216
	v_mul_f32_e32 v217, v225, v217
	v_mul_f32_e32 v218, v225, v218
	v_mul_f32_e32 v219, v225, v219
	v_fmac_f32_e32 v4, v100, v216
	v_fmac_f32_e32 v5, v101, v217
	v_fmac_f32_e32 v6, v102, v218
	v_fmac_f32_e32 v7, v103, v219
	global_store_dwordx4 v192, v[4:7], s[24:25] offset:1024
	v_lshlrev_b32_e32 v216, 16, v36
	v_and_b32_e32 v217, 0xffff0000, v36
	v_lshlrev_b32_e32 v218, 16, v37
	v_and_b32_e32 v219, 0xffff0000, v37
	v_mul_f32_e32 v216, v225, v216
	v_mul_f32_e32 v217, v225, v217
	v_mul_f32_e32 v218, v225, v218
	v_mul_f32_e32 v219, v225, v219
	v_fmac_f32_e32 v8, v104, v216
	v_fmac_f32_e32 v9, v105, v217
	v_fmac_f32_e32 v10, v106, v218
	v_fmac_f32_e32 v11, v107, v219
	global_store_dwordx4 v192, v[8:11], s[24:25] offset:2048
	v_lshlrev_b32_e32 v216, 16, v38
	v_and_b32_e32 v217, 0xffff0000, v38
	v_lshlrev_b32_e32 v218, 16, v39
	v_and_b32_e32 v219, 0xffff0000, v39
	v_mul_f32_e32 v216, v225, v216
	v_mul_f32_e32 v217, v225, v217
	v_mul_f32_e32 v218, v225, v218
	v_mul_f32_e32 v219, v225, v219
	v_fmac_f32_e32 v12, v108, v216
	v_fmac_f32_e32 v13, v109, v217
	v_fmac_f32_e32 v14, v110, v218
	v_fmac_f32_e32 v15, v111, v219
	global_store_dwordx4 v192, v[12:15], s[24:25] offset:3072
	v_lshlrev_b32_e32 v216, 16, v40
	v_and_b32_e32 v217, 0xffff0000, v40
	v_lshlrev_b32_e32 v218, 16, v41
	v_and_b32_e32 v219, 0xffff0000, v41
	v_mul_f32_e32 v216, v225, v216
	v_mul_f32_e32 v217, v225, v217
	v_mul_f32_e32 v218, v225, v218
	v_mul_f32_e32 v219, v225, v219
	v_fmac_f32_e32 v16, v112, v216
	v_fmac_f32_e32 v17, v113, v217
	v_fmac_f32_e32 v18, v114, v218
	v_fmac_f32_e32 v19, v115, v219
	global_store_dwordx4 v193, v[16:19], s[24:25] offset:0
	v_lshlrev_b32_e32 v216, 16, v42
	v_and_b32_e32 v217, 0xffff0000, v42
	v_lshlrev_b32_e32 v218, 16, v43
	v_and_b32_e32 v219, 0xffff0000, v43
	v_mul_f32_e32 v216, v225, v216
; __device__ __forceinline__ float bf_lo(unsigned w) { return __uint_as_float(w << 16); }
; __device__ __forceinline__ float bf_hi(unsigned w) { return __uint_as_float(w & 0xffff0000u); }
; __global__ void __launch_bounds__(NWAVES * 64, 2) mk_fwd(Args args) {
;     ...
;                 for (int j = 0; j < 8; ++j) { const int col = 4 * F.lane + 256 * j; const f32x4 gt = *(const f32x4*)(m0 + 2 * DM + col), pn = *(const f32x4*)(post_norm + col);
;                     const f32x4 y4 = (f32x4){bf_lo(yw[q][j].x), bf_hi(yw[q][j].x), bf_lo(yw[q][j].y), bf_hi(yw[q][j].y)};
;                     v[q][j] = v[q][j] + gt * (y4 * rsy * pn);
;                     if (lat) *(f32x4*)(args.out + (size_t)row * DM + col) = v[q][j]; }
;                 const float rstd = __builtin_amdgcn_rsqf(sumsq8(v[q]) * (1.f / DM) + EPS);
;                 modulate_store(v[q], rstd, pre_norm + DM, mod + (size_t)(9 + r) * 6144, H + (size_t)row * DM, F.lane); }
	v_mul_f32_e32 v217, v225, v217
	v_mul_f32_e32 v218, v225, v218
	v_mul_f32_e32 v219, v225, v219
	v_fmac_f32_e32 v20, v116, v216
	v_fmac_f32_e32 v21, v117, v217
	v_fmac_f32_e32 v22, v118, v218
	v_fmac_f32_e32 v23, v119, v219
	global_store_dwordx4 v193, v[20:23], s[24:25] offset:1024
	v_lshlrev_b32_e32 v216, 16, v44
	v_and_b32_e32 v217, 0xffff0000, v44
	v_lshlrev_b32_e32 v218, 16, v45
	v_and_b32_e32 v219, 0xffff0000, v45
	v_mul_f32_e32 v216, v225, v216
	v_mul_f32_e32 v217, v225, v217
	v_mul_f32_e32 v218, v225, v218
	v_mul_f32_e32 v219, v225, v219
	v_fmac_f32_e32 v24, v120, v216
	v_fmac_f32_e32 v25, v121, v217
	v_fmac_f32_e32 v26, v122, v218
	v_fmac_f32_e32 v27, v123, v219
	global_store_dwordx4 v193, v[24:27], s[24:25] offset:2048
	v_lshlrev_b32_e32 v216, 16, v46
	v_and_b32_e32 v217, 0xffff0000, v46
	v_lshlrev_b32_e32 v218, 16, v47
	v_and_b32_e32 v219, 0xffff0000, v47
	v_mul_f32_e32 v216, v225, v216
	v_mul_f32_e32 v217, v225, v217
	v_mul_f32_e32 v218, v225, v218
	v_mul_f32_e32 v219, v225, v219
	v_fmac_f32_e32 v28, v124, v216
	v_fmac_f32_e32 v29, v125, v217
	v_fmac_f32_e32 v30, v126, v218
	v_fmac_f32_e32 v31, v127, v219
	global_store_dwordx4 v193, v[28:31], s[24:25] offset:3072
	v_mul_f32_e32 v222, v0, v0
	v_mul_f32_e32 v223, v1, v1
	v_fmac_f32_e32 v222, v2, v2
	v_fmac_f32_e32 v223, v3, v3
	v_fmac_f32_e32 v222, v4, v4
	v_fmac_f32_e32 v223, v5, v5
	v_fmac_f32_e32 v222, v6, v6
	v_fmac_f32_e32 v223, v7, v7
	v_fmac_f32_e32 v222, v8, v8
	v_fmac_f32_e32 v223, v9, v9
	v_fmac_f32_e32 v222, v10, v10
	v_fmac_f32_e32 v223, v11, v11
	v_fmac_f32_e32 v222, v12, v12
	v_fmac_f32_e32 v223, v13, v13
	v_fmac_f32_e32 v222, v14, v14
	v_fmac_f32_e32 v223, v15, v15
	v_fmac_f32_e32 v222, v16, v16
	v_fmac_f32_e32 v223, v17, v17
	v_fmac_f32_e32 v222, v18, v18
	v_fmac_f32_e32 v223, v19, v19
	v_fmac_f32_e32 v222, v20, v20
	v_fmac_f32_e32 v223, v21, v21
	v_fmac_f32_e32 v222, v22, v22
	v_fmac_f32_e32 v223, v23, v23
	v_fmac_f32_e32 v222, v24, v24
	v_fmac_f32_e32 v223, v25, v25
	v_fmac_f32_e32 v222, v26, v26
	v_fmac_f32_e32 v223, v27, v27
	v_fmac_f32_e32 v222, v28, v28
	v_fmac_f32_e32 v223, v29, v29
	v_fmac_f32_e32 v222, v30, v30
	v_fmac_f32_e32 v223, v31, v31
	v_add_f32_e32 v222, v222, v223
	s_nop 1
	v_add_f32_dpp v224, v222, v222 quad_perm:[1,0,3,2] row_mask:0xf bank_mask:0xf
	s_nop 1
	v_add_f32_dpp v224, v224, v224 quad_perm:[2,3,0,1] row_mask:0xf bank_mask:0xf
	s_nop 1
	v_add_f32_dpp v224, v224, v224 row_half_mirror row_mask:0xf bank_mask:0xf
	s_nop 1
	v_add_f32_dpp v224, v224, v224 row_mirror row_mask:0xf bank_mask:0xf
	s_nop 1
	v_readlane_b32 s40, v224, 0
	v_readlane_b32 s41, v224, 16
	v_readlane_b32 s42, v224, 32
	v_readlane_b32 s43, v224, 48
	s_nop 1
	v_mov_b32_e32 v225, s40
	v_add_f32_e32 v225, s41, v225
	v_add_f32_e32 v225, s42, v225
	v_add_f32_e32 v225, s43, v225
	v_fmamk_f32 v225, v225, 0x3a000000, v195
	v_rsq_f32_e32 v225, v225
	s_nop 0
	s_add_i32 s0, s6, 6
	s_lshl_b32 s1, s0, 12
	s_add_u32 s26, s84, s1
	s_addc_u32 s27, s85, 0
	s_add_u32 s26, s26, 0x4000000
	s_addc_u32 s27, s27, 0
	v_mul_f32_e32 v216, v225, v0
	v_mul_f32_e32 v217, v225, v1
	v_mul_f32_e32 v218, v225, v2
	v_mul_f32_e32 v219, v225, v3
	v_fma_f32 v216, v216, v128, v160
	v_fma_f32 v217, v217, v129, v161
	v_fma_f32 v218, v218, v130, v162
	v_fma_f32 v219, v219, v131, v163
	v_cvt_pk_bf16_f32 v196, v216, v217
	v_cvt_pk_bf16_f32 v197, v218, v219
	global_store_dwordx2 v194, v[196:197], s[26:27] offset:0
	v_mul_f32_e32 v216, v225, v4
	v_mul_f32_e32 v217, v225, v5
	v_mul_f32_e32 v218, v225, v6
	v_mul_f32_e32 v219, v225, v7
	v_fma_f32 v216, v216, v132, v164
	v_fma_f32 v217, v217, v133, v165
	v_fma_f32 v218, v218, v134, v166
	v_fma_f32 v219, v219, v135, v167
	v_cvt_pk_bf16_f32 v220, v216, v217
	v_cvt_pk_bf16_f32 v221, v218, v219
	global_store_dwordx2 v194, v[220:221], s[26:27] offset:512
	v_mul_f32_e32 v216, v225, v8
	v_mul_f32_e32 v217, v225, v9
	v_mul_f32_e32 v218, v225, v10
	v_mul_f32_e32 v219, v225, v11
	v_fma_f32 v216, v216, v136, v168
	v_fma_f32 v217, v217, v137, v169
	v_fma_f32 v218, v218, v138, v170
	v_fma_f32 v219, v219, v139, v171
	v_cvt_pk_bf16_f32 v196, v216, v217
	v_cvt_pk_bf16_f32 v197, v218, v219
	global_store_dwordx2 v194, v[196:197], s[26:27] offset:1024
	v_mul_f32_e32 v216, v225, v12
	v_mul_f32_e32 v217, v225, v13
	v_mul_f32_e32 v218, v225, v14
	v_mul_f32_e32 v219, v225, v15
	v_fma_f32 v216, v216, v140, v172
	v_fma_f32 v217, v217, v141, v173
	v_fma_f32 v218, v218, v142, v174
	v_fma_f32 v219, v219, v143, v175
	v_cvt_pk_bf16_f32 v220, v216, v217
	v_cvt_pk_bf16_f32 v221, v218, v219
	global_store_dwordx2 v194, v[220:221], s[26:27] offset:1536
	v_mul_f32_e32 v216, v225, v16
	v_mul_f32_e32 v217, v225, v17
	v_mul_f32_e32 v218, v225, v18
	v_mul_f32_e32 v219, v225, v19
	v_fma_f32 v216, v216, v144, v176
	v_fma_f32 v217, v217, v145, v177
	v_fma_f32 v218, v218, v146, v178
	v_fma_f32 v219, v219, v147, v179
	v_cvt_pk_bf16_f32 v196, v216, v217
	v_cvt_pk_bf16_f32 v197, v218, v219
	global_store_dwordx2 v194, v[196:197], s[26:27] offset:2048
	v_mul_f32_e32 v216, v225, v20
	v_mul_f32_e32 v217, v225, v21
	v_mul_f32_e32 v218, v225, v22
	v_mul_f32_e32 v219, v225, v23
	v_fma_f32 v216, v216, v148, v180
	v_fma_f32 v217, v217, v149, v181
	v_fma_f32 v218, v218, v150, v182
	v_fma_f32 v219, v219, v151, v183
	v_cvt_pk_bf16_f32 v220, v216, v217
	v_cvt_pk_bf16_f32 v221, v218, v219
	global_store_dwordx2 v194, v[220:221], s[26:27] offset:2560
	v_mul_f32_e32 v216, v225, v24
	v_mul_f32_e32 v217, v225, v25
	v_mul_f32_e32 v218, v225, v26
	v_mul_f32_e32 v219, v225, v27
	v_fma_f32 v216, v216, v152, v184
	v_fma_f32 v217, v217, v153, v185
	v_fma_f32 v218, v218, v154, v186
	v_fma_f32 v219, v219, v155, v187
	v_cvt_pk_bf16_f32 v196, v216, v217
; __global__ void __launch_bounds__(NWAVES * 64, 2) mk_fwd(Args args) {
;     ...
;         for (int row0 = F.gw * 3; row0 < MT; row0 += F.NGW * 3) {
;             f32x4 v[3][8]; u32x2 yw[3][8];
; #pragma unroll
;             for (int q = 0; q < 3; ++q) { const int row = row0 + q; const float* src = row < ML ? x + (size_t)row * DM : ctx + (size_t)(row - ML) * DM; load_row_f32(src, F.lane, v[q]);
;                 const bf16_t* yr = Y + (size_t)row * DM;
; #pragma unroll
;                 for (int j = 0; j < 8; ++j) yw[q][j] = *(const u32x2*)(yr + 4 * F.lane + 256 * j); }
	v_cvt_pk_bf16_f32 v197, v218, v219
	global_store_dwordx2 v194, v[196:197], s[26:27] offset:3072
	v_mul_f32_e32 v216, v225, v28
	v_mul_f32_e32 v217, v225, v29
	v_mul_f32_e32 v218, v225, v30
	v_mul_f32_e32 v219, v225, v31
	v_fma_f32 v216, v216, v156, v188
	v_fma_f32 v217, v217, v157, v189
	v_fma_f32 v218, v218, v158, v190
	v_fma_f32 v219, v219, v159, v191
	v_cvt_pk_bf16_f32 v220, v216, v217
	v_cvt_pk_bf16_f32 v221, v218, v219
	global_store_dwordx2 v194, v[220:221], s[26:27] offset:3584
	s_add_i32 s0, s6, 8
	s_cmp_lt_u32 s0, 0x4000
	s_cselect_b32 s10, s68, s72
	s_cselect_b32 s11, s69, s73
	s_cselect_b32 s1, 0, 0x4000
	s_sub_i32 s1, s0, s1
	s_lshl_b32 s1, s1, 13
	s_add_u32 s10, s10, s1
	s_addc_u32 s11, s11, 0
	s_add_i32 s0, s6, 8
	s_lshl_b32 s1, s0, 12
	s_add_u32 s22, s84, s1
	s_addc_u32 s23, s85, 0
	s_add_u32 s22, s22, 0x11800000
	s_addc_u32 s23, s23, 0
	global_load_dwordx4 v[0:3], v192, s[10:11] offset:0 nt
	global_load_dwordx4 v[4:7], v192, s[10:11] offset:1024 nt
	global_load_dwordx4 v[8:11], v192, s[10:11] offset:2048 nt
	global_load_dwordx4 v[12:15], v192, s[10:11] offset:3072 nt
	global_load_dwordx4 v[16:19], v193, s[10:11] offset:0 nt
	global_load_dwordx4 v[20:23], v193, s[10:11] offset:1024 nt
	global_load_dwordx4 v[24:27], v193, s[10:11] offset:2048 nt
	global_load_dwordx4 v[28:31], v193, s[10:11] offset:3072 nt
	global_load_dwordx2 v[32:33], v194, s[22:23] offset:0 nt
	global_load_dwordx2 v[34:35], v194, s[22:23] offset:512 nt
	global_load_dwordx2 v[36:37], v194, s[22:23] offset:1024 nt
	global_load_dwordx2 v[38:39], v194, s[22:23] offset:1536 nt
	global_load_dwordx2 v[40:41], v194, s[22:23] offset:2048 nt
	global_load_dwordx2 v[42:43], v194, s[22:23] offset:2560 nt
	global_load_dwordx2 v[44:45], v194, s[22:23] offset:3072 nt
	global_load_dwordx2 v[46:47], v194, s[22:23] offset:3584 nt
	s_add_i32 s0, s6, 7
	s_add_i32 s0, s6, 7
	s_lshr_b32 s8, s0, 11
	s_cmp_lt_u32 s0, 0x4000
	s_cselect_b32 s8, s8, 8
	s_cmp_eq_u32 s8, s7
	s_cbranch_scc1 .Lp6_np7
; __device__ __forceinline__ float bf_lo(unsigned w) { return __uint_as_float(w << 16); }
; __device__ __forceinline__ float bf_hi(unsigned w) { return __uint_as_float(w & 0xffff0000u); }
; __device__ __forceinline__ void modulate_store(const f32x4 (&v)[8], float rstd, const float* pn, const float* modr, bf16_t* orow, int lane) {
; #pragma unroll
;     for (int j = 0; j < 8; ++j) { const int col = 4 * lane + 256 * j;
;         const f32x4 g = *(const f32x4*)(pn + col), sh = *(const f32x4*)(modr + col), sc = *(const f32x4*)(modr + DM + col);
;         const f32x4 hh = v[j] * rstd * g * (sc + 1.f) + sh;
; __global__ void __launch_bounds__(NWAVES * 64, 2) mk_fwd(Args args) {
;     ...
;                 const float* m0 = mod + (size_t)r * 6144;
; #pragma unroll
;                 for (int j = 0; j < 8; ++j) { const int col = 4 * F.lane + 256 * j; const f32x4 gt = *(const f32x4*)(m0 + 2 * DM + col), pn = *(const f32x4*)(post_norm + col);
;                     const f32x4 y4 = (f32x4){bf_lo(yw[q][j].x), bf_hi(yw[q][j].x), bf_lo(yw[q][j].y), bf_hi(yw[q][j].y)};
;                     v[q][j] = v[q][j] + gt * (y4 * rsy * pn);
	s_mov_b32 s7, s8
	s_add_i32 s1, s8, 9
	s_mul_i32 s1, s1, 0x6000
	s_add_u32 s44, s84, s1
	s_addc_u32 s45, s85, 0
	s_add_u32 s44, s44, 0x2000
	s_addc_u32 s45, s45, 0
	s_add_i32 s1, s8, 9
	s_mul_i32 s1, s1, 0x6000
	s_add_u32 s36, s84, s1
	s_addc_u32 s37, s85, 0
	s_add_u32 s38, s80, 0x2000
	s_addc_u32 s39, s81, 0
	s_mul_i32 s1, s8, 0x6000
	s_add_u32 s34, s84, s1
	s_addc_u32 s35, s85, 0
	s_add_u32 s34, s34, 0x4000
	s_addc_u32 s35, s35, 0
	global_load_dwordx4 v[96:99], v192, s[34:35] offset:0
	global_load_dwordx4 v[200:203], v192, s[82:83] offset:0
	global_load_dwordx4 v[100:103], v192, s[34:35] offset:1024
	global_load_dwordx4 v[204:207], v192, s[82:83] offset:1024
	global_load_dwordx4 v[104:107], v192, s[34:35] offset:2048
	global_load_dwordx4 v[208:211], v192, s[82:83] offset:2048
	global_load_dwordx4 v[108:111], v192, s[34:35] offset:3072
	global_load_dwordx4 v[212:215], v192, s[82:83] offset:3072
	s_waitcnt vmcnt(0)
	v_mul_f32_e32 v96, v96, v200
	v_mul_f32_e32 v97, v97, v201
	v_mul_f32_e32 v98, v98, v202
	v_mul_f32_e32 v99, v99, v203
	v_mul_f32_e32 v100, v100, v204
	v_mul_f32_e32 v101, v101, v205
	v_mul_f32_e32 v102, v102, v206
	v_mul_f32_e32 v103, v103, v207
	v_mul_f32_e32 v104, v104, v208
	v_mul_f32_e32 v105, v105, v209
	v_mul_f32_e32 v106, v106, v210
	v_mul_f32_e32 v107, v107, v211
	v_mul_f32_e32 v108, v108, v212
	v_mul_f32_e32 v109, v109, v213
	v_mul_f32_e32 v110, v110, v214
	v_mul_f32_e32 v111, v111, v215
	global_load_dwordx4 v[128:131], v192, s[38:39] offset:0
	global_load_dwordx4 v[200:203], v192, s[44:45] offset:0
	global_load_dwordx4 v[160:163], v192, s[36:37] offset:0
	global_load_dwordx4 v[132:135], v192, s[38:39] offset:1024
	global_load_dwordx4 v[204:207], v192, s[44:45] offset:1024
	global_load_dwordx4 v[164:167], v192, s[36:37] offset:1024
	global_load_dwordx4 v[136:139], v192, s[38:39] offset:2048
	global_load_dwordx4 v[208:211], v192, s[44:45] offset:2048
	global_load_dwordx4 v[168:171], v192, s[36:37] offset:2048
	global_load_dwordx4 v[140:143], v192, s[38:39] offset:3072
	global_load_dwordx4 v[212:215], v192, s[44:45] offset:3072
	global_load_dwordx4 v[172:175], v192, s[36:37] offset:3072
	s_waitcnt vmcnt(0)
	v_add_f32_e32 v200, 1.0, v200
	v_add_f32_e32 v201, 1.0, v201
	v_add_f32_e32 v202, 1.0, v202
	v_add_f32_e32 v203, 1.0, v203
	v_mul_f32_e32 v128, v128, v200
	v_mul_f32_e32 v129, v129, v201
	v_mul_f32_e32 v130, v130, v202
	v_mul_f32_e32 v131, v131, v203
	v_add_f32_e32 v204, 1.0, v204
	v_add_f32_e32 v205, 1.0, v205
	v_add_f32_e32 v206, 1.0, v206
	v_add_f32_e32 v207, 1.0, v207
	v_mul_f32_e32 v132, v132, v204
	v_mul_f32_e32 v133, v133, v205
	v_mul_f32_e32 v134, v134, v206
	v_mul_f32_e32 v135, v135, v207
	v_add_f32_e32 v208, 1.0, v208
	v_add_f32_e32 v209, 1.0, v209
	v_add_f32_e32 v210, 1.0, v210
	v_add_f32_e32 v211, 1.0, v211
	v_mul_f32_e32 v136, v136, v208
	v_mul_f32_e32 v137, v137, v209
	v_mul_f32_e32 v138, v138, v210
	v_mul_f32_e32 v139, v139, v211
	v_add_f32_e32 v212, 1.0, v212
	v_add_f32_e32 v213, 1.0, v213
	v_add_f32_e32 v214, 1.0, v214
	v_add_f32_e32 v215, 1.0, v215
	v_mul_f32_e32 v140, v140, v212
	v_mul_f32_e32 v141, v141, v213
	v_mul_f32_e32 v142, v142, v214
	v_mul_f32_e32 v143, v143, v215
	global_load_dwordx4 v[112:115], v193, s[34:35] offset:0
	global_load_dwordx4 v[200:203], v193, s[82:83] offset:0
	global_load_dwordx4 v[116:119], v193, s[34:35] offset:1024
	global_load_dwordx4 v[204:207], v193, s[82:83] offset:1024
	global_load_dwordx4 v[120:123], v193, s[34:35] offset:2048
	global_load_dwordx4 v[208:211], v193, s[82:83] offset:2048
	global_load_dwordx4 v[124:127], v193, s[34:35] offset:3072
	global_load_dwordx4 v[212:215], v193, s[82:83] offset:3072
	s_waitcnt vmcnt(0)
	v_mul_f32_e32 v112, v112, v200
	v_mul_f32_e32 v113, v113, v201
	v_mul_f32_e32 v114, v114, v202
	v_mul_f32_e32 v115, v115, v203
	v_mul_f32_e32 v116, v116, v204
	v_mul_f32_e32 v117, v117, v205
	v_mul_f32_e32 v118, v118, v206
	v_mul_f32_e32 v119, v119, v207
	v_mul_f32_e32 v120, v120, v208
	v_mul_f32_e32 v121, v121, v209
	v_mul_f32_e32 v122, v122, v210
	v_mul_f32_e32 v123, v123, v211
	v_mul_f32_e32 v124, v124, v212
	v_mul_f32_e32 v125, v125, v213
	v_mul_f32_e32 v126, v126, v214
	v_mul_f32_e32 v127, v127, v215
	global_load_dwordx4 v[144:147], v193, s[38:39] offset:0
	global_load_dwordx4 v[200:203], v193, s[44:45] offset:0
	global_load_dwordx4 v[176:179], v193, s[36:37] offset:0
	global_load_dwordx4 v[148:151], v193, s[38:39] offset:1024
	global_load_dwordx4 v[204:207], v193, s[44:45] offset:1024
	global_load_dwordx4 v[180:183], v193, s[36:37] offset:1024
	global_load_dwordx4 v[152:155], v193, s[38:39] offset:2048
	global_load_dwordx4 v[208:211], v193, s[44:45] offset:2048
	global_load_dwordx4 v[184:187], v193, s[36:37] offset:2048
	global_load_dwordx4 v[156:159], v193, s[38:39] offset:3072
	global_load_dwordx4 v[212:215], v193, s[44:45] offset:3072
	global_load_dwordx4 v[188:191], v193, s[36:37] offset:3072
	s_waitcnt vmcnt(0)
	v_add_f32_e32 v200, 1.0, v200
	v_add_f32_e32 v201, 1.0, v201
	v_add_f32_e32 v202, 1.0, v202
	v_add_f32_e32 v203, 1.0, v203
	v_mul_f32_e32 v144, v144, v200
	v_mul_f32_e32 v145, v145, v201
	v_mul_f32_e32 v146, v146, v202
	v_mul_f32_e32 v147, v147, v203
	v_add_f32_e32 v204, 1.0, v204
	v_add_f32_e32 v205, 1.0, v205
	v_add_f32_e32 v206, 1.0, v206
	v_add_f32_e32 v207, 1.0, v207
	v_mul_f32_e32 v148, v148, v204
	v_mul_f32_e32 v149, v149, v205
	v_mul_f32_e32 v150, v150, v206
	v_mul_f32_e32 v151, v151, v207
	v_add_f32_e32 v208, 1.0, v208
	v_add_f32_e32 v209, 1.0, v209
	v_add_f32_e32 v210, 1.0, v210
	v_add_f32_e32 v211, 1.0, v211
	v_mul_f32_e32 v152, v152, v208
	v_mul_f32_e32 v153, v153, v209
	v_mul_f32_e32 v154, v154, v210
	v_mul_f32_e32 v155, v155, v211
	v_add_f32_e32 v212, 1.0, v212
	v_add_f32_e32 v213, 1.0, v213
	v_add_f32_e32 v214, 1.0, v214
	v_add_f32_e32 v215, 1.0, v215
	v_mul_f32_e32 v156, v156, v212
	v_mul_f32_e32 v157, v157, v213
	v_mul_f32_e32 v158, v158, v214
	v_mul_f32_e32 v159, v159, v215
